# GEMM loops: LDS-DMA in saddr form (no 64-bit VALU address adds); barrier counter in spill-VGPR lane
# speedup vs baseline: 1.0260x; 1.0099x over previous
_Z10fwd_kernel4Args:
	v_writelane_b32 v242, 0, 63
	s_load_dword s3, s[0:1], 0xd8
	s_load_dwordx4 s[76:79], s[0:1], 0xc0
	s_load_dwordx2 s[60:61], s[0:1], 0xd0
	v_and_b32_e32 v185, 0x3ff, v0
	s_add_u32 s6, s0, 0xd0
	v_readfirstlane_b32 s74, v185
	s_addc_u32 s7, s1, 0
	v_cmp_gt_u32_e32 vcc, 16, v185
	s_waitcnt lgkmcnt(0)
	v_writelane_b32 v242, s3, 0
	s_and_saveexec_b64 s[4:5], vcc
	v_lshl_add_u32 v1, v185, 2, 0
	v_add_u32_e32 v1, 0x21000, v1
	v_mov_b32_e32 v2, 0
	ds_write_b32 v1, v2
	s_or_b64 exec, exec, s[4:5]
	s_waitcnt lgkmcnt(0)
	s_barrier
	s_getreg_b32 s3, hwreg(HW_REG_XCC_ID, 0, 4)
	s_and_b32 s84, s3, 15
	v_cmp_eq_u32_e64 s[8:9], 0, v185
	s_mov_b64 s[4:5], exec
	s_nop 0
	v_writelane_b32 v242, s8, 1
	s_nop 1
	v_writelane_b32 v242, s9, 2
	s_and_b64 s[8:9], s[4:5], s[8:9]
	s_mov_b64 exec, s[8:9]
	s_cbranch_execz .LBB0_5
	s_mov_b64 s[8:9], exec
	v_mbcnt_lo_u32_b32 v1, s8, 0
	v_mbcnt_hi_u32_b32 v1, s9, v1
	v_cmp_eq_u32_e32 vcc, 0, v1
	s_and_b64 s[10:11], exec, vcc
	s_mov_b64 exec, s[10:11]
	s_cbranch_execz .LBB0_5
	s_lshl_b32 s3, s84, 8
	s_bcnt1_i32_b64 s8, s[8:9]
	v_mov_b32_e32 v1, s3
	v_mov_b32_e32 v2, s8
	global_atomic_add v1, v2, s[76:77] offset:1024

.LBB0_100:
	s_or_b64 exec, exec, s[0:1]
	s_waitcnt lgkmcnt(0)
	s_barrier
	v_readlane_b32 s12, v242, 63
	s_add_u32 s12, s12, 1
	v_writelane_b32 v242, s12, 63

.LBB0_111:
	ds_read_b128 v[162:165], v155
	ds_read_b128 v[166:169], v155 offset:1024
	ds_read_b128 v[170:173], v155 offset:2048
	ds_read_b128 v[174:177], v155 offset:3072
	ds_read_b128 v[178:181], v157
	ds_read_b128 v[186:189], v157 offset:1024
	ds_read_b128 v[190:193], v157 offset:2048
	ds_read_b128 v[194:197], v157 offset:3072
	s_add_u32 s19, s40, 0xfffc0080
	s_addc_u32 s20, s41, -1
	s_cmp_eq_u32 s18, 12
	s_cselect_b32 s89, s12, s20
	s_cselect_b32 s88, s13, s19
	s_cselect_b32 s81, s14, s17
	s_cselect_b32 s80, s15, s16
	s_add_i32 m0, s62, 0xc000
	ds_read_b128 v[198:201], v159
	ds_read_b128 v[202:205], v159 offset:1024
	ds_read_b128 v[206:209], v159 offset:2048
	ds_read_b128 v[210:213], v159 offset:3072
	ds_read_b128 v[214:217], v159 offset:4096
	ds_read_b128 v[218:221], v159 offset:5120
	ds_read_b128 v[222:225], v159 offset:6144
	ds_read_b128 v[226:229], v159 offset:7168
	global_load_lds_dwordx4 v136, s[40:41]
	s_add_i32 m0, s62, 0xe000
	s_nop 0
	global_load_lds_dwordx4 v138, s[40:41]
	s_waitcnt vmcnt(8)
	s_waitcnt lgkmcnt(0)
	s_barrier
	s_waitcnt lgkmcnt(0)
	v_mfma_f32_16x16x32_bf16 v[124:127], v[162:165], v[198:201], v[124:127]
	v_mfma_f32_16x16x32_bf16 v[120:123], v[170:173], v[198:201], v[120:123]
	v_mfma_f32_16x16x32_bf16 v[108:111], v[162:165], v[206:209], v[108:111]
	v_mfma_f32_16x16x32_bf16 v[100:103], v[170:173], v[206:209], v[100:103]
	v_mfma_f32_16x16x32_bf16 v[92:95], v[162:165], v[214:217], v[92:95]
	v_mfma_f32_16x16x32_bf16 v[84:87], v[170:173], v[214:217], v[84:87]
	v_mfma_f32_16x16x32_bf16 v[76:79], v[162:165], v[222:225], v[76:79]
	v_mfma_f32_16x16x32_bf16 v[68:71], v[170:173], v[222:225], v[68:71]
	v_mfma_f32_16x16x32_bf16 v[124:127], v[166:169], v[202:205], v[124:127]
	v_mfma_f32_16x16x32_bf16 v[120:123], v[174:177], v[202:205], v[120:123]
	v_mfma_f32_16x16x32_bf16 v[108:111], v[166:169], v[210:213], v[108:111]
	v_mfma_f32_16x16x32_bf16 v[100:103], v[174:177], v[210:213], v[100:103]
	v_mfma_f32_16x16x32_bf16 v[92:95], v[166:169], v[218:221], v[92:95]
	v_mfma_f32_16x16x32_bf16 v[84:87], v[174:177], v[218:221], v[84:87]
	v_mfma_f32_16x16x32_bf16 v[76:79], v[166:169], v[226:229], v[76:79]
	v_mfma_f32_16x16x32_bf16 v[68:71], v[174:177], v[226:229], v[68:71]
	v_mfma_f32_16x16x32_bf16 v[116:119], v[178:181], v[198:201], v[116:119]
	v_mfma_f32_16x16x32_bf16 v[112:115], v[190:193], v[198:201], v[112:115]
	v_mfma_f32_16x16x32_bf16 v[104:107], v[178:181], v[206:209], v[104:107]
	v_mfma_f32_16x16x32_bf16 v[96:99], v[190:193], v[206:209], v[96:99]
	v_mfma_f32_16x16x32_bf16 v[88:91], v[178:181], v[214:217], v[88:91]
	v_mfma_f32_16x16x32_bf16 v[80:83], v[190:193], v[214:217], v[80:83]
	v_mfma_f32_16x16x32_bf16 v[72:75], v[178:181], v[222:225], v[72:75]
	v_mfma_f32_16x16x32_bf16 v[64:67], v[190:193], v[222:225], v[64:67]
	v_mfma_f32_16x16x32_bf16 v[116:119], v[186:189], v[202:205], v[116:119]
	v_mfma_f32_16x16x32_bf16 v[112:115], v[194:197], v[202:205], v[112:115]
	v_mfma_f32_16x16x32_bf16 v[104:107], v[186:189], v[210:213], v[104:107]
	v_mfma_f32_16x16x32_bf16 v[96:99], v[194:197], v[210:213], v[96:99]
	v_mfma_f32_16x16x32_bf16 v[88:91], v[186:189], v[218:221], v[88:91]
	v_mfma_f32_16x16x32_bf16 v[80:83], v[194:197], v[218:221], v[80:83]
	v_mfma_f32_16x16x32_bf16 v[72:75], v[186:189], v[226:229], v[72:75]
	v_mfma_f32_16x16x32_bf16 v[64:67], v[194:197], v[226:229], v[64:67]
	s_barrier
	s_add_i32 s19, s73, s3
	s_mov_b32 m0, s19
	ds_read_b128 v[198:201], v159 offset:16384
	ds_read_b128 v[202:205], v159 offset:17408
	ds_read_b128 v[206:209], v159 offset:18432
	ds_read_b128 v[210:213], v159 offset:19456
	ds_read_b128 v[214:217], v159 offset:20480
	ds_read_b128 v[218:221], v159 offset:21504
	ds_read_b128 v[222:225], v159 offset:22528
	ds_read_b128 v[226:229], v159 offset:23552
	global_load_lds_dwordx4 v132, s[80:81]
	s_add_i32 m0, s19, 0x2000
	s_add_u32 s20, s80, 0x40000
	s_addc_u32 s21, s81, 0
	s_add_i32 s19, s74, s3
	global_load_lds_dwordx4 v128, s[80:81]
	s_mov_b32 m0, s19
	global_load_lds_dwordx4 v132, s[20:21]
	s_add_i32 m0, s19, 0x2000
	s_nop 0
	global_load_lds_dwordx4 v128, s[20:21]
	s_mov_b32 m0, s62
	s_nop 0
	global_load_lds_dwordx4 v134, s[88:89]
	s_mov_b32 m0, s63
	s_nop 0
	global_load_lds_dwordx4 v130, s[88:89]
	s_add_u32 s98, s80, s28
	s_addc_u32 s99, s81, s29
	s_add_u32 s100, s88, s28
	s_addc_u32 s101, s89, s29
	s_waitcnt vmcnt(8)
	s_waitcnt lgkmcnt(0)
	s_barrier
	s_waitcnt lgkmcnt(0)
	v_mfma_f32_16x16x32_bf16 v[60:63], v[162:165], v[198:201], v[60:63]
	v_mfma_f32_16x16x32_bf16 v[52:55], v[170:173], v[198:201], v[52:55]
	v_mfma_f32_16x16x32_bf16 v[44:47], v[162:165], v[206:209], v[44:47]
	v_mfma_f32_16x16x32_bf16 v[36:39], v[170:173], v[206:209], v[36:39]
	v_mfma_f32_16x16x32_bf16 v[28:31], v[162:165], v[214:217], v[28:31]
	v_mfma_f32_16x16x32_bf16 v[20:23], v[170:173], v[214:217], v[20:23]
	v_mfma_f32_16x16x32_bf16 v[12:15], v[162:165], v[222:225], v[12:15]
	v_mfma_f32_16x16x32_bf16 v[4:7], v[170:173], v[222:225], v[4:7]
	v_mfma_f32_16x16x32_bf16 v[60:63], v[166:169], v[202:205], v[60:63]
	v_mfma_f32_16x16x32_bf16 v[52:55], v[174:177], v[202:205], v[52:55]
	v_mfma_f32_16x16x32_bf16 v[44:47], v[166:169], v[210:213], v[44:47]
	v_mfma_f32_16x16x32_bf16 v[36:39], v[174:177], v[210:213], v[36:39]
	v_mfma_f32_16x16x32_bf16 v[28:31], v[166:169], v[218:221], v[28:31]
	v_mfma_f32_16x16x32_bf16 v[20:23], v[174:177], v[218:221], v[20:23]
	v_mfma_f32_16x16x32_bf16 v[12:15], v[166:169], v[226:229], v[12:15]
	v_mfma_f32_16x16x32_bf16 v[4:7], v[174:177], v[226:229], v[4:7]
	v_mfma_f32_16x16x32_bf16 v[56:59], v[178:181], v[198:201], v[56:59]
	v_mfma_f32_16x16x32_bf16 v[48:51], v[190:193], v[198:201], v[48:51]
	v_mfma_f32_16x16x32_bf16 v[40:43], v[178:181], v[206:209], v[40:43]
	v_mfma_f32_16x16x32_bf16 v[32:35], v[190:193], v[206:209], v[32:35]
	v_mfma_f32_16x16x32_bf16 v[24:27], v[178:181], v[214:217], v[24:27]
	v_mfma_f32_16x16x32_bf16 v[16:19], v[190:193], v[214:217], v[16:19]
	v_mfma_f32_16x16x32_bf16 v[8:11], v[178:181], v[222:225], v[8:11]
	v_mfma_f32_16x16x32_bf16 v[0:3], v[190:193], v[222:225], v[0:3]
	v_mfma_f32_16x16x32_bf16 v[56:59], v[186:189], v[202:205], v[56:59]
	v_mfma_f32_16x16x32_bf16 v[48:51], v[194:197], v[202:205], v[48:51]
	v_mfma_f32_16x16x32_bf16 v[40:43], v[186:189], v[210:213], v[40:43]
	v_mfma_f32_16x16x32_bf16 v[32:35], v[194:197], v[210:213], v[32:35]
	v_mfma_f32_16x16x32_bf16 v[24:27], v[186:189], v[218:221], v[24:27]
	v_mfma_f32_16x16x32_bf16 v[16:19], v[194:197], v[218:221], v[16:19]
	v_mfma_f32_16x16x32_bf16 v[8:11], v[186:189], v[226:229], v[8:11]
	v_mfma_f32_16x16x32_bf16 v[0:3], v[194:197], v[226:229], v[0:3]
	s_barrier
	s_add_i32 s19, 0, 0x18000
	v_add_u32_e32 v146, s19, v151
	s_add_i32 s22, 0, 0x1c000
	ds_read_b128 v[162:165], v146
	ds_read_b128 v[166:169], v146 offset:1024
	ds_read_b128 v[170:173], v146 offset:2048
	ds_read_b128 v[174:177], v146 offset:3072
	v_add_u32_e32 v146, s22, v151
	ds_read_b128 v[178:181], v146
	ds_read_b128 v[186:189], v146 offset:1024
	ds_read_b128 v[190:193], v146 offset:2048
	ds_read_b128 v[194:197], v146 offset:3072
	s_add_u32 s20, s88, 0x40000
	s_addc_u32 s21, s89, 0
	s_mov_b32 m0, s64
	ds_read_b128 v[198:201], v159 offset:32768
	ds_read_b128 v[202:205], v159 offset:33792
	ds_read_b128 v[206:209], v159 offset:34816
	ds_read_b128 v[210:213], v159 offset:35840
	ds_read_b128 v[214:217], v159 offset:36864
	ds_read_b128 v[218:221], v159 offset:37888
	ds_read_b128 v[222:225], v159 offset:38912
	ds_read_b128 v[226:229], v159 offset:39936
	global_load_lds_dwordx4 v134, s[20:21]
	s_mov_b32 m0, s65
	s_nop 0
	global_load_lds_dwordx4 v130, s[20:21]
	s_waitcnt vmcnt(8)
	s_waitcnt lgkmcnt(0)
	s_barrier
	s_waitcnt lgkmcnt(0)
	v_mfma_f32_16x16x32_bf16 v[124:127], v[162:165], v[198:201], v[124:127]
	v_mfma_f32_16x16x32_bf16 v[120:123], v[170:173], v[198:201], v[120:123]
	v_mfma_f32_16x16x32_bf16 v[108:111], v[162:165], v[206:209], v[108:111]
	v_mfma_f32_16x16x32_bf16 v[100:103], v[170:173], v[206:209], v[100:103]
	v_mfma_f32_16x16x32_bf16 v[92:95], v[162:165], v[214:217], v[92:95]
	v_mfma_f32_16x16x32_bf16 v[84:87], v[170:173], v[214:217], v[84:87]
	v_mfma_f32_16x16x32_bf16 v[76:79], v[162:165], v[222:225], v[76:79]
	v_mfma_f32_16x16x32_bf16 v[68:71], v[170:173], v[222:225], v[68:71]
	v_mfma_f32_16x16x32_bf16 v[124:127], v[166:169], v[202:205], v[124:127]
	v_mfma_f32_16x16x32_bf16 v[120:123], v[174:177], v[202:205], v[120:123]
	v_mfma_f32_16x16x32_bf16 v[108:111], v[166:169], v[210:213], v[108:111]
	v_mfma_f32_16x16x32_bf16 v[100:103], v[174:177], v[210:213], v[100:103]
	v_mfma_f32_16x16x32_bf16 v[92:95], v[166:169], v[218:221], v[92:95]
	v_mfma_f32_16x16x32_bf16 v[84:87], v[174:177], v[218:221], v[84:87]
	v_mfma_f32_16x16x32_bf16 v[76:79], v[166:169], v[226:229], v[76:79]
	v_mfma_f32_16x16x32_bf16 v[68:71], v[174:177], v[226:229], v[68:71]
	v_mfma_f32_16x16x32_bf16 v[116:119], v[178:181], v[198:201], v[116:119]
	v_mfma_f32_16x16x32_bf16 v[112:115], v[190:193], v[198:201], v[112:115]
	v_mfma_f32_16x16x32_bf16 v[104:107], v[178:181], v[206:209], v[104:107]
	v_mfma_f32_16x16x32_bf16 v[96:99], v[190:193], v[206:209], v[96:99]
	v_mfma_f32_16x16x32_bf16 v[88:91], v[178:181], v[214:217], v[88:91]
	v_mfma_f32_16x16x32_bf16 v[80:83], v[190:193], v[214:217], v[80:83]
	v_mfma_f32_16x16x32_bf16 v[72:75], v[178:181], v[222:225], v[72:75]
	v_mfma_f32_16x16x32_bf16 v[64:67], v[190:193], v[222:225], v[64:67]
	v_mfma_f32_16x16x32_bf16 v[116:119], v[186:189], v[202:205], v[116:119]
	v_mfma_f32_16x16x32_bf16 v[112:115], v[194:197], v[202:205], v[112:115]
	v_mfma_f32_16x16x32_bf16 v[104:107], v[186:189], v[210:213], v[104:107]
	v_mfma_f32_16x16x32_bf16 v[96:99], v[194:197], v[210:213], v[96:99]
	v_mfma_f32_16x16x32_bf16 v[88:91], v[186:189], v[218:221], v[88:91]
	v_mfma_f32_16x16x32_bf16 v[80:83], v[194:197], v[218:221], v[80:83]
	v_mfma_f32_16x16x32_bf16 v[72:75], v[186:189], v[226:229], v[72:75]
	v_mfma_f32_16x16x32_bf16 v[64:67], v[194:197], v[226:229], v[64:67]
	s_barrier
	s_add_i32 s19, s19, s3
	s_mov_b32 m0, s19
	ds_read_b128 v[198:201], v159 offset:49152
	ds_read_b128 v[202:205], v159 offset:50176
	ds_read_b128 v[206:209], v159 offset:51200
	ds_read_b128 v[210:213], v159 offset:52224
	ds_read_b128 v[214:217], v159 offset:53248
	ds_read_b128 v[218:221], v159 offset:54272
	ds_read_b128 v[222:225], v159 offset:55296
	ds_read_b128 v[226:229], v159 offset:56320
	global_load_lds_dwordx4 v132, s[98:99]
	s_add_i32 m0, s19, 0x2000
	s_add_u32 s20, s80, 0x40080
	s_addc_u32 s21, s81, 0
	s_add_i32 s19, s22, s3
	global_load_lds_dwordx4 v128, s[98:99]
	s_mov_b32 m0, s19
	s_nop 0
	global_load_lds_dwordx4 v132, s[20:21]
	s_add_i32 m0, s19, 0x2000
	s_nop 0
	global_load_lds_dwordx4 v128, s[20:21]
	s_mov_b32 m0, s67
	s_nop 0
	global_load_lds_dwordx4 v134, s[100:101]
	s_mov_b32 m0, s70
	s_nop 0
	global_load_lds_dwordx4 v130, s[100:101]
	s_waitcnt vmcnt(8)
	s_waitcnt lgkmcnt(0)
	s_barrier
	s_waitcnt lgkmcnt(0)
	v_mfma_f32_16x16x32_bf16 v[60:63], v[162:165], v[198:201], v[60:63]
	v_mfma_f32_16x16x32_bf16 v[52:55], v[170:173], v[198:201], v[52:55]
	v_mfma_f32_16x16x32_bf16 v[44:47], v[162:165], v[206:209], v[44:47]
	v_mfma_f32_16x16x32_bf16 v[36:39], v[170:173], v[206:209], v[36:39]
	v_mfma_f32_16x16x32_bf16 v[28:31], v[162:165], v[214:217], v[28:31]
	v_mfma_f32_16x16x32_bf16 v[20:23], v[170:173], v[214:217], v[20:23]
	v_mfma_f32_16x16x32_bf16 v[12:15], v[162:165], v[222:225], v[12:15]
	v_mfma_f32_16x16x32_bf16 v[4:7], v[170:173], v[222:225], v[4:7]
	v_mfma_f32_16x16x32_bf16 v[60:63], v[166:169], v[202:205], v[60:63]
	v_mfma_f32_16x16x32_bf16 v[52:55], v[174:177], v[202:205], v[52:55]
	v_mfma_f32_16x16x32_bf16 v[44:47], v[166:169], v[210:213], v[44:47]
	v_mfma_f32_16x16x32_bf16 v[36:39], v[174:177], v[210:213], v[36:39]
	v_mfma_f32_16x16x32_bf16 v[28:31], v[166:169], v[218:221], v[28:31]
	v_mfma_f32_16x16x32_bf16 v[20:23], v[174:177], v[218:221], v[20:23]
	v_mfma_f32_16x16x32_bf16 v[12:15], v[166:169], v[226:229], v[12:15]
	v_mfma_f32_16x16x32_bf16 v[4:7], v[174:177], v[226:229], v[4:7]
	v_mfma_f32_16x16x32_bf16 v[56:59], v[178:181], v[198:201], v[56:59]
	v_mfma_f32_16x16x32_bf16 v[48:51], v[190:193], v[198:201], v[48:51]
	v_mfma_f32_16x16x32_bf16 v[40:43], v[178:181], v[206:209], v[40:43]
	v_mfma_f32_16x16x32_bf16 v[32:35], v[190:193], v[206:209], v[32:35]
	v_mfma_f32_16x16x32_bf16 v[24:27], v[178:181], v[214:217], v[24:27]
	v_mfma_f32_16x16x32_bf16 v[16:19], v[190:193], v[214:217], v[16:19]
	v_mfma_f32_16x16x32_bf16 v[8:11], v[178:181], v[222:225], v[8:11]
	v_mfma_f32_16x16x32_bf16 v[0:3], v[190:193], v[222:225], v[0:3]
	v_mfma_f32_16x16x32_bf16 v[56:59], v[186:189], v[202:205], v[56:59]
	v_mfma_f32_16x16x32_bf16 v[48:51], v[194:197], v[202:205], v[48:51]
	v_mfma_f32_16x16x32_bf16 v[40:43], v[186:189], v[210:213], v[40:43]
	v_mfma_f32_16x16x32_bf16 v[32:35], v[194:197], v[210:213], v[32:35]
	v_mfma_f32_16x16x32_bf16 v[24:27], v[186:189], v[218:221], v[24:27]
	v_mfma_f32_16x16x32_bf16 v[16:19], v[194:197], v[218:221], v[16:19]
	v_mfma_f32_16x16x32_bf16 v[8:11], v[186:189], v[226:229], v[8:11]
	v_mfma_f32_16x16x32_bf16 v[0:3], v[194:197], v[226:229], v[0:3]
	s_barrier
	s_add_i32 s18, s18, 2
	s_add_u32 s40, s40, 0x100
	s_addc_u32 s41, s41, 0
	s_add_u32 s16, s16, 0x100
	s_addc_u32 s17, s17, 0
	s_cmp_gt_u32 s18, 13
	s_cbranch_scc0 .LBB0_111
	s_and_b64 vcc, exec, s[30:31]
	s_cbranch_vccz .LBB0_114
	s_barrier

.LBB0_367:
	s_cmp_gt_i32 s79, 2
	s_cselect_b64 s[4:5], -1, 0
	s_and_b64 s[0:1], s[0:1], s[4:5]
	s_andn2_b64 vcc, exec, s[0:1]
	s_cbranch_vccnz .LBB0_421
	s_waitcnt vmcnt(0) lgkmcnt(0)
	s_barrier
	v_readlane_b32 s21, v242, 63
	s_add_u32 s21, s21, 1
	v_readlane_b32 s12, v242, 1
	v_readlane_b32 s13, v242, 2
	s_mov_b64 s[14:15], exec
	s_and_b64 s[12:13], s[14:15], s[12:13]
	s_mov_b64 exec, s[12:13]
	s_cbranch_execz .Lxb_done_1
	v_mov_b32_e32 v0, 0x21020
	ds_read2_b32 v[2:3], v0 offset1:1
	s_lshl_b32 s16, s84, 8
	s_add_u32 s16, s76, s16
	s_addc_u32 s17, s77, 0
	v_mov_b32_e32 v1, 0x1000
	v_mov_b32_e32 v4, 1
	global_atomic_add v5, v1, v4, s[16:17] offset:1024 sc0
	buffer_inv sc1
	s_waitcnt vmcnt(0) lgkmcnt(0)
	v_readfirstlane_b32 s18, v5
	v_readfirstlane_b32 s19, v2
	v_readfirstlane_b32 s20, v3
	v_mov_b32_e32 v1, 0x3000
	s_mul_i32 s22, s19, s21
	s_mul_i32 s23, s20, s21
	s_add_u32 s18, s18, 1
	s_cmp_lg_u32 s18, s22
	s_cbranch_scc1 .Lxb_spin_1
	buffer_wbl2 sc1
	s_waitcnt vmcnt(0)
	global_atomic_add v1, v4, s[76:77] offset:1024

.Lxb_done_1:
	s_mov_b64 exec, s[14:15]
	v_writelane_b32 v242, s21, 63
	s_barrier

.LBB0_445:
	ds_read_b128 v[128:131], v213
	ds_read_b128 v[132:135], v213 offset:1024
	ds_read_b128 v[136:139], v213 offset:2048
	ds_read_b128 v[140:143], v213 offset:3072
	ds_read_b128 v[144:147], v214
	ds_read_b128 v[148:151], v214 offset:1024
	ds_read_b128 v[152:155], v214 offset:2048
	ds_read_b128 v[156:159], v214 offset:3072
	s_add_u32 s42, s40, 0xfff50080
	s_addc_u32 s43, s41, -1
	s_cmp_eq_u32 s62, 40
	s_cselect_b32 s81, s1, s43
	s_cselect_b32 s80, s0, s42
	s_cselect_b32 s43, s37, s61
	s_cselect_b32 s42, s36, s39
	s_add_i32 m0, s14, 0xc000
	ds_read_b128 v[160:163], v215
	ds_read_b128 v[164:167], v215 offset:1024
	ds_read_b128 v[168:171], v215 offset:2048
	ds_read_b128 v[172:175], v215 offset:3072
	ds_read_b128 v[198:201], v215 offset:4096
	ds_read_b128 v[202:205], v215 offset:5120
	ds_read_b128 v[206:209], v215 offset:6144
	ds_read_b128 v[218:221], v215 offset:7168
	global_load_lds_dwordx4 v190, s[40:41]
	s_add_i32 m0, s14, 0xe000
	s_nop 0
	global_load_lds_dwordx4 v192, s[40:41]
	s_waitcnt vmcnt(8)
	s_waitcnt lgkmcnt(0)
	s_barrier
	s_waitcnt lgkmcnt(0)
	v_mfma_f32_16x16x32_bf16 v[124:127], v[128:131], v[160:163], v[124:127]
	v_mfma_f32_16x16x32_bf16 v[120:123], v[136:139], v[160:163], v[120:123]
	v_mfma_f32_16x16x32_bf16 v[108:111], v[128:131], v[168:171], v[108:111]
	v_mfma_f32_16x16x32_bf16 v[104:107], v[136:139], v[168:171], v[104:107]
	v_mfma_f32_16x16x32_bf16 v[92:95], v[128:131], v[198:201], v[92:95]
	v_mfma_f32_16x16x32_bf16 v[88:91], v[136:139], v[198:201], v[88:91]
	v_mfma_f32_16x16x32_bf16 v[76:79], v[128:131], v[206:209], v[76:79]
	v_mfma_f32_16x16x32_bf16 v[72:75], v[136:139], v[206:209], v[72:75]
	v_mfma_f32_16x16x32_bf16 v[124:127], v[132:135], v[164:167], v[124:127]
	v_mfma_f32_16x16x32_bf16 v[120:123], v[140:143], v[164:167], v[120:123]
	v_mfma_f32_16x16x32_bf16 v[108:111], v[132:135], v[172:175], v[108:111]
	v_mfma_f32_16x16x32_bf16 v[104:107], v[140:143], v[172:175], v[104:107]
	v_mfma_f32_16x16x32_bf16 v[92:95], v[132:135], v[202:205], v[92:95]
	v_mfma_f32_16x16x32_bf16 v[88:91], v[140:143], v[202:205], v[88:91]
	v_mfma_f32_16x16x32_bf16 v[76:79], v[132:135], v[218:221], v[76:79]
	v_mfma_f32_16x16x32_bf16 v[72:75], v[140:143], v[218:221], v[72:75]
	v_mfma_f32_16x16x32_bf16 v[116:119], v[144:147], v[160:163], v[116:119]
	v_mfma_f32_16x16x32_bf16 v[112:115], v[152:155], v[160:163], v[112:115]
	v_mfma_f32_16x16x32_bf16 v[100:103], v[144:147], v[168:171], v[100:103]
	v_mfma_f32_16x16x32_bf16 v[96:99], v[152:155], v[168:171], v[96:99]
	v_mfma_f32_16x16x32_bf16 v[84:87], v[144:147], v[198:201], v[84:87]
	v_mfma_f32_16x16x32_bf16 v[80:83], v[152:155], v[198:201], v[80:83]
	v_mfma_f32_16x16x32_bf16 v[68:71], v[144:147], v[206:209], v[68:71]
	v_mfma_f32_16x16x32_bf16 v[64:67], v[152:155], v[206:209], v[64:67]
	v_mfma_f32_16x16x32_bf16 v[116:119], v[148:151], v[164:167], v[116:119]
	v_mfma_f32_16x16x32_bf16 v[112:115], v[156:159], v[164:167], v[112:115]
	v_mfma_f32_16x16x32_bf16 v[100:103], v[148:151], v[172:175], v[100:103]
	v_mfma_f32_16x16x32_bf16 v[96:99], v[156:159], v[172:175], v[96:99]
	v_mfma_f32_16x16x32_bf16 v[84:87], v[148:151], v[202:205], v[84:87]
	v_mfma_f32_16x16x32_bf16 v[80:83], v[156:159], v[202:205], v[80:83]
	v_mfma_f32_16x16x32_bf16 v[68:71], v[148:151], v[218:221], v[68:71]
	v_mfma_f32_16x16x32_bf16 v[64:67], v[156:159], v[218:221], v[64:67]
	s_barrier
	s_add_i32 s63, s24, s13
	s_mov_b32 m0, s63
	ds_read_b128 v[160:163], v215 offset:16384
	ds_read_b128 v[164:167], v215 offset:17408
	ds_read_b128 v[168:171], v215 offset:18432
	ds_read_b128 v[172:175], v215 offset:19456
	ds_read_b128 v[198:201], v215 offset:20480
	ds_read_b128 v[202:205], v215 offset:21504
	ds_read_b128 v[206:209], v215 offset:22528
	ds_read_b128 v[218:221], v215 offset:23552
	global_load_lds_dwordx4 v178, s[42:43]
	s_add_i32 m0, s63, 0x2000
	s_add_u32 s64, s42, 0xb0000
	s_addc_u32 s65, s43, 0
	s_add_i32 s63, s25, s13
	global_load_lds_dwordx4 v182, s[42:43]
	s_mov_b32 m0, s63
	global_load_lds_dwordx4 v178, s[64:65]
	s_add_i32 m0, s63, 0x2000
	s_nop 0
	global_load_lds_dwordx4 v182, s[64:65]
	s_mov_b32 m0, s14
	s_nop 0
	global_load_lds_dwordx4 v176, s[80:81]
	s_mov_b32 m0, s15
	s_nop 0
	global_load_lds_dwordx4 v180, s[80:81]
	s_add_u32 s98, s42, s30
	s_addc_u32 s99, s43, s31
	s_add_u32 s100, s80, s30
	s_addc_u32 s101, s81, s31
	s_waitcnt vmcnt(8)
	s_waitcnt lgkmcnt(0)
	s_barrier
	s_waitcnt lgkmcnt(0)
	v_mfma_f32_16x16x32_bf16 v[60:63], v[128:131], v[160:163], v[60:63]
	v_mfma_f32_16x16x32_bf16 v[56:59], v[136:139], v[160:163], v[56:59]
	v_mfma_f32_16x16x32_bf16 v[44:47], v[128:131], v[168:171], v[44:47]
	v_mfma_f32_16x16x32_bf16 v[40:43], v[136:139], v[168:171], v[40:43]
	v_mfma_f32_16x16x32_bf16 v[28:31], v[128:131], v[198:201], v[28:31]
	v_mfma_f32_16x16x32_bf16 v[24:27], v[136:139], v[198:201], v[24:27]
	v_mfma_f32_16x16x32_bf16 v[12:15], v[128:131], v[206:209], v[12:15]
	v_mfma_f32_16x16x32_bf16 v[8:11], v[136:139], v[206:209], v[8:11]
	v_mfma_f32_16x16x32_bf16 v[60:63], v[132:135], v[164:167], v[60:63]
	v_mfma_f32_16x16x32_bf16 v[56:59], v[140:143], v[164:167], v[56:59]
	v_mfma_f32_16x16x32_bf16 v[44:47], v[132:135], v[172:175], v[44:47]
	v_mfma_f32_16x16x32_bf16 v[40:43], v[140:143], v[172:175], v[40:43]
	v_mfma_f32_16x16x32_bf16 v[28:31], v[132:135], v[202:205], v[28:31]
	v_mfma_f32_16x16x32_bf16 v[24:27], v[140:143], v[202:205], v[24:27]
	v_mfma_f32_16x16x32_bf16 v[12:15], v[132:135], v[218:221], v[12:15]
	v_mfma_f32_16x16x32_bf16 v[8:11], v[140:143], v[218:221], v[8:11]
	v_mfma_f32_16x16x32_bf16 v[52:55], v[144:147], v[160:163], v[52:55]
	v_mfma_f32_16x16x32_bf16 v[48:51], v[152:155], v[160:163], v[48:51]
	v_mfma_f32_16x16x32_bf16 v[36:39], v[144:147], v[168:171], v[36:39]
	v_mfma_f32_16x16x32_bf16 v[32:35], v[152:155], v[168:171], v[32:35]
	v_mfma_f32_16x16x32_bf16 v[20:23], v[144:147], v[198:201], v[20:23]
	v_mfma_f32_16x16x32_bf16 v[16:19], v[152:155], v[198:201], v[16:19]
	v_mfma_f32_16x16x32_bf16 v[4:7], v[144:147], v[206:209], v[4:7]
	v_mfma_f32_16x16x32_bf16 v[0:3], v[152:155], v[206:209], v[0:3]
	v_mfma_f32_16x16x32_bf16 v[52:55], v[148:151], v[164:167], v[52:55]
	v_mfma_f32_16x16x32_bf16 v[48:51], v[156:159], v[164:167], v[48:51]
	v_mfma_f32_16x16x32_bf16 v[36:39], v[148:151], v[172:175], v[36:39]
	v_mfma_f32_16x16x32_bf16 v[32:35], v[156:159], v[172:175], v[32:35]
	v_mfma_f32_16x16x32_bf16 v[20:23], v[148:151], v[202:205], v[20:23]
	v_mfma_f32_16x16x32_bf16 v[16:19], v[156:159], v[202:205], v[16:19]
	v_mfma_f32_16x16x32_bf16 v[4:7], v[148:151], v[218:221], v[4:7]
	v_mfma_f32_16x16x32_bf16 v[0:3], v[156:159], v[218:221], v[0:3]
	s_barrier
	s_add_i32 s63, 0, 0x18000
	s_add_i32 s66, 0, 0x1c000
	v_add_u32_e32 v140, s63, v210
	v_add_u32_e32 v156, s66, v210
	ds_read_b128 v[128:131], v140
	ds_read_b128 v[132:135], v140 offset:1024
	ds_read_b128 v[136:139], v140 offset:2048
	ds_read_b128 v[140:143], v140 offset:3072
	ds_read_b128 v[144:147], v156
	ds_read_b128 v[148:151], v156 offset:1024
	ds_read_b128 v[152:155], v156 offset:2048
	ds_read_b128 v[156:159], v156 offset:3072
	s_add_u32 s64, s80, 0xb0000
	s_addc_u32 s65, s81, 0
	s_mov_b32 m0, s16
	ds_read_b128 v[160:163], v215 offset:32768
	ds_read_b128 v[164:167], v215 offset:33792
	ds_read_b128 v[168:171], v215 offset:34816
	ds_read_b128 v[172:175], v215 offset:35840
	ds_read_b128 v[198:201], v215 offset:36864
	ds_read_b128 v[202:205], v215 offset:37888
	ds_read_b128 v[206:209], v215 offset:38912
	ds_read_b128 v[218:221], v215 offset:39936
	global_load_lds_dwordx4 v176, s[64:65]
	s_mov_b32 m0, s17
	s_nop 0
	global_load_lds_dwordx4 v180, s[64:65]
	s_waitcnt vmcnt(8)
	s_waitcnt lgkmcnt(0)
	s_barrier
	s_waitcnt lgkmcnt(0)
	v_mfma_f32_16x16x32_bf16 v[124:127], v[128:131], v[160:163], v[124:127]
	v_mfma_f32_16x16x32_bf16 v[120:123], v[136:139], v[160:163], v[120:123]
	v_mfma_f32_16x16x32_bf16 v[108:111], v[128:131], v[168:171], v[108:111]
	v_mfma_f32_16x16x32_bf16 v[104:107], v[136:139], v[168:171], v[104:107]
	v_mfma_f32_16x16x32_bf16 v[92:95], v[128:131], v[198:201], v[92:95]
	v_mfma_f32_16x16x32_bf16 v[88:91], v[136:139], v[198:201], v[88:91]
	v_mfma_f32_16x16x32_bf16 v[76:79], v[128:131], v[206:209], v[76:79]
	v_mfma_f32_16x16x32_bf16 v[72:75], v[136:139], v[206:209], v[72:75]
	v_mfma_f32_16x16x32_bf16 v[124:127], v[132:135], v[164:167], v[124:127]
	v_mfma_f32_16x16x32_bf16 v[120:123], v[140:143], v[164:167], v[120:123]
	v_mfma_f32_16x16x32_bf16 v[108:111], v[132:135], v[172:175], v[108:111]
	v_mfma_f32_16x16x32_bf16 v[104:107], v[140:143], v[172:175], v[104:107]
	v_mfma_f32_16x16x32_bf16 v[92:95], v[132:135], v[202:205], v[92:95]
	v_mfma_f32_16x16x32_bf16 v[88:91], v[140:143], v[202:205], v[88:91]
	v_mfma_f32_16x16x32_bf16 v[76:79], v[132:135], v[218:221], v[76:79]
	v_mfma_f32_16x16x32_bf16 v[72:75], v[140:143], v[218:221], v[72:75]
	v_mfma_f32_16x16x32_bf16 v[116:119], v[144:147], v[160:163], v[116:119]
	v_mfma_f32_16x16x32_bf16 v[112:115], v[152:155], v[160:163], v[112:115]
	v_mfma_f32_16x16x32_bf16 v[100:103], v[144:147], v[168:171], v[100:103]
	v_mfma_f32_16x16x32_bf16 v[96:99], v[152:155], v[168:171], v[96:99]
	v_mfma_f32_16x16x32_bf16 v[84:87], v[144:147], v[198:201], v[84:87]
	v_mfma_f32_16x16x32_bf16 v[80:83], v[152:155], v[198:201], v[80:83]
	v_mfma_f32_16x16x32_bf16 v[68:71], v[144:147], v[206:209], v[68:71]
	v_mfma_f32_16x16x32_bf16 v[64:67], v[152:155], v[206:209], v[64:67]
	v_mfma_f32_16x16x32_bf16 v[116:119], v[148:151], v[164:167], v[116:119]
	v_mfma_f32_16x16x32_bf16 v[112:115], v[156:159], v[164:167], v[112:115]
	v_mfma_f32_16x16x32_bf16 v[100:103], v[148:151], v[172:175], v[100:103]
	v_mfma_f32_16x16x32_bf16 v[96:99], v[156:159], v[172:175], v[96:99]
	v_mfma_f32_16x16x32_bf16 v[84:87], v[148:151], v[202:205], v[84:87]
	v_mfma_f32_16x16x32_bf16 v[80:83], v[156:159], v[202:205], v[80:83]
	v_mfma_f32_16x16x32_bf16 v[68:71], v[148:151], v[218:221], v[68:71]
	v_mfma_f32_16x16x32_bf16 v[64:67], v[156:159], v[218:221], v[64:67]
	s_barrier
	s_add_i32 s63, s63, s13
	s_mov_b32 m0, s63
	ds_read_b128 v[160:163], v215 offset:49152
	ds_read_b128 v[164:167], v215 offset:50176
	ds_read_b128 v[168:171], v215 offset:51200
	ds_read_b128 v[172:175], v215 offset:52224
	ds_read_b128 v[198:201], v215 offset:53248
	ds_read_b128 v[202:205], v215 offset:54272
	ds_read_b128 v[206:209], v215 offset:55296
	ds_read_b128 v[218:221], v215 offset:56320
	global_load_lds_dwordx4 v178, s[98:99]
	s_add_i32 m0, s63, 0x2000
	s_add_u32 s42, s42, 0xb0080
	s_addc_u32 s43, s43, 0
	s_add_i32 s63, s66, s13
	global_load_lds_dwordx4 v182, s[98:99]
	s_mov_b32 m0, s63
	s_nop 0
	global_load_lds_dwordx4 v178, s[42:43]
	s_add_i32 m0, s63, 0x2000
	s_nop 0
	global_load_lds_dwordx4 v182, s[42:43]
	s_mov_b32 m0, s19
	s_nop 0
	global_load_lds_dwordx4 v176, s[100:101]
	s_mov_b32 m0, s20
	s_nop 0
	global_load_lds_dwordx4 v180, s[100:101]
	s_waitcnt vmcnt(8)
	s_waitcnt lgkmcnt(0)
	s_barrier
	s_waitcnt lgkmcnt(0)
	v_mfma_f32_16x16x32_bf16 v[60:63], v[128:131], v[160:163], v[60:63]
	v_mfma_f32_16x16x32_bf16 v[56:59], v[136:139], v[160:163], v[56:59]
	v_mfma_f32_16x16x32_bf16 v[44:47], v[128:131], v[168:171], v[44:47]
	v_mfma_f32_16x16x32_bf16 v[40:43], v[136:139], v[168:171], v[40:43]
	v_mfma_f32_16x16x32_bf16 v[28:31], v[128:131], v[198:201], v[28:31]
	v_mfma_f32_16x16x32_bf16 v[24:27], v[136:139], v[198:201], v[24:27]
	v_mfma_f32_16x16x32_bf16 v[12:15], v[128:131], v[206:209], v[12:15]
	v_mfma_f32_16x16x32_bf16 v[8:11], v[136:139], v[206:209], v[8:11]
	v_mfma_f32_16x16x32_bf16 v[60:63], v[132:135], v[164:167], v[60:63]
	v_mfma_f32_16x16x32_bf16 v[56:59], v[140:143], v[164:167], v[56:59]
	v_mfma_f32_16x16x32_bf16 v[44:47], v[132:135], v[172:175], v[44:47]
	v_mfma_f32_16x16x32_bf16 v[40:43], v[140:143], v[172:175], v[40:43]
	v_mfma_f32_16x16x32_bf16 v[28:31], v[132:135], v[202:205], v[28:31]
	v_mfma_f32_16x16x32_bf16 v[24:27], v[140:143], v[202:205], v[24:27]
	v_mfma_f32_16x16x32_bf16 v[12:15], v[132:135], v[218:221], v[12:15]
	v_mfma_f32_16x16x32_bf16 v[8:11], v[140:143], v[218:221], v[8:11]
	v_mfma_f32_16x16x32_bf16 v[52:55], v[144:147], v[160:163], v[52:55]
	v_mfma_f32_16x16x32_bf16 v[48:51], v[152:155], v[160:163], v[48:51]
	v_mfma_f32_16x16x32_bf16 v[36:39], v[144:147], v[168:171], v[36:39]
	v_mfma_f32_16x16x32_bf16 v[32:35], v[152:155], v[168:171], v[32:35]
	v_mfma_f32_16x16x32_bf16 v[20:23], v[144:147], v[198:201], v[20:23]
	v_mfma_f32_16x16x32_bf16 v[16:19], v[152:155], v[198:201], v[16:19]
	v_mfma_f32_16x16x32_bf16 v[4:7], v[144:147], v[206:209], v[4:7]
	v_mfma_f32_16x16x32_bf16 v[0:3], v[152:155], v[206:209], v[0:3]
	v_mfma_f32_16x16x32_bf16 v[52:55], v[148:151], v[164:167], v[52:55]
	v_mfma_f32_16x16x32_bf16 v[48:51], v[156:159], v[164:167], v[48:51]
	v_mfma_f32_16x16x32_bf16 v[36:39], v[148:151], v[172:175], v[36:39]
	v_mfma_f32_16x16x32_bf16 v[32:35], v[156:159], v[172:175], v[32:35]
	v_mfma_f32_16x16x32_bf16 v[20:23], v[148:151], v[202:205], v[20:23]
	v_mfma_f32_16x16x32_bf16 v[16:19], v[156:159], v[202:205], v[16:19]
	v_mfma_f32_16x16x32_bf16 v[4:7], v[148:151], v[218:221], v[4:7]
	v_mfma_f32_16x16x32_bf16 v[0:3], v[156:159], v[218:221], v[0:3]
	s_barrier
	s_add_i32 s62, s62, 2
	s_add_u32 s40, s40, 0x100
	s_addc_u32 s41, s41, 0
	s_add_u32 s39, s39, 0x100
	s_addc_u32 s61, s61, 0
	s_cmp_gt_u32 s62, 41
	s_cbranch_scc0 .LBB0_445
	s_and_b64 vcc, exec, s[34:35]
	s_cbranch_vccz .LBB0_448
	s_barrier

.LBB0_470:
	s_cmp_gt_i32 s79, 3
	s_cselect_b64 s[0:1], -1, 0
	s_and_b64 s[4:5], s[10:11], s[0:1]
	v_readlane_b32 s64, v242, 58
	s_andn2_b64 vcc, exec, s[4:5]
	v_readlane_b32 s65, v242, 59
	s_cbranch_vccnz .LBB0_524
	s_waitcnt vmcnt(0) lgkmcnt(0)
	s_barrier
	v_readlane_b32 s21, v242, 63
	s_add_u32 s21, s21, 1
	v_readlane_b32 s12, v242, 1
	v_readlane_b32 s13, v242, 2
	s_mov_b64 s[14:15], exec
	s_and_b64 s[12:13], s[14:15], s[12:13]
	s_mov_b64 exec, s[12:13]
	s_cbranch_execz .Lxb_done_2
	v_mov_b32_e32 v0, 0x21020
	ds_read2_b32 v[2:3], v0 offset1:1
	s_lshl_b32 s16, s84, 8
	s_add_u32 s16, s76, s16
	s_addc_u32 s17, s77, 0
	v_mov_b32_e32 v1, 0x1000
	v_mov_b32_e32 v4, 1
	global_atomic_add v5, v1, v4, s[16:17] offset:1024 sc0
	buffer_inv sc1
	s_waitcnt vmcnt(0) lgkmcnt(0)
	v_readfirstlane_b32 s18, v5
	v_readfirstlane_b32 s19, v2
	v_readfirstlane_b32 s20, v3
	v_mov_b32_e32 v1, 0x3000
	s_mul_i32 s22, s19, s21
	s_mul_i32 s23, s20, s21
	s_add_u32 s18, s18, 1
	s_cmp_lg_u32 s18, s22
	s_cbranch_scc1 .Lxb_spin_2
	buffer_wbl2 sc1
	s_waitcnt vmcnt(0)
	global_atomic_add v1, v4, s[76:77] offset:1024

.LBB0_546:
	ds_read_b128 v[144:147], v155
	ds_read_b128 v[148:151], v155 offset:1024
	ds_read_b128 v[160:163], v155 offset:2048
	ds_read_b128 v[164:167], v155 offset:3072
	ds_read_b128 v[168:171], v156
	ds_read_b128 v[172:175], v156 offset:1024
	ds_read_b128 v[176:179], v156 offset:2048
	ds_read_b128 v[180:183], v156 offset:3072
	s_add_u32 s19, s6, 0xfffc0080
	s_addc_u32 s20, s7, -1
	s_cmp_eq_u32 s18, 12
	s_cselect_b32 s89, s8, s20
	s_cselect_b32 s88, s9, s19
	s_cselect_b32 s43, s14, s17
	s_cselect_b32 s42, s15, s16
	s_add_i32 m0, s63, 0xc000
	ds_read_b128 v[186:189], v157
	ds_read_b128 v[190:193], v157 offset:1024
	ds_read_b128 v[194:197], v157 offset:2048
	ds_read_b128 v[198:201], v157 offset:3072
	ds_read_b128 v[202:205], v157 offset:4096
	ds_read_b128 v[206:209], v157 offset:5120
	ds_read_b128 v[210:213], v157 offset:6144
	ds_read_b128 v[214:217], v157 offset:7168
	global_load_lds_dwordx4 v136, s[6:7]
	s_add_i32 m0, s63, 0xe000
	s_nop 0
	global_load_lds_dwordx4 v138, s[6:7]
	s_waitcnt vmcnt(8)
	s_waitcnt lgkmcnt(0)
	s_barrier
	s_waitcnt lgkmcnt(0)
	v_mfma_f32_16x16x32_bf16 v[124:127], v[144:147], v[186:189], v[124:127]
	v_mfma_f32_16x16x32_bf16 v[120:123], v[160:163], v[186:189], v[120:123]
	v_mfma_f32_16x16x32_bf16 v[108:111], v[144:147], v[194:197], v[108:111]
	v_mfma_f32_16x16x32_bf16 v[104:107], v[160:163], v[194:197], v[104:107]
	v_mfma_f32_16x16x32_bf16 v[92:95], v[144:147], v[202:205], v[92:95]
	v_mfma_f32_16x16x32_bf16 v[88:91], v[160:163], v[202:205], v[88:91]
	v_mfma_f32_16x16x32_bf16 v[76:79], v[144:147], v[210:213], v[76:79]
	v_mfma_f32_16x16x32_bf16 v[72:75], v[160:163], v[210:213], v[72:75]
	v_mfma_f32_16x16x32_bf16 v[124:127], v[148:151], v[190:193], v[124:127]
	v_mfma_f32_16x16x32_bf16 v[120:123], v[164:167], v[190:193], v[120:123]
	v_mfma_f32_16x16x32_bf16 v[108:111], v[148:151], v[198:201], v[108:111]
	v_mfma_f32_16x16x32_bf16 v[104:107], v[164:167], v[198:201], v[104:107]
	v_mfma_f32_16x16x32_bf16 v[92:95], v[148:151], v[206:209], v[92:95]
	v_mfma_f32_16x16x32_bf16 v[88:91], v[164:167], v[206:209], v[88:91]
	v_mfma_f32_16x16x32_bf16 v[76:79], v[148:151], v[214:217], v[76:79]
	v_mfma_f32_16x16x32_bf16 v[72:75], v[164:167], v[214:217], v[72:75]
	v_mfma_f32_16x16x32_bf16 v[116:119], v[168:171], v[186:189], v[116:119]
	v_mfma_f32_16x16x32_bf16 v[112:115], v[176:179], v[186:189], v[112:115]
	v_mfma_f32_16x16x32_bf16 v[100:103], v[168:171], v[194:197], v[100:103]
	v_mfma_f32_16x16x32_bf16 v[96:99], v[176:179], v[194:197], v[96:99]
	v_mfma_f32_16x16x32_bf16 v[84:87], v[168:171], v[202:205], v[84:87]
	v_mfma_f32_16x16x32_bf16 v[80:83], v[176:179], v[202:205], v[80:83]
	v_mfma_f32_16x16x32_bf16 v[68:71], v[168:171], v[210:213], v[68:71]
	v_mfma_f32_16x16x32_bf16 v[64:67], v[176:179], v[210:213], v[64:67]
	v_mfma_f32_16x16x32_bf16 v[116:119], v[172:175], v[190:193], v[116:119]
	v_mfma_f32_16x16x32_bf16 v[112:115], v[180:183], v[190:193], v[112:115]
	v_mfma_f32_16x16x32_bf16 v[100:103], v[172:175], v[198:201], v[100:103]
	v_mfma_f32_16x16x32_bf16 v[96:99], v[180:183], v[198:201], v[96:99]
	v_mfma_f32_16x16x32_bf16 v[84:87], v[172:175], v[206:209], v[84:87]
	v_mfma_f32_16x16x32_bf16 v[80:83], v[180:183], v[206:209], v[80:83]
	v_mfma_f32_16x16x32_bf16 v[68:71], v[172:175], v[214:217], v[68:71]
	v_mfma_f32_16x16x32_bf16 v[64:67], v[180:183], v[214:217], v[64:67]
	s_barrier
	s_add_i32 s19, s72, s62
	s_mov_b32 m0, s19
	ds_read_b128 v[186:189], v157 offset:16384
	ds_read_b128 v[190:193], v157 offset:17408
	ds_read_b128 v[194:197], v157 offset:18432
	ds_read_b128 v[198:201], v157 offset:19456
	ds_read_b128 v[202:205], v157 offset:20480
	ds_read_b128 v[206:209], v157 offset:21504
	ds_read_b128 v[210:213], v157 offset:22528
	ds_read_b128 v[214:217], v157 offset:23552
	global_load_lds_dwordx4 v130, s[42:43]
	s_add_i32 m0, s19, 0x2000
	s_add_u32 s20, s42, 0x40000
	s_addc_u32 s21, s43, 0
	s_add_i32 s19, s73, s62
	global_load_lds_dwordx4 v134, s[42:43]
	s_mov_b32 m0, s19
	global_load_lds_dwordx4 v130, s[20:21]
	s_add_i32 m0, s19, 0x2000
	s_nop 0
	global_load_lds_dwordx4 v134, s[20:21]
	s_mov_b32 m0, s63
	s_nop 0
	global_load_lds_dwordx4 v128, s[88:89]
	s_mov_b32 m0, s64
	s_nop 0
	global_load_lds_dwordx4 v132, s[88:89]
	s_add_u32 s98, s42, s28
	s_addc_u32 s99, s43, s29
	s_add_u32 s100, s88, s28
	s_addc_u32 s101, s89, s29
	s_waitcnt vmcnt(8)
	s_waitcnt lgkmcnt(0)
	s_barrier
	s_waitcnt lgkmcnt(0)
	v_mfma_f32_16x16x32_bf16 v[60:63], v[144:147], v[186:189], v[60:63]
	v_mfma_f32_16x16x32_bf16 v[56:59], v[160:163], v[186:189], v[56:59]
	v_mfma_f32_16x16x32_bf16 v[44:47], v[144:147], v[194:197], v[44:47]
	v_mfma_f32_16x16x32_bf16 v[40:43], v[160:163], v[194:197], v[40:43]
	v_mfma_f32_16x16x32_bf16 v[28:31], v[144:147], v[202:205], v[28:31]
	v_mfma_f32_16x16x32_bf16 v[24:27], v[160:163], v[202:205], v[24:27]
	v_mfma_f32_16x16x32_bf16 v[12:15], v[144:147], v[210:213], v[12:15]
	v_mfma_f32_16x16x32_bf16 v[8:11], v[160:163], v[210:213], v[8:11]
	v_mfma_f32_16x16x32_bf16 v[60:63], v[148:151], v[190:193], v[60:63]
	v_mfma_f32_16x16x32_bf16 v[56:59], v[164:167], v[190:193], v[56:59]
	v_mfma_f32_16x16x32_bf16 v[44:47], v[148:151], v[198:201], v[44:47]
	v_mfma_f32_16x16x32_bf16 v[40:43], v[164:167], v[198:201], v[40:43]
	v_mfma_f32_16x16x32_bf16 v[28:31], v[148:151], v[206:209], v[28:31]
	v_mfma_f32_16x16x32_bf16 v[24:27], v[164:167], v[206:209], v[24:27]
	v_mfma_f32_16x16x32_bf16 v[12:15], v[148:151], v[214:217], v[12:15]
	v_mfma_f32_16x16x32_bf16 v[8:11], v[164:167], v[214:217], v[8:11]
	v_mfma_f32_16x16x32_bf16 v[52:55], v[168:171], v[186:189], v[52:55]
	v_mfma_f32_16x16x32_bf16 v[48:51], v[176:179], v[186:189], v[48:51]
	v_mfma_f32_16x16x32_bf16 v[36:39], v[168:171], v[194:197], v[36:39]
	v_mfma_f32_16x16x32_bf16 v[32:35], v[176:179], v[194:197], v[32:35]
	v_mfma_f32_16x16x32_bf16 v[20:23], v[168:171], v[202:205], v[20:23]
	v_mfma_f32_16x16x32_bf16 v[16:19], v[176:179], v[202:205], v[16:19]
	v_mfma_f32_16x16x32_bf16 v[4:7], v[168:171], v[210:213], v[4:7]
	v_mfma_f32_16x16x32_bf16 v[0:3], v[176:179], v[210:213], v[0:3]
	v_mfma_f32_16x16x32_bf16 v[52:55], v[172:175], v[190:193], v[52:55]
	v_mfma_f32_16x16x32_bf16 v[48:51], v[180:183], v[190:193], v[48:51]
	v_mfma_f32_16x16x32_bf16 v[36:39], v[172:175], v[198:201], v[36:39]
	v_mfma_f32_16x16x32_bf16 v[32:35], v[180:183], v[198:201], v[32:35]
	v_mfma_f32_16x16x32_bf16 v[20:23], v[172:175], v[206:209], v[20:23]
	v_mfma_f32_16x16x32_bf16 v[16:19], v[180:183], v[206:209], v[16:19]
	v_mfma_f32_16x16x32_bf16 v[4:7], v[172:175], v[214:217], v[4:7]
	v_mfma_f32_16x16x32_bf16 v[0:3], v[180:183], v[214:217], v[0:3]
	s_barrier
	s_add_i32 s19, 0, 0x18000
	v_add_u32_e32 v159, s19, v153
	s_add_i32 s22, 0, 0x1c000
	ds_read_b128 v[144:147], v159
	ds_read_b128 v[148:151], v159 offset:1024
	ds_read_b128 v[160:163], v159 offset:2048
	ds_read_b128 v[164:167], v159 offset:3072
	v_add_u32_e32 v159, s22, v153
	ds_read_b128 v[168:171], v159
	ds_read_b128 v[172:175], v159 offset:1024
	ds_read_b128 v[176:179], v159 offset:2048
	ds_read_b128 v[180:183], v159 offset:3072
	s_add_u32 s20, s88, 0x40000
	s_addc_u32 s21, s89, 0
	s_mov_b32 m0, s65
	ds_read_b128 v[186:189], v157 offset:32768
	ds_read_b128 v[190:193], v157 offset:33792
	ds_read_b128 v[194:197], v157 offset:34816
	ds_read_b128 v[198:201], v157 offset:35840
	ds_read_b128 v[202:205], v157 offset:36864
	ds_read_b128 v[206:209], v157 offset:37888
	ds_read_b128 v[210:213], v157 offset:38912
	ds_read_b128 v[214:217], v157 offset:39936
	global_load_lds_dwordx4 v128, s[20:21]
	s_mov_b32 m0, s66
	s_nop 0
	global_load_lds_dwordx4 v132, s[20:21]
	s_waitcnt vmcnt(8)
	s_waitcnt lgkmcnt(0)
	s_barrier
	s_waitcnt lgkmcnt(0)
	v_mfma_f32_16x16x32_bf16 v[124:127], v[144:147], v[186:189], v[124:127]
	v_mfma_f32_16x16x32_bf16 v[120:123], v[160:163], v[186:189], v[120:123]
	v_mfma_f32_16x16x32_bf16 v[108:111], v[144:147], v[194:197], v[108:111]
	v_mfma_f32_16x16x32_bf16 v[104:107], v[160:163], v[194:197], v[104:107]
	v_mfma_f32_16x16x32_bf16 v[92:95], v[144:147], v[202:205], v[92:95]
	v_mfma_f32_16x16x32_bf16 v[88:91], v[160:163], v[202:205], v[88:91]
	v_mfma_f32_16x16x32_bf16 v[76:79], v[144:147], v[210:213], v[76:79]
	v_mfma_f32_16x16x32_bf16 v[72:75], v[160:163], v[210:213], v[72:75]
	v_mfma_f32_16x16x32_bf16 v[124:127], v[148:151], v[190:193], v[124:127]
	v_mfma_f32_16x16x32_bf16 v[120:123], v[164:167], v[190:193], v[120:123]
	v_mfma_f32_16x16x32_bf16 v[108:111], v[148:151], v[198:201], v[108:111]
	v_mfma_f32_16x16x32_bf16 v[104:107], v[164:167], v[198:201], v[104:107]
	v_mfma_f32_16x16x32_bf16 v[92:95], v[148:151], v[206:209], v[92:95]
	v_mfma_f32_16x16x32_bf16 v[88:91], v[164:167], v[206:209], v[88:91]
	v_mfma_f32_16x16x32_bf16 v[76:79], v[148:151], v[214:217], v[76:79]
	v_mfma_f32_16x16x32_bf16 v[72:75], v[164:167], v[214:217], v[72:75]
	v_mfma_f32_16x16x32_bf16 v[116:119], v[168:171], v[186:189], v[116:119]
	v_mfma_f32_16x16x32_bf16 v[112:115], v[176:179], v[186:189], v[112:115]
	v_mfma_f32_16x16x32_bf16 v[100:103], v[168:171], v[194:197], v[100:103]
	v_mfma_f32_16x16x32_bf16 v[96:99], v[176:179], v[194:197], v[96:99]
	v_mfma_f32_16x16x32_bf16 v[84:87], v[168:171], v[202:205], v[84:87]
	v_mfma_f32_16x16x32_bf16 v[80:83], v[176:179], v[202:205], v[80:83]
	v_mfma_f32_16x16x32_bf16 v[68:71], v[168:171], v[210:213], v[68:71]
	v_mfma_f32_16x16x32_bf16 v[64:67], v[176:179], v[210:213], v[64:67]
	v_mfma_f32_16x16x32_bf16 v[116:119], v[172:175], v[190:193], v[116:119]
	v_mfma_f32_16x16x32_bf16 v[112:115], v[180:183], v[190:193], v[112:115]
	v_mfma_f32_16x16x32_bf16 v[100:103], v[172:175], v[198:201], v[100:103]
	v_mfma_f32_16x16x32_bf16 v[96:99], v[180:183], v[198:201], v[96:99]
	v_mfma_f32_16x16x32_bf16 v[84:87], v[172:175], v[206:209], v[84:87]
	v_mfma_f32_16x16x32_bf16 v[80:83], v[180:183], v[206:209], v[80:83]
	v_mfma_f32_16x16x32_bf16 v[68:71], v[172:175], v[214:217], v[68:71]
	v_mfma_f32_16x16x32_bf16 v[64:67], v[180:183], v[214:217], v[64:67]
	s_barrier
	s_add_i32 s19, s19, s62
	s_mov_b32 m0, s19
	ds_read_b128 v[186:189], v157 offset:49152
	ds_read_b128 v[190:193], v157 offset:50176
	ds_read_b128 v[194:197], v157 offset:51200
	ds_read_b128 v[198:201], v157 offset:52224
	ds_read_b128 v[202:205], v157 offset:53248
	ds_read_b128 v[206:209], v157 offset:54272
	ds_read_b128 v[210:213], v157 offset:55296
	ds_read_b128 v[214:217], v157 offset:56320
	global_load_lds_dwordx4 v130, s[98:99]
	s_add_i32 m0, s19, 0x2000
	s_add_u32 s20, s42, 0x40080
	s_addc_u32 s21, s43, 0
	s_add_i32 s19, s22, s62
	global_load_lds_dwordx4 v134, s[98:99]
	s_mov_b32 m0, s19
	s_nop 0
	global_load_lds_dwordx4 v130, s[20:21]
	s_add_i32 m0, s19, 0x2000
	s_nop 0
	global_load_lds_dwordx4 v134, s[20:21]
	s_mov_b32 m0, s70
	s_nop 0
	global_load_lds_dwordx4 v128, s[100:101]
	s_mov_b32 m0, s71
	s_nop 0
	global_load_lds_dwordx4 v132, s[100:101]
	s_waitcnt vmcnt(8)
	s_waitcnt lgkmcnt(0)
	s_barrier
	s_waitcnt lgkmcnt(0)
	v_mfma_f32_16x16x32_bf16 v[60:63], v[144:147], v[186:189], v[60:63]
	v_mfma_f32_16x16x32_bf16 v[56:59], v[160:163], v[186:189], v[56:59]
	v_mfma_f32_16x16x32_bf16 v[44:47], v[144:147], v[194:197], v[44:47]
	v_mfma_f32_16x16x32_bf16 v[40:43], v[160:163], v[194:197], v[40:43]
	v_mfma_f32_16x16x32_bf16 v[28:31], v[144:147], v[202:205], v[28:31]
	v_mfma_f32_16x16x32_bf16 v[24:27], v[160:163], v[202:205], v[24:27]
	v_mfma_f32_16x16x32_bf16 v[12:15], v[144:147], v[210:213], v[12:15]
	v_mfma_f32_16x16x32_bf16 v[8:11], v[160:163], v[210:213], v[8:11]
	v_mfma_f32_16x16x32_bf16 v[60:63], v[148:151], v[190:193], v[60:63]
	v_mfma_f32_16x16x32_bf16 v[56:59], v[164:167], v[190:193], v[56:59]
	v_mfma_f32_16x16x32_bf16 v[44:47], v[148:151], v[198:201], v[44:47]
	v_mfma_f32_16x16x32_bf16 v[40:43], v[164:167], v[198:201], v[40:43]
	v_mfma_f32_16x16x32_bf16 v[28:31], v[148:151], v[206:209], v[28:31]
	v_mfma_f32_16x16x32_bf16 v[24:27], v[164:167], v[206:209], v[24:27]
	v_mfma_f32_16x16x32_bf16 v[12:15], v[148:151], v[214:217], v[12:15]
	v_mfma_f32_16x16x32_bf16 v[8:11], v[164:167], v[214:217], v[8:11]
	v_mfma_f32_16x16x32_bf16 v[52:55], v[168:171], v[186:189], v[52:55]
	v_mfma_f32_16x16x32_bf16 v[48:51], v[176:179], v[186:189], v[48:51]
	v_mfma_f32_16x16x32_bf16 v[36:39], v[168:171], v[194:197], v[36:39]
	v_mfma_f32_16x16x32_bf16 v[32:35], v[176:179], v[194:197], v[32:35]
	v_mfma_f32_16x16x32_bf16 v[20:23], v[168:171], v[202:205], v[20:23]
	v_mfma_f32_16x16x32_bf16 v[16:19], v[176:179], v[202:205], v[16:19]
	v_mfma_f32_16x16x32_bf16 v[4:7], v[168:171], v[210:213], v[4:7]
	v_mfma_f32_16x16x32_bf16 v[0:3], v[176:179], v[210:213], v[0:3]
	v_mfma_f32_16x16x32_bf16 v[52:55], v[172:175], v[190:193], v[52:55]
	v_mfma_f32_16x16x32_bf16 v[48:51], v[180:183], v[190:193], v[48:51]
	v_mfma_f32_16x16x32_bf16 v[36:39], v[172:175], v[198:201], v[36:39]
	v_mfma_f32_16x16x32_bf16 v[32:35], v[180:183], v[198:201], v[32:35]
	v_mfma_f32_16x16x32_bf16 v[20:23], v[172:175], v[206:209], v[20:23]
	v_mfma_f32_16x16x32_bf16 v[16:19], v[180:183], v[206:209], v[16:19]
	v_mfma_f32_16x16x32_bf16 v[4:7], v[172:175], v[214:217], v[4:7]
	v_mfma_f32_16x16x32_bf16 v[0:3], v[180:183], v[214:217], v[0:3]
	s_barrier
	s_add_i32 s18, s18, 2
	s_add_u32 s6, s6, 0x100
	s_addc_u32 s7, s7, 0
	s_add_u32 s16, s16, 0x100
	s_addc_u32 s17, s17, 0
	s_cmp_gt_u32 s18, 13
	s_cbranch_scc0 .LBB0_546
	s_and_b64 vcc, exec, s[30:31]
	s_cbranch_vccz .LBB0_549
	s_barrier

.LBB0_759:
	s_cmp_gt_i32 s79, 4
	s_cselect_b64 s[0:1], -1, 0
	s_and_b64 s[0:1], s[24:25], s[0:1]
	s_andn2_b64 vcc, exec, s[0:1]
	s_cbranch_vccnz .LBB0_813
	s_waitcnt vmcnt(0) lgkmcnt(0)
	s_barrier
	v_readlane_b32 s21, v242, 63
	s_add_u32 s21, s21, 1
	v_readlane_b32 s12, v242, 1
	v_readlane_b32 s13, v242, 2
	s_mov_b64 s[14:15], exec
	s_and_b64 s[12:13], s[14:15], s[12:13]
	s_mov_b64 exec, s[12:13]
	s_cbranch_execz .Lxb_done_3
	v_mov_b32_e32 v0, 0x21020
	ds_read2_b32 v[2:3], v0 offset1:1
	s_lshl_b32 s16, s84, 8
	s_add_u32 s16, s76, s16
	s_addc_u32 s17, s77, 0
	v_mov_b32_e32 v1, 0x1000
	v_mov_b32_e32 v4, 1
	global_atomic_add v5, v1, v4, s[16:17] offset:1024 sc0
	buffer_inv sc1
	s_waitcnt vmcnt(0) lgkmcnt(0)
	v_readfirstlane_b32 s18, v5
	v_readfirstlane_b32 s19, v2
	v_readfirstlane_b32 s20, v3
	v_mov_b32_e32 v1, 0x3000
	s_mul_i32 s22, s19, s21
	s_mul_i32 s23, s20, s21
	s_add_u32 s18, s18, 1
	s_cmp_lg_u32 s18, s22
	s_cbranch_scc1 .Lxb_spin_3
	buffer_wbl2 sc1
	s_waitcnt vmcnt(0)
	global_atomic_add v1, v4, s[76:77] offset:1024

.LBB0_860:
	s_add_u32 s17, s88, s90
	s_addc_u32 s20, s89, s91
	s_add_u32 s21, s17, 0x100
	s_addc_u32 s22, s20, 0
	s_and_b64 s[18:19], s[42:43], exec
	s_cselect_b32 s93, s39, s22
	s_cselect_b32 s92, s38, s21
	s_add_u32 s18, s80, s90
	s_addc_u32 s19, s81, s91
	s_add_u32 s21, s18, 0x100
	s_addc_u32 s22, s19, 0
	s_and_b64 s[18:19], s[42:43], exec
	s_cselect_b32 s95, s15, s22
	s_cselect_b32 s94, s16, s21
	s_add_u32 vcc_lo, s17, 0x40080
	ds_read_b128 v[36:39], v219
	ds_read_b128 v[40:43], v219 offset:1024
	ds_read_b128 v[44:47], v219 offset:2048
	ds_read_b128 v[52:55], v219 offset:3072
	ds_read_b128 v[60:63], v220
	ds_read_b128 v[64:67], v220 offset:1024
	ds_read_b128 v[68:71], v220 offset:2048
	ds_read_b128 v[84:87], v220 offset:3072
	s_addc_u32 vcc_hi, s20, 0
	s_add_i32 s74, s72, s63
	s_add_i32 m0, s41, 0xc000
	s_add_i32 s75, s41, 0xe000
	s_add_i32 s23, s74, 0x2000
	s_add_u32 s96, s94, 0x10000
	s_addc_u32 s97, s95, 0
	s_add_i32 s37, s73, s63
	s_add_i32 s35, s37, 0x2000
	s_add_i32 s22, 0, 0x18000
	s_add_i32 s21, 0, 0x1c000
	s_add_u32 s90, s92, 0x40000
	s_addc_u32 s91, s93, 0
	s_add_i32 s20, s22, s63
	s_add_i32 s18, s20, 0x2000
	s_add_u32 s42, s94, 0x10080
	s_addc_u32 s43, s95, 0
	s_add_i32 s19, s21, s63
	s_add_i32 s17, s19, 0x2000
	v_lshl_add_u64 v[206:207], vcc, 0, v[186:187]
	ds_read_b128 v[100:103], v221
	ds_read_b128 v[120:123], v221 offset:1024
	ds_read_b128 v[136:139], v221 offset:2048
	ds_read_b128 v[156:159], v221 offset:3072
	ds_read_b128 v[176:179], v221 offset:4096
	ds_read_b128 v[180:183], v221 offset:5120
	ds_read_b128 v[198:201], v221 offset:6144
	ds_read_b128 v[202:205], v221 offset:7168
	global_load_lds_dwordx4 v[206:207], off
	v_lshl_add_u64 v[206:207], vcc, 0, v[190:191]
	s_mov_b32 m0, s75
	s_nop 0
	global_load_lds_dwordx4 v[206:207], off
	s_waitcnt vmcnt(8)
	s_waitcnt lgkmcnt(0)
	s_barrier
	s_waitcnt lgkmcnt(0)
	v_mfma_f32_16x16x32_bf16 v[172:175], v[36:39], v[100:103], v[172:175]
	v_mfma_f32_16x16x32_bf16 v[164:167], v[44:47], v[100:103], v[164:167]
	v_mfma_f32_16x16x32_bf16 v[152:155], v[36:39], v[136:139], v[152:155]
	v_mfma_f32_16x16x32_bf16 v[144:147], v[44:47], v[136:139], v[144:147]
	v_mfma_f32_16x16x32_bf16 v[132:135], v[36:39], v[176:179], v[132:135]
	v_mfma_f32_16x16x32_bf16 v[124:127], v[44:47], v[176:179], v[124:127]
	v_mfma_f32_16x16x32_bf16 v[112:115], v[36:39], v[198:201], v[112:115]
	v_mfma_f32_16x16x32_bf16 v[104:107], v[44:47], v[198:201], v[104:107]
	v_mfma_f32_16x16x32_bf16 v[172:175], v[40:43], v[120:123], v[172:175]
	v_mfma_f32_16x16x32_bf16 v[164:167], v[52:55], v[120:123], v[164:167]
	v_mfma_f32_16x16x32_bf16 v[152:155], v[40:43], v[156:159], v[152:155]
	v_mfma_f32_16x16x32_bf16 v[144:147], v[52:55], v[156:159], v[144:147]
	v_mfma_f32_16x16x32_bf16 v[132:135], v[40:43], v[180:183], v[132:135]
	v_mfma_f32_16x16x32_bf16 v[124:127], v[52:55], v[180:183], v[124:127]
	v_mfma_f32_16x16x32_bf16 v[112:115], v[40:43], v[202:205], v[112:115]
	v_mfma_f32_16x16x32_bf16 v[104:107], v[52:55], v[202:205], v[104:107]
	v_mfma_f32_16x16x32_bf16 v[168:171], v[60:63], v[100:103], v[168:171]
	v_mfma_f32_16x16x32_bf16 v[100:103], v[68:71], v[100:103], v[160:163]
	v_mfma_f32_16x16x32_bf16 v[128:131], v[60:63], v[176:179], v[128:131]
	v_mfma_f32_16x16x32_bf16 v[116:119], v[68:71], v[176:179], v[116:119]
	v_mfma_f32_16x16x32_bf16 v[108:111], v[60:63], v[198:201], v[108:111]
	v_mfma_f32_16x16x32_bf16 v[96:99], v[68:71], v[198:201], v[96:99]
	v_mfma_f32_16x16x32_bf16 v[168:171], v[64:67], v[120:123], v[168:171]
	v_mfma_f32_16x16x32_bf16 v[100:103], v[84:87], v[120:123], v[100:103]
	v_mfma_f32_16x16x32_bf16 v[120:123], v[60:63], v[136:139], v[148:151]
	v_mfma_f32_16x16x32_bf16 v[136:139], v[68:71], v[136:139], v[140:143]
	v_mfma_f32_16x16x32_bf16 v[128:131], v[64:67], v[180:183], v[128:131]
	v_mfma_f32_16x16x32_bf16 v[116:119], v[84:87], v[180:183], v[116:119]
	v_mfma_f32_16x16x32_bf16 v[108:111], v[64:67], v[202:205], v[108:111]
	v_mfma_f32_16x16x32_bf16 v[96:99], v[84:87], v[202:205], v[96:99]
	v_mfma_f32_16x16x32_bf16 v[120:123], v[64:67], v[156:159], v[120:123]
	v_mfma_f32_16x16x32_bf16 v[136:139], v[84:87], v[156:159], v[136:139]
	s_barrier
	s_mov_b32 m0, s74
	ds_read_b128 v[140:143], v221 offset:16384
	ds_read_b128 v[148:151], v221 offset:17408
	ds_read_b128 v[156:159], v221 offset:18432
	ds_read_b128 v[160:163], v221 offset:19456
	ds_read_b128 v[176:179], v221 offset:20480
	ds_read_b128 v[180:183], v221 offset:21504
	ds_read_b128 v[198:201], v221 offset:22528
	ds_read_b128 v[202:205], v221 offset:23552
	global_load_lds_dwordx4 v188, s[94:95]
	s_mov_b32 m0, s23
	global_load_lds_dwordx4 v192, s[94:95]
	s_mov_b32 m0, s37
	global_load_lds_dwordx4 v188, s[96:97]
	s_mov_b32 m0, s35
	v_lshl_add_u64 v[226:227], s[92:93], 0, v[190:191]
	global_load_lds_dwordx4 v192, s[96:97]
	s_mov_b32 m0, s41
	s_nop 0
	global_load_lds_dwordx4 v186, s[92:93]
	s_mov_b32 m0, s64
	s_nop 0
	global_load_lds_dwordx4 v190, s[92:93]
	s_add_u32 s98, s94, s28
	s_addc_u32 s99, s95, s29
	s_add_u32 s100, s92, s28
	s_addc_u32 s101, s93, s29
	s_waitcnt vmcnt(8)
	s_waitcnt lgkmcnt(0)
	s_barrier
	s_waitcnt lgkmcnt(0)
	v_mfma_f32_16x16x32_bf16 v[92:95], v[36:39], v[140:143], v[92:95]
	v_mfma_f32_16x16x32_bf16 v[80:83], v[44:47], v[140:143], v[80:83]
	v_mfma_f32_16x16x32_bf16 v[72:75], v[36:39], v[156:159], v[72:75]
	v_mfma_f32_16x16x32_bf16 v[48:51], v[44:47], v[156:159], v[48:51]
	v_mfma_f32_16x16x32_bf16 v[28:31], v[36:39], v[176:179], v[28:31]
	v_mfma_f32_16x16x32_bf16 v[20:23], v[44:47], v[176:179], v[20:23]
	v_mfma_f32_16x16x32_bf16 v[12:15], v[36:39], v[198:201], v[12:15]
	v_mfma_f32_16x16x32_bf16 v[4:7], v[44:47], v[198:201], v[4:7]
	v_mfma_f32_16x16x32_bf16 v[92:95], v[40:43], v[148:151], v[92:95]
	v_mfma_f32_16x16x32_bf16 v[80:83], v[52:55], v[148:151], v[80:83]
	v_mfma_f32_16x16x32_bf16 v[72:75], v[40:43], v[160:163], v[72:75]
	v_mfma_f32_16x16x32_bf16 v[48:51], v[52:55], v[160:163], v[48:51]
	v_mfma_f32_16x16x32_bf16 v[28:31], v[40:43], v[180:183], v[28:31]
	v_mfma_f32_16x16x32_bf16 v[20:23], v[52:55], v[180:183], v[20:23]
	v_mfma_f32_16x16x32_bf16 v[12:15], v[40:43], v[202:205], v[12:15]
	v_mfma_f32_16x16x32_bf16 v[4:7], v[52:55], v[202:205], v[4:7]
	v_mfma_f32_16x16x32_bf16 v[32:35], v[68:71], v[156:159], v[32:35]
	v_mfma_f32_16x16x32_bf16 v[24:27], v[60:63], v[176:179], v[24:27]
	v_mfma_f32_16x16x32_bf16 v[16:19], v[68:71], v[176:179], v[16:19]
	v_mfma_f32_16x16x32_bf16 v[8:11], v[60:63], v[198:201], v[8:11]
	v_mfma_f32_16x16x32_bf16 v[0:3], v[68:71], v[198:201], v[0:3]
	v_mfma_f32_16x16x32_bf16 v[36:39], v[60:63], v[140:143], v[88:91]
	v_mfma_f32_16x16x32_bf16 v[40:43], v[68:71], v[140:143], v[76:79]
	v_mfma_f32_16x16x32_bf16 v[44:47], v[60:63], v[156:159], v[56:59]
	v_mfma_f32_16x16x32_bf16 v[32:35], v[84:87], v[160:163], v[32:35]
	v_mfma_f32_16x16x32_bf16 v[24:27], v[64:67], v[180:183], v[24:27]
	v_mfma_f32_16x16x32_bf16 v[16:19], v[84:87], v[180:183], v[16:19]
	v_mfma_f32_16x16x32_bf16 v[8:11], v[64:67], v[202:205], v[8:11]
	v_mfma_f32_16x16x32_bf16 v[0:3], v[84:87], v[202:205], v[0:3]
	v_mfma_f32_16x16x32_bf16 v[36:39], v[64:67], v[148:151], v[36:39]
	v_mfma_f32_16x16x32_bf16 v[40:43], v[84:87], v[148:151], v[40:43]
	v_mfma_f32_16x16x32_bf16 v[44:47], v[64:67], v[160:163], v[44:47]
	s_barrier
	v_add_u32_e32 v64, s22, v217
	v_add_u32_e32 v76, s21, v217
	ds_read_b128 v[52:55], v64
	ds_read_b128 v[56:59], v64 offset:1024
	ds_read_b128 v[60:63], v64 offset:2048
	ds_read_b128 v[64:67], v64 offset:3072
	ds_read_b128 v[68:71], v76
	ds_read_b128 v[84:87], v76 offset:1024
	ds_read_b128 v[156:159], v76 offset:2048
	ds_read_b128 v[176:179], v76 offset:3072
	s_mov_b32 m0, s65
	ds_read_b128 v[76:79], v221 offset:32768
	ds_read_b128 v[88:91], v221 offset:33792
	ds_read_b128 v[140:143], v221 offset:34816
	ds_read_b128 v[180:183], v221 offset:35840
	ds_read_b128 v[198:201], v221 offset:36864
	ds_read_b128 v[202:205], v221 offset:37888
	ds_read_b128 v[206:209], v221 offset:38912
	ds_read_b128 v[210:213], v221 offset:39936
	global_load_lds_dwordx4 v186, s[90:91]
	v_lshl_add_u64 v[148:149], s[90:91], 0, v[190:191]
	s_mov_b32 m0, s66
	s_nop 0
	global_load_lds_dwordx4 v190, s[90:91]
	s_waitcnt vmcnt(8)
	s_waitcnt lgkmcnt(0)
	s_barrier
	s_waitcnt lgkmcnt(0)
	v_mfma_f32_16x16x32_bf16 v[148:151], v[52:55], v[76:79], v[172:175]
	v_mfma_f32_16x16x32_bf16 v[172:175], v[56:59], v[88:91], v[148:151]
	v_mfma_f32_16x16x32_bf16 v[148:151], v[60:63], v[76:79], v[164:167]
	v_mfma_f32_16x16x32_bf16 v[164:167], v[64:67], v[88:91], v[148:151]
	v_mfma_f32_16x16x32_bf16 v[148:151], v[52:55], v[140:143], v[152:155]
	v_mfma_f32_16x16x32_bf16 v[144:147], v[60:63], v[140:143], v[144:147]
	v_mfma_f32_16x16x32_bf16 v[132:135], v[52:55], v[198:201], v[132:135]
	v_mfma_f32_16x16x32_bf16 v[124:127], v[60:63], v[198:201], v[124:127]
	v_mfma_f32_16x16x32_bf16 v[112:115], v[52:55], v[206:209], v[112:115]
	v_mfma_f32_16x16x32_bf16 v[104:107], v[60:63], v[206:209], v[104:107]
	v_mfma_f32_16x16x32_bf16 v[152:155], v[56:59], v[180:183], v[148:151]
	v_mfma_f32_16x16x32_bf16 v[144:147], v[64:67], v[180:183], v[144:147]
	v_mfma_f32_16x16x32_bf16 v[132:135], v[56:59], v[202:205], v[132:135]
	v_mfma_f32_16x16x32_bf16 v[124:127], v[64:67], v[202:205], v[124:127]
	v_mfma_f32_16x16x32_bf16 v[112:115], v[56:59], v[210:213], v[112:115]
	v_mfma_f32_16x16x32_bf16 v[104:107], v[64:67], v[210:213], v[104:107]
	v_mfma_f32_16x16x32_bf16 v[148:151], v[68:71], v[76:79], v[168:171]
	v_mfma_f32_16x16x32_bf16 v[76:79], v[156:159], v[76:79], v[100:103]
	v_mfma_f32_16x16x32_bf16 v[160:163], v[176:179], v[88:91], v[76:79]
	v_mfma_f32_16x16x32_bf16 v[76:79], v[68:71], v[140:143], v[120:123]
	v_mfma_f32_16x16x32_bf16 v[168:171], v[84:87], v[88:91], v[148:151]
	v_mfma_f32_16x16x32_bf16 v[148:151], v[84:87], v[180:183], v[76:79]
	v_mfma_f32_16x16x32_bf16 v[76:79], v[156:159], v[140:143], v[136:139]
	v_mfma_f32_16x16x32_bf16 v[140:143], v[176:179], v[180:183], v[76:79]
	v_mfma_f32_16x16x32_bf16 v[76:79], v[68:71], v[198:201], v[128:131]
	v_mfma_f32_16x16x32_bf16 v[128:131], v[84:87], v[202:205], v[76:79]
	v_mfma_f32_16x16x32_bf16 v[76:79], v[156:159], v[198:201], v[116:119]
	v_mfma_f32_16x16x32_bf16 v[116:119], v[176:179], v[202:205], v[76:79]
	v_mfma_f32_16x16x32_bf16 v[76:79], v[68:71], v[206:209], v[108:111]
	v_mfma_f32_16x16x32_bf16 v[108:111], v[84:87], v[210:213], v[76:79]
	v_mfma_f32_16x16x32_bf16 v[76:79], v[156:159], v[206:209], v[96:99]
	v_mfma_f32_16x16x32_bf16 v[96:99], v[176:179], v[210:213], v[76:79]
	s_barrier
	s_mov_b32 m0, s20
	s_nop 2
	ds_read_b128 v[76:79], v221 offset:49152
	ds_read_b128 v[100:103], v221 offset:50176
	ds_read_b128 v[120:123], v221 offset:51200
	ds_read_b128 v[136:139], v221 offset:52224
	ds_read_b128 v[180:183], v221 offset:53248
	ds_read_b128 v[198:201], v221 offset:54272
	ds_read_b128 v[202:205], v221 offset:55296
	ds_read_b128 v[206:209], v221 offset:56320
	global_load_lds_dwordx4 v188, s[98:99]
	s_mov_b32 m0, s18
	s_nop 0
	global_load_lds_dwordx4 v192, s[98:99]
	s_mov_b32 m0, s19
	s_nop 0
	global_load_lds_dwordx4 v188, s[42:43]
	s_mov_b32 m0, s17
	s_nop 0
	global_load_lds_dwordx4 v192, s[42:43]
	s_mov_b32 m0, s70
	s_nop 0
	global_load_lds_dwordx4 v186, s[100:101]
	v_lshl_add_u64 v[88:89], v[226:227], 0, s[28:29]
	s_mov_b32 m0, s71
	s_nop 0
	global_load_lds_dwordx4 v190, s[100:101]
	s_waitcnt vmcnt(8)
	s_waitcnt lgkmcnt(0)
	s_barrier
	s_waitcnt lgkmcnt(0)
	v_mfma_f32_16x16x32_bf16 v[88:91], v[52:55], v[76:79], v[92:95]
	v_mfma_f32_16x16x32_bf16 v[80:83], v[60:63], v[76:79], v[80:83]
	v_mfma_f32_16x16x32_bf16 v[72:75], v[52:55], v[120:123], v[72:75]
	v_mfma_f32_16x16x32_bf16 v[48:51], v[60:63], v[120:123], v[48:51]
	v_mfma_f32_16x16x32_bf16 v[28:31], v[52:55], v[180:183], v[28:31]
	v_mfma_f32_16x16x32_bf16 v[20:23], v[60:63], v[180:183], v[20:23]
	v_mfma_f32_16x16x32_bf16 v[12:15], v[52:55], v[202:205], v[12:15]
	v_mfma_f32_16x16x32_bf16 v[4:7], v[60:63], v[202:205], v[4:7]
	v_mfma_f32_16x16x32_bf16 v[92:95], v[56:59], v[100:103], v[88:91]
	v_mfma_f32_16x16x32_bf16 v[80:83], v[64:67], v[100:103], v[80:83]
	v_mfma_f32_16x16x32_bf16 v[72:75], v[56:59], v[136:139], v[72:75]
	v_mfma_f32_16x16x32_bf16 v[48:51], v[64:67], v[136:139], v[48:51]
	v_mfma_f32_16x16x32_bf16 v[28:31], v[56:59], v[198:201], v[28:31]
	v_mfma_f32_16x16x32_bf16 v[20:23], v[64:67], v[198:201], v[20:23]
	v_mfma_f32_16x16x32_bf16 v[12:15], v[56:59], v[206:209], v[12:15]
	v_mfma_f32_16x16x32_bf16 v[4:7], v[64:67], v[206:209], v[4:7]
	v_mfma_f32_16x16x32_bf16 v[36:39], v[68:71], v[76:79], v[36:39]
	v_mfma_f32_16x16x32_bf16 v[88:91], v[84:87], v[100:103], v[36:39]
	v_mfma_f32_16x16x32_bf16 v[36:39], v[156:159], v[76:79], v[40:43]
	v_mfma_f32_16x16x32_bf16 v[76:79], v[176:179], v[100:103], v[36:39]
	v_mfma_f32_16x16x32_bf16 v[36:39], v[68:71], v[120:123], v[44:47]
	v_mfma_f32_16x16x32_bf16 v[32:35], v[156:159], v[120:123], v[32:35]
	v_mfma_f32_16x16x32_bf16 v[24:27], v[68:71], v[180:183], v[24:27]
	v_mfma_f32_16x16x32_bf16 v[16:19], v[156:159], v[180:183], v[16:19]
	v_mfma_f32_16x16x32_bf16 v[8:11], v[68:71], v[202:205], v[8:11]
	v_mfma_f32_16x16x32_bf16 v[0:3], v[156:159], v[202:205], v[0:3]
	v_mfma_f32_16x16x32_bf16 v[56:59], v[84:87], v[136:139], v[36:39]
	v_mfma_f32_16x16x32_bf16 v[32:35], v[176:179], v[136:139], v[32:35]
	v_mfma_f32_16x16x32_bf16 v[24:27], v[84:87], v[198:201], v[24:27]
	v_mfma_f32_16x16x32_bf16 v[16:19], v[176:179], v[198:201], v[16:19]
	v_mfma_f32_16x16x32_bf16 v[8:11], v[84:87], v[206:209], v[8:11]
	v_mfma_f32_16x16x32_bf16 v[0:3], v[176:179], v[206:209], v[0:3]
	s_barrier
	s_andn2_b64 vcc, exec, s[0:1]
	s_mov_b64 s[42:43], -1
	s_mov_b64 s[0:1], 0
	s_mov_b64 s[90:91], 0x100
	s_cbranch_vccz .LBB0_860
	s_and_b64 vcc, exec, s[30:31]
	s_cbranch_vccz .LBB0_863
	s_barrier

.LBB0_882:
	s_cmp_gt_i32 s79, 6
	s_cselect_b64 s[0:1], -1, 0
	s_and_b64 s[0:1], s[6:7], s[0:1]
	s_andn2_b64 vcc, exec, s[0:1]
	s_cbranch_vccnz .LBB0_936
	s_waitcnt vmcnt(0) lgkmcnt(0)
	s_barrier
	v_readlane_b32 s21, v242, 63
	s_add_u32 s21, s21, 1
	v_readlane_b32 s12, v242, 1
	v_readlane_b32 s13, v242, 2
	s_mov_b64 s[14:15], exec
	s_and_b64 s[12:13], s[14:15], s[12:13]
	s_mov_b64 exec, s[12:13]
	s_cbranch_execz .Lxb_done_4
	v_mov_b32_e32 v0, 0x21020
	ds_read2_b32 v[2:3], v0 offset1:1
	s_lshl_b32 s16, s84, 8
	s_add_u32 s16, s76, s16
	s_addc_u32 s17, s77, 0
	v_mov_b32_e32 v1, 0x1000
	v_mov_b32_e32 v4, 1
	global_atomic_add v5, v1, v4, s[16:17] offset:1024 sc0
	buffer_inv sc1
	s_waitcnt vmcnt(0) lgkmcnt(0)
	v_readfirstlane_b32 s18, v5
	v_readfirstlane_b32 s19, v2
	v_readfirstlane_b32 s20, v3
	v_mov_b32_e32 v1, 0x3000
	s_mul_i32 s22, s19, s21
	s_mul_i32 s23, s20, s21
	s_add_u32 s18, s18, 1
	s_cmp_lg_u32 s18, s22
	s_cbranch_scc1 .Lxb_spin_4
	buffer_wbl2 sc1
	s_waitcnt vmcnt(0)
	global_atomic_add v1, v4, s[76:77] offset:1024

.LBB0_952:
	s_cmp_gt_i32 s79, 8
	s_cselect_b64 s[6:7], -1, 0
	s_and_b64 s[0:1], s[4:5], s[6:7]
	s_andn2_b64 vcc, exec, s[0:1]
	s_cbranch_vccnz .LBB0_1006
	s_waitcnt vmcnt(0) lgkmcnt(0)
	s_barrier
	v_readlane_b32 s21, v242, 63
	s_add_u32 s21, s21, 1
	v_readlane_b32 s12, v242, 1
	v_readlane_b32 s13, v242, 2
	s_mov_b64 s[14:15], exec
	s_and_b64 s[12:13], s[14:15], s[12:13]
	s_mov_b64 exec, s[12:13]
	s_cbranch_execz .Lxb_done_5
	v_mov_b32_e32 v0, 0x21020
	ds_read2_b32 v[2:3], v0 offset1:1
	s_lshl_b32 s16, s84, 8
	s_add_u32 s16, s76, s16
	s_addc_u32 s17, s77, 0
	v_mov_b32_e32 v1, 0x1000
	v_mov_b32_e32 v4, 1
	global_atomic_add v5, v1, v4, s[16:17] offset:1024 sc0
	buffer_inv sc1
	s_waitcnt vmcnt(0) lgkmcnt(0)
	v_readfirstlane_b32 s18, v5
	v_readfirstlane_b32 s19, v2
	v_readfirstlane_b32 s20, v3
	v_mov_b32_e32 v1, 0x3000
	s_mul_i32 s22, s19, s21
	s_mul_i32 s23, s20, s21
	s_add_u32 s18, s18, 1
	s_cmp_lg_u32 s18, s22
	s_cbranch_scc1 .Lxb_spin_5
	buffer_wbl2 sc1
	s_waitcnt vmcnt(0)
	global_atomic_add v1, v4, s[76:77] offset:1024

.LBB0_1026:
	ds_read_b128 v[128:131], v189
	ds_read_b128 v[132:135], v189 offset:1024
	ds_read_b128 v[136:139], v189 offset:2048
	ds_read_b128 v[140:143], v189 offset:3072
	ds_read_b128 v[144:147], v190
	ds_read_b128 v[148:151], v190 offset:1024
	ds_read_b128 v[172:175], v190 offset:2048
	ds_read_b128 v[176:179], v190 offset:3072
	s_add_u32 s42, s40, 0xfffc0080
	s_addc_u32 s43, s41, -1
	s_cmp_eq_u32 s72, 12
	s_cselect_b32 s63, s27, s43
	s_cselect_b32 s62, s37, s42
	s_cselect_b32 s43, s29, s71
	s_cselect_b32 s42, s39, s70
	s_add_i32 m0, s18, 0xc000
	ds_read_b128 v[180:183], v191
	ds_read_b128 v[194:197], v191 offset:1024
	ds_read_b128 v[198:201], v191 offset:2048
	ds_read_b128 v[202:205], v191 offset:3072
	ds_read_b128 v[206:209], v191 offset:4096
	ds_read_b128 v[210:213], v191 offset:5120
	ds_read_b128 v[214:217], v191 offset:6144
	ds_read_b128 v[218:221], v191 offset:7168
	global_load_lds_dwordx4 v164, s[40:41]
	s_add_i32 m0, s18, 0xe000
	s_nop 0
	global_load_lds_dwordx4 v166, s[40:41]
	s_waitcnt vmcnt(8)
	s_waitcnt lgkmcnt(0)
	s_barrier
	s_waitcnt lgkmcnt(0)
	v_mfma_f32_16x16x32_bf16 v[124:127], v[128:131], v[180:183], v[124:127]
	v_mfma_f32_16x16x32_bf16 v[120:123], v[136:139], v[180:183], v[120:123]
	v_mfma_f32_16x16x32_bf16 v[108:111], v[128:131], v[198:201], v[108:111]
	v_mfma_f32_16x16x32_bf16 v[104:107], v[136:139], v[198:201], v[104:107]
	v_mfma_f32_16x16x32_bf16 v[92:95], v[128:131], v[206:209], v[92:95]
	v_mfma_f32_16x16x32_bf16 v[88:91], v[136:139], v[206:209], v[88:91]
	v_mfma_f32_16x16x32_bf16 v[76:79], v[128:131], v[214:217], v[76:79]
	v_mfma_f32_16x16x32_bf16 v[72:75], v[136:139], v[214:217], v[72:75]
	v_mfma_f32_16x16x32_bf16 v[124:127], v[132:135], v[194:197], v[124:127]
	v_mfma_f32_16x16x32_bf16 v[120:123], v[140:143], v[194:197], v[120:123]
	v_mfma_f32_16x16x32_bf16 v[108:111], v[132:135], v[202:205], v[108:111]
	v_mfma_f32_16x16x32_bf16 v[104:107], v[140:143], v[202:205], v[104:107]
	v_mfma_f32_16x16x32_bf16 v[92:95], v[132:135], v[210:213], v[92:95]
	v_mfma_f32_16x16x32_bf16 v[88:91], v[140:143], v[210:213], v[88:91]
	v_mfma_f32_16x16x32_bf16 v[76:79], v[132:135], v[218:221], v[76:79]
	v_mfma_f32_16x16x32_bf16 v[72:75], v[140:143], v[218:221], v[72:75]
	v_mfma_f32_16x16x32_bf16 v[116:119], v[144:147], v[180:183], v[116:119]
	v_mfma_f32_16x16x32_bf16 v[112:115], v[172:175], v[180:183], v[112:115]
	v_mfma_f32_16x16x32_bf16 v[100:103], v[144:147], v[198:201], v[100:103]
	v_mfma_f32_16x16x32_bf16 v[96:99], v[172:175], v[198:201], v[96:99]
	v_mfma_f32_16x16x32_bf16 v[84:87], v[144:147], v[206:209], v[84:87]
	v_mfma_f32_16x16x32_bf16 v[80:83], v[172:175], v[206:209], v[80:83]
	v_mfma_f32_16x16x32_bf16 v[68:71], v[144:147], v[214:217], v[68:71]
	v_mfma_f32_16x16x32_bf16 v[64:67], v[172:175], v[214:217], v[64:67]
	v_mfma_f32_16x16x32_bf16 v[116:119], v[148:151], v[194:197], v[116:119]
	v_mfma_f32_16x16x32_bf16 v[112:115], v[176:179], v[194:197], v[112:115]
	v_mfma_f32_16x16x32_bf16 v[100:103], v[148:151], v[202:205], v[100:103]
	v_mfma_f32_16x16x32_bf16 v[96:99], v[176:179], v[202:205], v[96:99]
	v_mfma_f32_16x16x32_bf16 v[84:87], v[148:151], v[210:213], v[84:87]
	v_mfma_f32_16x16x32_bf16 v[80:83], v[176:179], v[210:213], v[80:83]
	v_mfma_f32_16x16x32_bf16 v[68:71], v[148:151], v[218:221], v[68:71]
	v_mfma_f32_16x16x32_bf16 v[64:67], v[176:179], v[218:221], v[64:67]
	s_barrier
	s_add_i32 s73, s66, s17
	s_mov_b32 m0, s73
	ds_read_b128 v[180:183], v191 offset:16384
	ds_read_b128 v[194:197], v191 offset:17408
	ds_read_b128 v[198:201], v191 offset:18432
	ds_read_b128 v[202:205], v191 offset:19456
	ds_read_b128 v[206:209], v191 offset:20480
	ds_read_b128 v[210:213], v191 offset:21504
	ds_read_b128 v[214:217], v191 offset:22528
	ds_read_b128 v[218:221], v191 offset:23552
	global_load_lds_dwordx4 v154, s[42:43]
	s_add_i32 m0, s73, 0x2000
	s_add_u32 s74, s42, 0x40000
	s_addc_u32 s75, s43, 0
	s_add_i32 s73, s67, s17
	global_load_lds_dwordx4 v158, s[42:43]
	s_mov_b32 m0, s73
	global_load_lds_dwordx4 v154, s[74:75]
	s_add_i32 m0, s73, 0x2000
	s_nop 0
	global_load_lds_dwordx4 v158, s[74:75]
	s_mov_b32 m0, s18
	s_nop 0
	global_load_lds_dwordx4 v152, s[62:63]
	s_mov_b32 m0, s19
	s_nop 0
	global_load_lds_dwordx4 v156, s[62:63]
	s_add_u32 s98, s42, s12
	s_addc_u32 s99, s43, s13
	s_add_u32 s100, s62, s12
	s_addc_u32 s101, s63, s13
	s_waitcnt vmcnt(8)
	s_waitcnt lgkmcnt(0)
	s_barrier
	s_waitcnt lgkmcnt(0)
	v_mfma_f32_16x16x32_bf16 v[60:63], v[128:131], v[180:183], v[60:63]
	v_mfma_f32_16x16x32_bf16 v[56:59], v[136:139], v[180:183], v[56:59]
	v_mfma_f32_16x16x32_bf16 v[44:47], v[128:131], v[198:201], v[44:47]
	v_mfma_f32_16x16x32_bf16 v[40:43], v[136:139], v[198:201], v[40:43]
	v_mfma_f32_16x16x32_bf16 v[28:31], v[128:131], v[206:209], v[28:31]
	v_mfma_f32_16x16x32_bf16 v[24:27], v[136:139], v[206:209], v[24:27]
	v_mfma_f32_16x16x32_bf16 v[12:15], v[128:131], v[214:217], v[12:15]
	v_mfma_f32_16x16x32_bf16 v[8:11], v[136:139], v[214:217], v[8:11]
	v_mfma_f32_16x16x32_bf16 v[60:63], v[132:135], v[194:197], v[60:63]
	v_mfma_f32_16x16x32_bf16 v[56:59], v[140:143], v[194:197], v[56:59]
	v_mfma_f32_16x16x32_bf16 v[44:47], v[132:135], v[202:205], v[44:47]
	v_mfma_f32_16x16x32_bf16 v[40:43], v[140:143], v[202:205], v[40:43]
	v_mfma_f32_16x16x32_bf16 v[28:31], v[132:135], v[210:213], v[28:31]
	v_mfma_f32_16x16x32_bf16 v[24:27], v[140:143], v[210:213], v[24:27]
	v_mfma_f32_16x16x32_bf16 v[12:15], v[132:135], v[218:221], v[12:15]
	v_mfma_f32_16x16x32_bf16 v[8:11], v[140:143], v[218:221], v[8:11]
	v_mfma_f32_16x16x32_bf16 v[52:55], v[144:147], v[180:183], v[52:55]
	v_mfma_f32_16x16x32_bf16 v[48:51], v[172:175], v[180:183], v[48:51]
	v_mfma_f32_16x16x32_bf16 v[36:39], v[144:147], v[198:201], v[36:39]
	v_mfma_f32_16x16x32_bf16 v[32:35], v[172:175], v[198:201], v[32:35]
	v_mfma_f32_16x16x32_bf16 v[20:23], v[144:147], v[206:209], v[20:23]
	v_mfma_f32_16x16x32_bf16 v[16:19], v[172:175], v[206:209], v[16:19]
	v_mfma_f32_16x16x32_bf16 v[4:7], v[144:147], v[214:217], v[4:7]
	v_mfma_f32_16x16x32_bf16 v[0:3], v[172:175], v[214:217], v[0:3]
	v_mfma_f32_16x16x32_bf16 v[52:55], v[148:151], v[194:197], v[52:55]
	v_mfma_f32_16x16x32_bf16 v[48:51], v[176:179], v[194:197], v[48:51]
	v_mfma_f32_16x16x32_bf16 v[36:39], v[148:151], v[202:205], v[36:39]
	v_mfma_f32_16x16x32_bf16 v[32:35], v[176:179], v[202:205], v[32:35]
	v_mfma_f32_16x16x32_bf16 v[20:23], v[148:151], v[210:213], v[20:23]
	v_mfma_f32_16x16x32_bf16 v[16:19], v[176:179], v[210:213], v[16:19]
	v_mfma_f32_16x16x32_bf16 v[4:7], v[148:151], v[218:221], v[4:7]
	v_mfma_f32_16x16x32_bf16 v[0:3], v[176:179], v[218:221], v[0:3]
	s_barrier
	s_add_i32 s73, 0, 0x18000
	s_add_i32 s74, 0, 0x1c000
	v_add_u32_e32 v140, s73, v186
	v_add_u32_e32 v176, s74, v186
	ds_read_b128 v[128:131], v140
	ds_read_b128 v[132:135], v140 offset:1024
	ds_read_b128 v[136:139], v140 offset:2048
	ds_read_b128 v[140:143], v140 offset:3072
	ds_read_b128 v[144:147], v176
	ds_read_b128 v[148:151], v176 offset:1024
	ds_read_b128 v[172:175], v176 offset:2048
	ds_read_b128 v[176:179], v176 offset:3072
	s_add_u32 s62, s62, 0x40000
	s_addc_u32 s63, s63, 0
	s_mov_b32 m0, s20
	ds_read_b128 v[180:183], v191 offset:32768
	ds_read_b128 v[194:197], v191 offset:33792
	ds_read_b128 v[198:201], v191 offset:34816
	ds_read_b128 v[202:205], v191 offset:35840
	ds_read_b128 v[206:209], v191 offset:36864
	ds_read_b128 v[210:213], v191 offset:37888
	ds_read_b128 v[214:217], v191 offset:38912
	ds_read_b128 v[218:221], v191 offset:39936
	global_load_lds_dwordx4 v152, s[62:63]
	s_mov_b32 m0, s21
	s_nop 0
	global_load_lds_dwordx4 v156, s[62:63]
	s_waitcnt vmcnt(8)
	s_waitcnt lgkmcnt(0)
	s_barrier
	s_waitcnt lgkmcnt(0)
	v_mfma_f32_16x16x32_bf16 v[124:127], v[128:131], v[180:183], v[124:127]
	v_mfma_f32_16x16x32_bf16 v[120:123], v[136:139], v[180:183], v[120:123]
	v_mfma_f32_16x16x32_bf16 v[108:111], v[128:131], v[198:201], v[108:111]
	v_mfma_f32_16x16x32_bf16 v[104:107], v[136:139], v[198:201], v[104:107]
	v_mfma_f32_16x16x32_bf16 v[92:95], v[128:131], v[206:209], v[92:95]
	v_mfma_f32_16x16x32_bf16 v[88:91], v[136:139], v[206:209], v[88:91]
	v_mfma_f32_16x16x32_bf16 v[76:79], v[128:131], v[214:217], v[76:79]
	v_mfma_f32_16x16x32_bf16 v[72:75], v[136:139], v[214:217], v[72:75]
	v_mfma_f32_16x16x32_bf16 v[124:127], v[132:135], v[194:197], v[124:127]
	v_mfma_f32_16x16x32_bf16 v[120:123], v[140:143], v[194:197], v[120:123]
	v_mfma_f32_16x16x32_bf16 v[108:111], v[132:135], v[202:205], v[108:111]
	v_mfma_f32_16x16x32_bf16 v[104:107], v[140:143], v[202:205], v[104:107]
	v_mfma_f32_16x16x32_bf16 v[92:95], v[132:135], v[210:213], v[92:95]
	v_mfma_f32_16x16x32_bf16 v[88:91], v[140:143], v[210:213], v[88:91]
	v_mfma_f32_16x16x32_bf16 v[76:79], v[132:135], v[218:221], v[76:79]
	v_mfma_f32_16x16x32_bf16 v[72:75], v[140:143], v[218:221], v[72:75]
	v_mfma_f32_16x16x32_bf16 v[116:119], v[144:147], v[180:183], v[116:119]
	v_mfma_f32_16x16x32_bf16 v[112:115], v[172:175], v[180:183], v[112:115]
	v_mfma_f32_16x16x32_bf16 v[100:103], v[144:147], v[198:201], v[100:103]
	v_mfma_f32_16x16x32_bf16 v[96:99], v[172:175], v[198:201], v[96:99]
	v_mfma_f32_16x16x32_bf16 v[84:87], v[144:147], v[206:209], v[84:87]
	v_mfma_f32_16x16x32_bf16 v[80:83], v[172:175], v[206:209], v[80:83]
	v_mfma_f32_16x16x32_bf16 v[68:71], v[144:147], v[214:217], v[68:71]
	v_mfma_f32_16x16x32_bf16 v[64:67], v[172:175], v[214:217], v[64:67]
	v_mfma_f32_16x16x32_bf16 v[116:119], v[148:151], v[194:197], v[116:119]
	v_mfma_f32_16x16x32_bf16 v[112:115], v[176:179], v[194:197], v[112:115]
	v_mfma_f32_16x16x32_bf16 v[100:103], v[148:151], v[202:205], v[100:103]
	v_mfma_f32_16x16x32_bf16 v[96:99], v[176:179], v[202:205], v[96:99]
	v_mfma_f32_16x16x32_bf16 v[84:87], v[148:151], v[210:213], v[84:87]
	v_mfma_f32_16x16x32_bf16 v[80:83], v[176:179], v[210:213], v[80:83]
	v_mfma_f32_16x16x32_bf16 v[68:71], v[148:151], v[218:221], v[68:71]
	v_mfma_f32_16x16x32_bf16 v[64:67], v[176:179], v[218:221], v[64:67]
	s_barrier
	s_add_i32 s62, s73, s17
	s_mov_b32 m0, s62
	ds_read_b128 v[180:183], v191 offset:49152
	ds_read_b128 v[194:197], v191 offset:50176
	ds_read_b128 v[198:201], v191 offset:51200
	ds_read_b128 v[202:205], v191 offset:52224
	ds_read_b128 v[206:209], v191 offset:53248
	ds_read_b128 v[210:213], v191 offset:54272
	ds_read_b128 v[214:217], v191 offset:55296
	ds_read_b128 v[218:221], v191 offset:56320
	global_load_lds_dwordx4 v154, s[98:99]
	s_add_i32 m0, s62, 0x2000
	s_add_u32 s42, s42, 0x40080
	s_addc_u32 s43, s43, 0
	s_add_i32 s62, s74, s17
	global_load_lds_dwordx4 v158, s[98:99]
	s_mov_b32 m0, s62
	s_nop 0
	global_load_lds_dwordx4 v154, s[42:43]
	s_add_i32 m0, s62, 0x2000
	s_nop 0
	global_load_lds_dwordx4 v158, s[42:43]
	s_mov_b32 m0, s23
	s_nop 0
	global_load_lds_dwordx4 v152, s[100:101]
	s_mov_b32 m0, s60
	s_nop 0
	global_load_lds_dwordx4 v156, s[100:101]
	s_waitcnt vmcnt(8)
	s_waitcnt lgkmcnt(0)
	s_barrier
	s_waitcnt lgkmcnt(0)
	v_mfma_f32_16x16x32_bf16 v[60:63], v[128:131], v[180:183], v[60:63]
	v_mfma_f32_16x16x32_bf16 v[56:59], v[136:139], v[180:183], v[56:59]
	v_mfma_f32_16x16x32_bf16 v[44:47], v[128:131], v[198:201], v[44:47]
	v_mfma_f32_16x16x32_bf16 v[40:43], v[136:139], v[198:201], v[40:43]
	v_mfma_f32_16x16x32_bf16 v[28:31], v[128:131], v[206:209], v[28:31]
	v_mfma_f32_16x16x32_bf16 v[24:27], v[136:139], v[206:209], v[24:27]
	v_mfma_f32_16x16x32_bf16 v[12:15], v[128:131], v[214:217], v[12:15]
	v_mfma_f32_16x16x32_bf16 v[8:11], v[136:139], v[214:217], v[8:11]
	v_mfma_f32_16x16x32_bf16 v[60:63], v[132:135], v[194:197], v[60:63]
	v_mfma_f32_16x16x32_bf16 v[56:59], v[140:143], v[194:197], v[56:59]
	v_mfma_f32_16x16x32_bf16 v[44:47], v[132:135], v[202:205], v[44:47]
	v_mfma_f32_16x16x32_bf16 v[40:43], v[140:143], v[202:205], v[40:43]
	v_mfma_f32_16x16x32_bf16 v[28:31], v[132:135], v[210:213], v[28:31]
	v_mfma_f32_16x16x32_bf16 v[24:27], v[140:143], v[210:213], v[24:27]
	v_mfma_f32_16x16x32_bf16 v[12:15], v[132:135], v[218:221], v[12:15]
	v_mfma_f32_16x16x32_bf16 v[8:11], v[140:143], v[218:221], v[8:11]
	v_mfma_f32_16x16x32_bf16 v[52:55], v[144:147], v[180:183], v[52:55]
	v_mfma_f32_16x16x32_bf16 v[48:51], v[172:175], v[180:183], v[48:51]
	v_mfma_f32_16x16x32_bf16 v[36:39], v[144:147], v[198:201], v[36:39]
	v_mfma_f32_16x16x32_bf16 v[32:35], v[172:175], v[198:201], v[32:35]
	v_mfma_f32_16x16x32_bf16 v[20:23], v[144:147], v[206:209], v[20:23]
	v_mfma_f32_16x16x32_bf16 v[16:19], v[172:175], v[206:209], v[16:19]
	v_mfma_f32_16x16x32_bf16 v[4:7], v[144:147], v[214:217], v[4:7]
	v_mfma_f32_16x16x32_bf16 v[0:3], v[172:175], v[214:217], v[0:3]
	v_mfma_f32_16x16x32_bf16 v[52:55], v[148:151], v[194:197], v[52:55]
	v_mfma_f32_16x16x32_bf16 v[48:51], v[176:179], v[194:197], v[48:51]
	v_mfma_f32_16x16x32_bf16 v[36:39], v[148:151], v[202:205], v[36:39]
	v_mfma_f32_16x16x32_bf16 v[32:35], v[176:179], v[202:205], v[32:35]
	v_mfma_f32_16x16x32_bf16 v[20:23], v[148:151], v[210:213], v[20:23]
	v_mfma_f32_16x16x32_bf16 v[16:19], v[176:179], v[210:213], v[16:19]
	v_mfma_f32_16x16x32_bf16 v[4:7], v[148:151], v[218:221], v[4:7]
	v_mfma_f32_16x16x32_bf16 v[0:3], v[176:179], v[218:221], v[0:3]
	s_barrier
	s_add_i32 s72, s72, 2
	s_add_u32 s40, s40, 0x100
	s_addc_u32 s41, s41, 0
	s_add_u32 s70, s70, 0x100
	s_addc_u32 s71, s71, 0
	s_cmp_gt_u32 s72, 13
	s_cbranch_scc0 .LBB0_1026
	s_and_b64 vcc, exec, s[24:25]
	s_cbranch_vccz .LBB0_1029
	s_barrier

.LBB0_1051:
	s_cmp_gt_i32 s79, 9
	s_cselect_b64 s[4:5], -1, 0
	s_and_b64 s[0:1], s[0:1], s[4:5]
	s_andn2_b64 vcc, exec, s[0:1]
	s_cbranch_vccnz .LBB0_1105
	s_waitcnt vmcnt(0) lgkmcnt(0)
	s_barrier
	v_readlane_b32 s21, v242, 63
	s_add_u32 s21, s21, 1
	v_readlane_b32 s12, v242, 1
	v_readlane_b32 s13, v242, 2
	s_mov_b64 s[14:15], exec
	s_and_b64 s[12:13], s[14:15], s[12:13]
	s_mov_b64 exec, s[12:13]
	s_cbranch_execz .Lxb_done_6
	v_mov_b32_e32 v0, 0x21020
	ds_read2_b32 v[2:3], v0 offset1:1
	s_lshl_b32 s16, s84, 8
	s_add_u32 s16, s76, s16
	s_addc_u32 s17, s77, 0
	v_mov_b32_e32 v1, 0x1000
	v_mov_b32_e32 v4, 1
	global_atomic_add v5, v1, v4, s[16:17] offset:1024 sc0
	buffer_inv sc1
	s_waitcnt vmcnt(0) lgkmcnt(0)
	v_readfirstlane_b32 s18, v5
	v_readfirstlane_b32 s19, v2
	v_readfirstlane_b32 s20, v3
	v_mov_b32_e32 v1, 0x3000
	s_mul_i32 s22, s19, s21
	s_mul_i32 s23, s20, s21
	s_add_u32 s18, s18, 1
	s_cmp_lg_u32 s18, s22
	s_cbranch_scc1 .Lxb_spin_6
	buffer_wbl2 sc1
	s_waitcnt vmcnt(0)
	global_atomic_add v1, v4, s[76:77] offset:1024

.LBB0_1115:
	ds_read_b128 v[144:147], v155
	ds_read_b128 v[160:163], v155 offset:1024
	ds_read_b128 v[164:167], v155 offset:2048
	ds_read_b128 v[168:171], v155 offset:3072
	ds_read_b128 v[172:175], v157
	ds_read_b128 v[176:179], v157 offset:1024
	ds_read_b128 v[180:183], v157 offset:2048
	ds_read_b128 v[186:189], v157 offset:3072
	s_add_u32 s40, s38, 0xfffc0080
	s_addc_u32 s41, s39, -1
	s_cmp_eq_u32 s70, 12
	s_cselect_b32 s43, s27, s41
	s_cselect_b32 s42, s64, s40
	s_cselect_b32 s41, s29, s67
	s_cselect_b32 s40, s65, s66
	s_add_i32 m0, s16, 0xc000
	ds_read_b128 v[190:193], v158
	ds_read_b128 v[194:197], v158 offset:1024
	ds_read_b128 v[198:201], v158 offset:2048
	ds_read_b128 v[202:205], v158 offset:3072
	ds_read_b128 v[206:209], v158 offset:4096
	ds_read_b128 v[210:213], v158 offset:5120
	ds_read_b128 v[214:217], v158 offset:6144
	ds_read_b128 v[218:221], v158 offset:7168
	global_load_lds_dwordx4 v136, s[38:39]
	s_add_i32 m0, s16, 0xe000
	s_nop 0
	global_load_lds_dwordx4 v138, s[38:39]
	s_waitcnt vmcnt(8)
	s_waitcnt lgkmcnt(0)
	s_barrier
	s_waitcnt lgkmcnt(0)
	v_mfma_f32_16x16x32_bf16 v[124:127], v[144:147], v[190:193], v[124:127]
	v_mfma_f32_16x16x32_bf16 v[120:123], v[164:167], v[190:193], v[120:123]
	v_mfma_f32_16x16x32_bf16 v[116:119], v[144:147], v[198:201], v[116:119]
	v_mfma_f32_16x16x32_bf16 v[104:107], v[164:167], v[198:201], v[104:107]
	v_mfma_f32_16x16x32_bf16 v[92:95], v[144:147], v[206:209], v[92:95]
	v_mfma_f32_16x16x32_bf16 v[88:91], v[164:167], v[206:209], v[88:91]
	v_mfma_f32_16x16x32_bf16 v[76:79], v[144:147], v[214:217], v[76:79]
	v_mfma_f32_16x16x32_bf16 v[72:75], v[164:167], v[214:217], v[72:75]
	v_mfma_f32_16x16x32_bf16 v[124:127], v[160:163], v[194:197], v[124:127]
	v_mfma_f32_16x16x32_bf16 v[120:123], v[168:171], v[194:197], v[120:123]
	v_mfma_f32_16x16x32_bf16 v[116:119], v[160:163], v[202:205], v[116:119]
	v_mfma_f32_16x16x32_bf16 v[104:107], v[168:171], v[202:205], v[104:107]
	v_mfma_f32_16x16x32_bf16 v[92:95], v[160:163], v[210:213], v[92:95]
	v_mfma_f32_16x16x32_bf16 v[88:91], v[168:171], v[210:213], v[88:91]
	v_mfma_f32_16x16x32_bf16 v[76:79], v[160:163], v[218:221], v[76:79]
	v_mfma_f32_16x16x32_bf16 v[72:75], v[168:171], v[218:221], v[72:75]
	v_mfma_f32_16x16x32_bf16 v[112:115], v[172:175], v[190:193], v[112:115]
	v_mfma_f32_16x16x32_bf16 v[108:111], v[180:183], v[190:193], v[108:111]
	v_mfma_f32_16x16x32_bf16 v[100:103], v[172:175], v[198:201], v[100:103]
	v_mfma_f32_16x16x32_bf16 v[96:99], v[180:183], v[198:201], v[96:99]
	v_mfma_f32_16x16x32_bf16 v[84:87], v[172:175], v[206:209], v[84:87]
	v_mfma_f32_16x16x32_bf16 v[80:83], v[180:183], v[206:209], v[80:83]
	v_mfma_f32_16x16x32_bf16 v[68:71], v[172:175], v[214:217], v[68:71]
	v_mfma_f32_16x16x32_bf16 v[64:67], v[180:183], v[214:217], v[64:67]
	v_mfma_f32_16x16x32_bf16 v[112:115], v[176:179], v[194:197], v[112:115]
	v_mfma_f32_16x16x32_bf16 v[108:111], v[186:189], v[194:197], v[108:111]
	v_mfma_f32_16x16x32_bf16 v[100:103], v[176:179], v[202:205], v[100:103]
	v_mfma_f32_16x16x32_bf16 v[96:99], v[186:189], v[202:205], v[96:99]
	v_mfma_f32_16x16x32_bf16 v[84:87], v[176:179], v[210:213], v[84:87]
	v_mfma_f32_16x16x32_bf16 v[80:83], v[186:189], v[210:213], v[80:83]
	v_mfma_f32_16x16x32_bf16 v[68:71], v[176:179], v[218:221], v[68:71]
	v_mfma_f32_16x16x32_bf16 v[64:67], v[186:189], v[218:221], v[64:67]
	s_barrier
	s_add_i32 s71, s60, s3
	s_mov_b32 m0, s71
	ds_read_b128 v[190:193], v158 offset:16384
	ds_read_b128 v[194:197], v158 offset:17408
	ds_read_b128 v[198:201], v158 offset:18432
	ds_read_b128 v[202:205], v158 offset:19456
	ds_read_b128 v[206:209], v158 offset:20480
	ds_read_b128 v[210:213], v158 offset:21504
	ds_read_b128 v[214:217], v158 offset:22528
	ds_read_b128 v[218:221], v158 offset:23552
	global_load_lds_dwordx4 v132, s[40:41]
	s_add_i32 m0, s71, 0x2000
	s_add_u32 s72, s40, 0x40000
	s_addc_u32 s73, s41, 0
	s_add_i32 s71, s61, s3
	global_load_lds_dwordx4 v128, s[40:41]
	s_mov_b32 m0, s71
	global_load_lds_dwordx4 v132, s[72:73]
	s_add_i32 m0, s71, 0x2000
	s_nop 0
	global_load_lds_dwordx4 v128, s[72:73]
	s_mov_b32 m0, s16
	s_nop 0
	global_load_lds_dwordx4 v134, s[42:43]
	s_mov_b32 m0, s17
	s_nop 0
	global_load_lds_dwordx4 v130, s[42:43]
	s_add_u32 s98, s40, s12
	s_addc_u32 s99, s41, s13
	s_add_u32 s100, s42, s12
	s_addc_u32 s101, s43, s13
	s_waitcnt vmcnt(8)
	s_waitcnt lgkmcnt(0)
	s_barrier
	s_waitcnt lgkmcnt(0)
	v_mfma_f32_16x16x32_bf16 v[60:63], v[144:147], v[190:193], v[60:63]
	v_mfma_f32_16x16x32_bf16 v[56:59], v[164:167], v[190:193], v[56:59]
	v_mfma_f32_16x16x32_bf16 v[44:47], v[144:147], v[198:201], v[44:47]
	v_mfma_f32_16x16x32_bf16 v[40:43], v[164:167], v[198:201], v[40:43]
	v_mfma_f32_16x16x32_bf16 v[28:31], v[144:147], v[206:209], v[28:31]
	v_mfma_f32_16x16x32_bf16 v[24:27], v[164:167], v[206:209], v[24:27]
	v_mfma_f32_16x16x32_bf16 v[12:15], v[144:147], v[214:217], v[12:15]
	v_mfma_f32_16x16x32_bf16 v[8:11], v[164:167], v[214:217], v[8:11]
	v_mfma_f32_16x16x32_bf16 v[60:63], v[160:163], v[194:197], v[60:63]
	v_mfma_f32_16x16x32_bf16 v[56:59], v[168:171], v[194:197], v[56:59]
	v_mfma_f32_16x16x32_bf16 v[44:47], v[160:163], v[202:205], v[44:47]
	v_mfma_f32_16x16x32_bf16 v[40:43], v[168:171], v[202:205], v[40:43]
	v_mfma_f32_16x16x32_bf16 v[28:31], v[160:163], v[210:213], v[28:31]
	v_mfma_f32_16x16x32_bf16 v[24:27], v[168:171], v[210:213], v[24:27]
	v_mfma_f32_16x16x32_bf16 v[12:15], v[160:163], v[218:221], v[12:15]
	v_mfma_f32_16x16x32_bf16 v[8:11], v[168:171], v[218:221], v[8:11]
	v_mfma_f32_16x16x32_bf16 v[52:55], v[172:175], v[190:193], v[52:55]
	v_mfma_f32_16x16x32_bf16 v[48:51], v[180:183], v[190:193], v[48:51]
	v_mfma_f32_16x16x32_bf16 v[36:39], v[172:175], v[198:201], v[36:39]
	v_mfma_f32_16x16x32_bf16 v[32:35], v[180:183], v[198:201], v[32:35]
	v_mfma_f32_16x16x32_bf16 v[20:23], v[172:175], v[206:209], v[20:23]
	v_mfma_f32_16x16x32_bf16 v[16:19], v[180:183], v[206:209], v[16:19]
	v_mfma_f32_16x16x32_bf16 v[4:7], v[172:175], v[214:217], v[4:7]
	v_mfma_f32_16x16x32_bf16 v[0:3], v[180:183], v[214:217], v[0:3]
	v_mfma_f32_16x16x32_bf16 v[52:55], v[176:179], v[194:197], v[52:55]
	v_mfma_f32_16x16x32_bf16 v[48:51], v[186:189], v[194:197], v[48:51]
	v_mfma_f32_16x16x32_bf16 v[36:39], v[176:179], v[202:205], v[36:39]
	v_mfma_f32_16x16x32_bf16 v[32:35], v[186:189], v[202:205], v[32:35]
	v_mfma_f32_16x16x32_bf16 v[20:23], v[176:179], v[210:213], v[20:23]
	v_mfma_f32_16x16x32_bf16 v[16:19], v[186:189], v[210:213], v[16:19]
	v_mfma_f32_16x16x32_bf16 v[4:7], v[176:179], v[218:221], v[4:7]
	v_mfma_f32_16x16x32_bf16 v[0:3], v[186:189], v[218:221], v[0:3]
	s_barrier
	s_add_i32 s71, 0, 0x18000
	v_add_u32_e32 v148, s71, v151
	s_add_i32 s72, 0, 0x1c000
	ds_read_b128 v[144:147], v148
	ds_read_b128 v[160:163], v148 offset:1024
	ds_read_b128 v[164:167], v148 offset:2048
	ds_read_b128 v[168:171], v148 offset:3072
	v_add_u32_e32 v148, s72, v151
	ds_read_b128 v[172:175], v148
	ds_read_b128 v[176:179], v148 offset:1024
	ds_read_b128 v[180:183], v148 offset:2048
	ds_read_b128 v[186:189], v148 offset:3072
	s_add_u32 s42, s42, 0x40000
	s_addc_u32 s43, s43, 0
	s_mov_b32 m0, s18
	ds_read_b128 v[190:193], v158 offset:32768
	ds_read_b128 v[194:197], v158 offset:33792
	ds_read_b128 v[198:201], v158 offset:34816
	ds_read_b128 v[202:205], v158 offset:35840
	ds_read_b128 v[206:209], v158 offset:36864
	ds_read_b128 v[210:213], v158 offset:37888
	ds_read_b128 v[214:217], v158 offset:38912
	ds_read_b128 v[218:221], v158 offset:39936
	global_load_lds_dwordx4 v134, s[42:43]
	s_mov_b32 m0, s19
	s_nop 0
	global_load_lds_dwordx4 v130, s[42:43]
	s_waitcnt vmcnt(8)
	s_waitcnt lgkmcnt(0)
	s_barrier
	s_waitcnt lgkmcnt(0)
	v_mfma_f32_16x16x32_bf16 v[124:127], v[144:147], v[190:193], v[124:127]
	v_mfma_f32_16x16x32_bf16 v[120:123], v[164:167], v[190:193], v[120:123]
	v_mfma_f32_16x16x32_bf16 v[116:119], v[144:147], v[198:201], v[116:119]
	v_mfma_f32_16x16x32_bf16 v[104:107], v[164:167], v[198:201], v[104:107]
	v_mfma_f32_16x16x32_bf16 v[92:95], v[144:147], v[206:209], v[92:95]
	v_mfma_f32_16x16x32_bf16 v[88:91], v[164:167], v[206:209], v[88:91]
	v_mfma_f32_16x16x32_bf16 v[76:79], v[144:147], v[214:217], v[76:79]
	v_mfma_f32_16x16x32_bf16 v[72:75], v[164:167], v[214:217], v[72:75]
	v_mfma_f32_16x16x32_bf16 v[124:127], v[160:163], v[194:197], v[124:127]
	v_mfma_f32_16x16x32_bf16 v[120:123], v[168:171], v[194:197], v[120:123]
	v_mfma_f32_16x16x32_bf16 v[116:119], v[160:163], v[202:205], v[116:119]
	v_mfma_f32_16x16x32_bf16 v[104:107], v[168:171], v[202:205], v[104:107]
	v_mfma_f32_16x16x32_bf16 v[92:95], v[160:163], v[210:213], v[92:95]
	v_mfma_f32_16x16x32_bf16 v[88:91], v[168:171], v[210:213], v[88:91]
	v_mfma_f32_16x16x32_bf16 v[76:79], v[160:163], v[218:221], v[76:79]
	v_mfma_f32_16x16x32_bf16 v[72:75], v[168:171], v[218:221], v[72:75]
	v_mfma_f32_16x16x32_bf16 v[112:115], v[172:175], v[190:193], v[112:115]
	v_mfma_f32_16x16x32_bf16 v[108:111], v[180:183], v[190:193], v[108:111]
	v_mfma_f32_16x16x32_bf16 v[100:103], v[172:175], v[198:201], v[100:103]
	v_mfma_f32_16x16x32_bf16 v[96:99], v[180:183], v[198:201], v[96:99]
	v_mfma_f32_16x16x32_bf16 v[84:87], v[172:175], v[206:209], v[84:87]
	v_mfma_f32_16x16x32_bf16 v[80:83], v[180:183], v[206:209], v[80:83]
	v_mfma_f32_16x16x32_bf16 v[68:71], v[172:175], v[214:217], v[68:71]
	v_mfma_f32_16x16x32_bf16 v[64:67], v[180:183], v[214:217], v[64:67]
	v_mfma_f32_16x16x32_bf16 v[112:115], v[176:179], v[194:197], v[112:115]
	v_mfma_f32_16x16x32_bf16 v[108:111], v[186:189], v[194:197], v[108:111]
	v_mfma_f32_16x16x32_bf16 v[100:103], v[176:179], v[202:205], v[100:103]
	v_mfma_f32_16x16x32_bf16 v[96:99], v[186:189], v[202:205], v[96:99]
	v_mfma_f32_16x16x32_bf16 v[84:87], v[176:179], v[210:213], v[84:87]
	v_mfma_f32_16x16x32_bf16 v[80:83], v[186:189], v[210:213], v[80:83]
	v_mfma_f32_16x16x32_bf16 v[68:71], v[176:179], v[218:221], v[68:71]
	v_mfma_f32_16x16x32_bf16 v[64:67], v[186:189], v[218:221], v[64:67]
	s_barrier
	s_add_i32 s42, s71, s3
	s_mov_b32 m0, s42
	ds_read_b128 v[190:193], v158 offset:49152
	ds_read_b128 v[194:197], v158 offset:50176
	ds_read_b128 v[198:201], v158 offset:51200
	ds_read_b128 v[202:205], v158 offset:52224
	ds_read_b128 v[206:209], v158 offset:53248
	ds_read_b128 v[210:213], v158 offset:54272
	ds_read_b128 v[214:217], v158 offset:55296
	ds_read_b128 v[218:221], v158 offset:56320
	global_load_lds_dwordx4 v132, s[98:99]
	s_add_i32 m0, s42, 0x2000
	s_add_u32 s40, s40, 0x40080
	s_addc_u32 s41, s41, 0
	s_add_i32 s42, s72, s3
	global_load_lds_dwordx4 v128, s[98:99]
	s_mov_b32 m0, s42
	s_nop 0
	global_load_lds_dwordx4 v132, s[40:41]
	s_add_i32 m0, s42, 0x2000
	s_nop 0
	global_load_lds_dwordx4 v128, s[40:41]
	s_mov_b32 m0, s21
	s_nop 0
	global_load_lds_dwordx4 v134, s[100:101]
	s_mov_b32 m0, s22
	s_nop 0
	global_load_lds_dwordx4 v130, s[100:101]
	s_waitcnt vmcnt(8)
	s_waitcnt lgkmcnt(0)
	s_barrier
	s_waitcnt lgkmcnt(0)
	v_mfma_f32_16x16x32_bf16 v[60:63], v[144:147], v[190:193], v[60:63]
	v_mfma_f32_16x16x32_bf16 v[56:59], v[164:167], v[190:193], v[56:59]
	v_mfma_f32_16x16x32_bf16 v[44:47], v[144:147], v[198:201], v[44:47]
	v_mfma_f32_16x16x32_bf16 v[40:43], v[164:167], v[198:201], v[40:43]
	v_mfma_f32_16x16x32_bf16 v[28:31], v[144:147], v[206:209], v[28:31]
	v_mfma_f32_16x16x32_bf16 v[24:27], v[164:167], v[206:209], v[24:27]
	v_mfma_f32_16x16x32_bf16 v[12:15], v[144:147], v[214:217], v[12:15]
	v_mfma_f32_16x16x32_bf16 v[8:11], v[164:167], v[214:217], v[8:11]
	v_mfma_f32_16x16x32_bf16 v[60:63], v[160:163], v[194:197], v[60:63]
	v_mfma_f32_16x16x32_bf16 v[56:59], v[168:171], v[194:197], v[56:59]
	v_mfma_f32_16x16x32_bf16 v[44:47], v[160:163], v[202:205], v[44:47]
	v_mfma_f32_16x16x32_bf16 v[40:43], v[168:171], v[202:205], v[40:43]
	v_mfma_f32_16x16x32_bf16 v[28:31], v[160:163], v[210:213], v[28:31]
	v_mfma_f32_16x16x32_bf16 v[24:27], v[168:171], v[210:213], v[24:27]
	v_mfma_f32_16x16x32_bf16 v[12:15], v[160:163], v[218:221], v[12:15]
	v_mfma_f32_16x16x32_bf16 v[8:11], v[168:171], v[218:221], v[8:11]
	v_mfma_f32_16x16x32_bf16 v[52:55], v[172:175], v[190:193], v[52:55]
	v_mfma_f32_16x16x32_bf16 v[48:51], v[180:183], v[190:193], v[48:51]
	v_mfma_f32_16x16x32_bf16 v[36:39], v[172:175], v[198:201], v[36:39]
	v_mfma_f32_16x16x32_bf16 v[32:35], v[180:183], v[198:201], v[32:35]
	v_mfma_f32_16x16x32_bf16 v[20:23], v[172:175], v[206:209], v[20:23]
	v_mfma_f32_16x16x32_bf16 v[16:19], v[180:183], v[206:209], v[16:19]
	v_mfma_f32_16x16x32_bf16 v[4:7], v[172:175], v[214:217], v[4:7]
	v_mfma_f32_16x16x32_bf16 v[0:3], v[180:183], v[214:217], v[0:3]
	v_mfma_f32_16x16x32_bf16 v[52:55], v[176:179], v[194:197], v[52:55]
	v_mfma_f32_16x16x32_bf16 v[48:51], v[186:189], v[194:197], v[48:51]
	v_mfma_f32_16x16x32_bf16 v[36:39], v[176:179], v[202:205], v[36:39]
	v_mfma_f32_16x16x32_bf16 v[32:35], v[186:189], v[202:205], v[32:35]
	v_mfma_f32_16x16x32_bf16 v[20:23], v[176:179], v[210:213], v[20:23]
	v_mfma_f32_16x16x32_bf16 v[16:19], v[186:189], v[210:213], v[16:19]
	v_mfma_f32_16x16x32_bf16 v[4:7], v[176:179], v[218:221], v[4:7]
	v_mfma_f32_16x16x32_bf16 v[0:3], v[186:189], v[218:221], v[0:3]
	s_barrier
	s_add_i32 s70, s70, 2
	s_add_u32 s38, s38, 0x100
	s_addc_u32 s39, s39, 0
	s_add_u32 s66, s66, 0x100
	s_addc_u32 s67, s67, 0
	s_cmp_gt_u32 s70, 13
	s_cbranch_scc0 .LBB0_1115
	s_and_b64 vcc, exec, s[24:25]
	s_cbranch_vccz .LBB0_1118
	s_barrier

.LBB0_1246:
	s_cmp_gt_i32 s79, 10
	s_cselect_b64 s[4:5], -1, 0
	s_and_b64 s[0:1], s[0:1], s[4:5]
	s_andn2_b64 vcc, exec, s[0:1]
	s_cbranch_vccnz .LBB0_1300
	s_waitcnt vmcnt(0) lgkmcnt(0)
	s_barrier
	v_readlane_b32 s21, v242, 63
	s_add_u32 s21, s21, 1
	v_readlane_b32 s12, v242, 1
	v_readlane_b32 s13, v242, 2
	s_mov_b64 s[14:15], exec
	s_and_b64 s[12:13], s[14:15], s[12:13]
	s_mov_b64 exec, s[12:13]
	s_cbranch_execz .Lxb_done_7
	v_mov_b32_e32 v0, 0x21020
	ds_read2_b32 v[2:3], v0 offset1:1
	s_lshl_b32 s16, s84, 8
	s_add_u32 s16, s76, s16
	s_addc_u32 s17, s77, 0
	v_mov_b32_e32 v1, 0x1000
	v_mov_b32_e32 v4, 1
	global_atomic_add v5, v1, v4, s[16:17] offset:1024 sc0
	buffer_inv sc1
	s_waitcnt vmcnt(0) lgkmcnt(0)
	v_readfirstlane_b32 s18, v5
	v_readfirstlane_b32 s19, v2
	v_readfirstlane_b32 s20, v3
	v_mov_b32_e32 v1, 0x3000
	s_mul_i32 s22, s19, s21
	s_mul_i32 s23, s20, s21
	s_add_u32 s18, s18, 1
	s_cmp_lg_u32 s18, s22
	s_cbranch_scc1 .Lxb_spin_7
	buffer_wbl2 sc1
	s_waitcnt vmcnt(0)
	global_atomic_add v1, v4, s[76:77] offset:1024

.LBB0_1324:
	ds_read_b128 v[128:131], v189
	ds_read_b128 v[132:135], v189 offset:1024
	ds_read_b128 v[136:139], v189 offset:2048
	ds_read_b128 v[140:143], v189 offset:3072
	ds_read_b128 v[144:147], v190
	ds_read_b128 v[148:151], v190 offset:1024
	ds_read_b128 v[172:175], v190 offset:2048
	ds_read_b128 v[176:179], v190 offset:3072
	s_add_u32 s36, s34, 0xfff50080
	s_addc_u32 s37, s35, -1
	s_cmp_eq_u32 s64, 40
	s_cselect_b32 s39, s1, s37
	s_cselect_b32 s38, s0, s36
	s_cselect_b32 s37, s29, s63
	s_cselect_b32 s36, s28, s31
	s_add_i32 m0, s16, 0xc000
	ds_read_b128 v[180:183], v191
	ds_read_b128 v[194:197], v191 offset:1024
	ds_read_b128 v[198:201], v191 offset:2048
	ds_read_b128 v[202:205], v191 offset:3072
	ds_read_b128 v[206:209], v191 offset:4096
	ds_read_b128 v[210:213], v191 offset:5120
	ds_read_b128 v[214:217], v191 offset:6144
	ds_read_b128 v[218:221], v191 offset:7168
	global_load_lds_dwordx4 v164, s[34:35]
	s_add_i32 m0, s16, 0xe000
	s_nop 0
	global_load_lds_dwordx4 v166, s[34:35]
	s_waitcnt vmcnt(8)
	s_waitcnt lgkmcnt(0)
	s_barrier
	s_waitcnt lgkmcnt(0)
	v_mfma_f32_16x16x32_bf16 v[124:127], v[128:131], v[180:183], v[124:127]
	v_mfma_f32_16x16x32_bf16 v[120:123], v[136:139], v[180:183], v[120:123]
	v_mfma_f32_16x16x32_bf16 v[108:111], v[128:131], v[198:201], v[108:111]
	v_mfma_f32_16x16x32_bf16 v[104:107], v[136:139], v[198:201], v[104:107]
	v_mfma_f32_16x16x32_bf16 v[92:95], v[128:131], v[206:209], v[92:95]
	v_mfma_f32_16x16x32_bf16 v[88:91], v[136:139], v[206:209], v[88:91]
	v_mfma_f32_16x16x32_bf16 v[76:79], v[128:131], v[214:217], v[76:79]
	v_mfma_f32_16x16x32_bf16 v[72:75], v[136:139], v[214:217], v[72:75]
	v_mfma_f32_16x16x32_bf16 v[124:127], v[132:135], v[194:197], v[124:127]
	v_mfma_f32_16x16x32_bf16 v[120:123], v[140:143], v[194:197], v[120:123]
	v_mfma_f32_16x16x32_bf16 v[108:111], v[132:135], v[202:205], v[108:111]
	v_mfma_f32_16x16x32_bf16 v[104:107], v[140:143], v[202:205], v[104:107]
	v_mfma_f32_16x16x32_bf16 v[92:95], v[132:135], v[210:213], v[92:95]
	v_mfma_f32_16x16x32_bf16 v[88:91], v[140:143], v[210:213], v[88:91]
	v_mfma_f32_16x16x32_bf16 v[76:79], v[132:135], v[218:221], v[76:79]
	v_mfma_f32_16x16x32_bf16 v[72:75], v[140:143], v[218:221], v[72:75]
	v_mfma_f32_16x16x32_bf16 v[116:119], v[144:147], v[180:183], v[116:119]
	v_mfma_f32_16x16x32_bf16 v[112:115], v[172:175], v[180:183], v[112:115]
	v_mfma_f32_16x16x32_bf16 v[100:103], v[144:147], v[198:201], v[100:103]
	v_mfma_f32_16x16x32_bf16 v[96:99], v[172:175], v[198:201], v[96:99]
	v_mfma_f32_16x16x32_bf16 v[84:87], v[144:147], v[206:209], v[84:87]
	v_mfma_f32_16x16x32_bf16 v[80:83], v[172:175], v[206:209], v[80:83]
	v_mfma_f32_16x16x32_bf16 v[68:71], v[144:147], v[214:217], v[68:71]
	v_mfma_f32_16x16x32_bf16 v[64:67], v[172:175], v[214:217], v[64:67]
	v_mfma_f32_16x16x32_bf16 v[116:119], v[148:151], v[194:197], v[116:119]
	v_mfma_f32_16x16x32_bf16 v[112:115], v[176:179], v[194:197], v[112:115]
	v_mfma_f32_16x16x32_bf16 v[100:103], v[148:151], v[202:205], v[100:103]
	v_mfma_f32_16x16x32_bf16 v[96:99], v[176:179], v[202:205], v[96:99]
	v_mfma_f32_16x16x32_bf16 v[84:87], v[148:151], v[210:213], v[84:87]
	v_mfma_f32_16x16x32_bf16 v[80:83], v[176:179], v[210:213], v[80:83]
	v_mfma_f32_16x16x32_bf16 v[68:71], v[148:151], v[218:221], v[68:71]
	v_mfma_f32_16x16x32_bf16 v[64:67], v[176:179], v[218:221], v[64:67]
	s_barrier
	s_add_i32 s65, s42, s15
	s_mov_b32 m0, s65
	ds_read_b128 v[180:183], v191 offset:16384
	ds_read_b128 v[194:197], v191 offset:17408
	ds_read_b128 v[198:201], v191 offset:18432
	ds_read_b128 v[202:205], v191 offset:19456
	ds_read_b128 v[206:209], v191 offset:20480
	ds_read_b128 v[210:213], v191 offset:21504
	ds_read_b128 v[214:217], v191 offset:22528
	ds_read_b128 v[218:221], v191 offset:23552
	global_load_lds_dwordx4 v154, s[36:37]
	s_add_i32 m0, s65, 0x2000
	s_add_u32 s66, s36, 0xb0000
	s_addc_u32 s67, s37, 0
	s_add_i32 s65, s43, s15
	global_load_lds_dwordx4 v158, s[36:37]
	s_mov_b32 m0, s65
	global_load_lds_dwordx4 v154, s[66:67]
	s_add_i32 m0, s65, 0x2000
	s_nop 0
	global_load_lds_dwordx4 v158, s[66:67]
	s_mov_b32 m0, s16
	s_nop 0
	global_load_lds_dwordx4 v152, s[38:39]
	s_mov_b32 m0, s17
	s_nop 0
	global_load_lds_dwordx4 v156, s[38:39]
	s_add_u32 s98, s36, s24
	s_addc_u32 s99, s37, s25
	s_add_u32 s100, s38, s24
	s_addc_u32 s101, s39, s25
	s_waitcnt vmcnt(8)
	s_waitcnt lgkmcnt(0)
	s_barrier
	s_waitcnt lgkmcnt(0)
	v_mfma_f32_16x16x32_bf16 v[60:63], v[128:131], v[180:183], v[60:63]
	v_mfma_f32_16x16x32_bf16 v[56:59], v[136:139], v[180:183], v[56:59]
	v_mfma_f32_16x16x32_bf16 v[44:47], v[128:131], v[198:201], v[44:47]
	v_mfma_f32_16x16x32_bf16 v[40:43], v[136:139], v[198:201], v[40:43]
	v_mfma_f32_16x16x32_bf16 v[28:31], v[128:131], v[206:209], v[28:31]
	v_mfma_f32_16x16x32_bf16 v[24:27], v[136:139], v[206:209], v[24:27]
	v_mfma_f32_16x16x32_bf16 v[12:15], v[128:131], v[214:217], v[12:15]
	v_mfma_f32_16x16x32_bf16 v[8:11], v[136:139], v[214:217], v[8:11]
	v_mfma_f32_16x16x32_bf16 v[60:63], v[132:135], v[194:197], v[60:63]
	v_mfma_f32_16x16x32_bf16 v[56:59], v[140:143], v[194:197], v[56:59]
	v_mfma_f32_16x16x32_bf16 v[44:47], v[132:135], v[202:205], v[44:47]
	v_mfma_f32_16x16x32_bf16 v[40:43], v[140:143], v[202:205], v[40:43]
	v_mfma_f32_16x16x32_bf16 v[28:31], v[132:135], v[210:213], v[28:31]
	v_mfma_f32_16x16x32_bf16 v[24:27], v[140:143], v[210:213], v[24:27]
	v_mfma_f32_16x16x32_bf16 v[12:15], v[132:135], v[218:221], v[12:15]
	v_mfma_f32_16x16x32_bf16 v[8:11], v[140:143], v[218:221], v[8:11]
	v_mfma_f32_16x16x32_bf16 v[52:55], v[144:147], v[180:183], v[52:55]
	v_mfma_f32_16x16x32_bf16 v[48:51], v[172:175], v[180:183], v[48:51]
	v_mfma_f32_16x16x32_bf16 v[36:39], v[144:147], v[198:201], v[36:39]
	v_mfma_f32_16x16x32_bf16 v[32:35], v[172:175], v[198:201], v[32:35]
	v_mfma_f32_16x16x32_bf16 v[20:23], v[144:147], v[206:209], v[20:23]
	v_mfma_f32_16x16x32_bf16 v[16:19], v[172:175], v[206:209], v[16:19]
	v_mfma_f32_16x16x32_bf16 v[4:7], v[144:147], v[214:217], v[4:7]
	v_mfma_f32_16x16x32_bf16 v[0:3], v[172:175], v[214:217], v[0:3]
	v_mfma_f32_16x16x32_bf16 v[52:55], v[148:151], v[194:197], v[52:55]
	v_mfma_f32_16x16x32_bf16 v[48:51], v[176:179], v[194:197], v[48:51]
	v_mfma_f32_16x16x32_bf16 v[36:39], v[148:151], v[202:205], v[36:39]
	v_mfma_f32_16x16x32_bf16 v[32:35], v[176:179], v[202:205], v[32:35]
	v_mfma_f32_16x16x32_bf16 v[20:23], v[148:151], v[210:213], v[20:23]
	v_mfma_f32_16x16x32_bf16 v[16:19], v[176:179], v[210:213], v[16:19]
	v_mfma_f32_16x16x32_bf16 v[4:7], v[148:151], v[218:221], v[4:7]
	v_mfma_f32_16x16x32_bf16 v[0:3], v[176:179], v[218:221], v[0:3]
	s_barrier
	s_add_i32 s65, 0, 0x18000
	s_add_i32 s66, 0, 0x1c000
	v_add_u32_e32 v140, s65, v186
	v_add_u32_e32 v176, s66, v186
	ds_read_b128 v[128:131], v140
	ds_read_b128 v[132:135], v140 offset:1024
	ds_read_b128 v[136:139], v140 offset:2048
	ds_read_b128 v[140:143], v140 offset:3072
	ds_read_b128 v[144:147], v176
	ds_read_b128 v[148:151], v176 offset:1024
	ds_read_b128 v[172:175], v176 offset:2048
	ds_read_b128 v[176:179], v176 offset:3072
	s_add_u32 s38, s38, 0xb0000
	s_addc_u32 s39, s39, 0
	s_mov_b32 m0, s18
	ds_read_b128 v[180:183], v191 offset:32768
	ds_read_b128 v[194:197], v191 offset:33792
	ds_read_b128 v[198:201], v191 offset:34816
	ds_read_b128 v[202:205], v191 offset:35840
	ds_read_b128 v[206:209], v191 offset:36864
	ds_read_b128 v[210:213], v191 offset:37888
	ds_read_b128 v[214:217], v191 offset:38912
	ds_read_b128 v[218:221], v191 offset:39936
	global_load_lds_dwordx4 v152, s[38:39]
	s_mov_b32 m0, s19
	s_nop 0
	global_load_lds_dwordx4 v156, s[38:39]
	s_waitcnt vmcnt(8)
	s_waitcnt lgkmcnt(0)
	s_barrier
	s_waitcnt lgkmcnt(0)
	v_mfma_f32_16x16x32_bf16 v[124:127], v[128:131], v[180:183], v[124:127]
	v_mfma_f32_16x16x32_bf16 v[120:123], v[136:139], v[180:183], v[120:123]
	v_mfma_f32_16x16x32_bf16 v[108:111], v[128:131], v[198:201], v[108:111]
	v_mfma_f32_16x16x32_bf16 v[104:107], v[136:139], v[198:201], v[104:107]
	v_mfma_f32_16x16x32_bf16 v[92:95], v[128:131], v[206:209], v[92:95]
	v_mfma_f32_16x16x32_bf16 v[88:91], v[136:139], v[206:209], v[88:91]
	v_mfma_f32_16x16x32_bf16 v[76:79], v[128:131], v[214:217], v[76:79]
	v_mfma_f32_16x16x32_bf16 v[72:75], v[136:139], v[214:217], v[72:75]
	v_mfma_f32_16x16x32_bf16 v[124:127], v[132:135], v[194:197], v[124:127]
	v_mfma_f32_16x16x32_bf16 v[120:123], v[140:143], v[194:197], v[120:123]
	v_mfma_f32_16x16x32_bf16 v[108:111], v[132:135], v[202:205], v[108:111]
	v_mfma_f32_16x16x32_bf16 v[104:107], v[140:143], v[202:205], v[104:107]
	v_mfma_f32_16x16x32_bf16 v[92:95], v[132:135], v[210:213], v[92:95]
	v_mfma_f32_16x16x32_bf16 v[88:91], v[140:143], v[210:213], v[88:91]
	v_mfma_f32_16x16x32_bf16 v[76:79], v[132:135], v[218:221], v[76:79]
	v_mfma_f32_16x16x32_bf16 v[72:75], v[140:143], v[218:221], v[72:75]
	v_mfma_f32_16x16x32_bf16 v[116:119], v[144:147], v[180:183], v[116:119]
	v_mfma_f32_16x16x32_bf16 v[112:115], v[172:175], v[180:183], v[112:115]
	v_mfma_f32_16x16x32_bf16 v[100:103], v[144:147], v[198:201], v[100:103]
	v_mfma_f32_16x16x32_bf16 v[96:99], v[172:175], v[198:201], v[96:99]
	v_mfma_f32_16x16x32_bf16 v[84:87], v[144:147], v[206:209], v[84:87]
	v_mfma_f32_16x16x32_bf16 v[80:83], v[172:175], v[206:209], v[80:83]
	v_mfma_f32_16x16x32_bf16 v[68:71], v[144:147], v[214:217], v[68:71]
	v_mfma_f32_16x16x32_bf16 v[64:67], v[172:175], v[214:217], v[64:67]
	v_mfma_f32_16x16x32_bf16 v[116:119], v[148:151], v[194:197], v[116:119]
	v_mfma_f32_16x16x32_bf16 v[112:115], v[176:179], v[194:197], v[112:115]
	v_mfma_f32_16x16x32_bf16 v[100:103], v[148:151], v[202:205], v[100:103]
	v_mfma_f32_16x16x32_bf16 v[96:99], v[176:179], v[202:205], v[96:99]
	v_mfma_f32_16x16x32_bf16 v[84:87], v[148:151], v[210:213], v[84:87]
	v_mfma_f32_16x16x32_bf16 v[80:83], v[176:179], v[210:213], v[80:83]
	v_mfma_f32_16x16x32_bf16 v[68:71], v[148:151], v[218:221], v[68:71]
	v_mfma_f32_16x16x32_bf16 v[64:67], v[176:179], v[218:221], v[64:67]
	s_barrier
	s_add_i32 s38, s65, s15
	s_mov_b32 m0, s38
	ds_read_b128 v[180:183], v191 offset:49152
	ds_read_b128 v[194:197], v191 offset:50176
	ds_read_b128 v[198:201], v191 offset:51200
	ds_read_b128 v[202:205], v191 offset:52224
	ds_read_b128 v[206:209], v191 offset:53248
	ds_read_b128 v[210:213], v191 offset:54272
	ds_read_b128 v[214:217], v191 offset:55296
	ds_read_b128 v[218:221], v191 offset:56320
	global_load_lds_dwordx4 v154, s[98:99]
	s_add_i32 m0, s38, 0x2000
	s_add_u32 s36, s36, 0xb0080
	s_addc_u32 s37, s37, 0
	s_add_i32 s38, s66, s15
	global_load_lds_dwordx4 v158, s[98:99]
	s_mov_b32 m0, s38
	s_nop 0
	global_load_lds_dwordx4 v154, s[36:37]
	s_add_i32 m0, s38, 0x2000
	s_nop 0
	global_load_lds_dwordx4 v158, s[36:37]
	s_mov_b32 m0, s21
	s_nop 0
	global_load_lds_dwordx4 v152, s[100:101]
	s_mov_b32 m0, s22
	s_nop 0
	global_load_lds_dwordx4 v156, s[100:101]
	s_waitcnt vmcnt(8)
	s_waitcnt lgkmcnt(0)
	s_barrier
	s_waitcnt lgkmcnt(0)
	v_mfma_f32_16x16x32_bf16 v[60:63], v[128:131], v[180:183], v[60:63]
	v_mfma_f32_16x16x32_bf16 v[56:59], v[136:139], v[180:183], v[56:59]
	v_mfma_f32_16x16x32_bf16 v[44:47], v[128:131], v[198:201], v[44:47]
	v_mfma_f32_16x16x32_bf16 v[40:43], v[136:139], v[198:201], v[40:43]
	v_mfma_f32_16x16x32_bf16 v[28:31], v[128:131], v[206:209], v[28:31]
	v_mfma_f32_16x16x32_bf16 v[24:27], v[136:139], v[206:209], v[24:27]
	v_mfma_f32_16x16x32_bf16 v[12:15], v[128:131], v[214:217], v[12:15]
	v_mfma_f32_16x16x32_bf16 v[8:11], v[136:139], v[214:217], v[8:11]
	v_mfma_f32_16x16x32_bf16 v[60:63], v[132:135], v[194:197], v[60:63]
	v_mfma_f32_16x16x32_bf16 v[56:59], v[140:143], v[194:197], v[56:59]
	v_mfma_f32_16x16x32_bf16 v[44:47], v[132:135], v[202:205], v[44:47]
	v_mfma_f32_16x16x32_bf16 v[40:43], v[140:143], v[202:205], v[40:43]
	v_mfma_f32_16x16x32_bf16 v[28:31], v[132:135], v[210:213], v[28:31]
	v_mfma_f32_16x16x32_bf16 v[24:27], v[140:143], v[210:213], v[24:27]
	v_mfma_f32_16x16x32_bf16 v[12:15], v[132:135], v[218:221], v[12:15]
	v_mfma_f32_16x16x32_bf16 v[8:11], v[140:143], v[218:221], v[8:11]
	v_mfma_f32_16x16x32_bf16 v[52:55], v[144:147], v[180:183], v[52:55]
	v_mfma_f32_16x16x32_bf16 v[48:51], v[172:175], v[180:183], v[48:51]
	v_mfma_f32_16x16x32_bf16 v[36:39], v[144:147], v[198:201], v[36:39]
	v_mfma_f32_16x16x32_bf16 v[32:35], v[172:175], v[198:201], v[32:35]
	v_mfma_f32_16x16x32_bf16 v[20:23], v[144:147], v[206:209], v[20:23]
	v_mfma_f32_16x16x32_bf16 v[16:19], v[172:175], v[206:209], v[16:19]
	v_mfma_f32_16x16x32_bf16 v[4:7], v[144:147], v[214:217], v[4:7]
	v_mfma_f32_16x16x32_bf16 v[0:3], v[172:175], v[214:217], v[0:3]
	v_mfma_f32_16x16x32_bf16 v[52:55], v[148:151], v[194:197], v[52:55]
	v_mfma_f32_16x16x32_bf16 v[48:51], v[176:179], v[194:197], v[48:51]
	v_mfma_f32_16x16x32_bf16 v[36:39], v[148:151], v[202:205], v[36:39]
	v_mfma_f32_16x16x32_bf16 v[32:35], v[176:179], v[202:205], v[32:35]
	v_mfma_f32_16x16x32_bf16 v[20:23], v[148:151], v[210:213], v[20:23]
	v_mfma_f32_16x16x32_bf16 v[16:19], v[176:179], v[210:213], v[16:19]
	v_mfma_f32_16x16x32_bf16 v[4:7], v[148:151], v[218:221], v[4:7]
	v_mfma_f32_16x16x32_bf16 v[0:3], v[176:179], v[218:221], v[0:3]
	s_barrier
	s_add_i32 s64, s64, 2
	s_add_u32 s34, s34, 0x100
	s_addc_u32 s35, s35, 0
	s_add_u32 s31, s31, 0x100
	s_addc_u32 s63, s63, 0
	s_cmp_gt_u32 s64, 41
	s_cbranch_scc0 .LBB0_1324
	s_and_b64 vcc, exec, s[26:27]
	s_cbranch_vccz .LBB0_1327
	s_barrier

.LBB0_1349:
	s_cmp_gt_i32 s79, 11
	s_cselect_b64 s[4:5], -1, 0
	s_and_b64 s[0:1], s[10:11], s[4:5]
	s_andn2_b64 vcc, exec, s[0:1]
	s_cbranch_vccnz .LBB0_1403
	s_waitcnt vmcnt(0) lgkmcnt(0)
	s_barrier
	v_readlane_b32 s21, v242, 63
	s_add_u32 s21, s21, 1
	v_readlane_b32 s12, v242, 1
	v_readlane_b32 s13, v242, 2
	s_mov_b64 s[14:15], exec
	s_and_b64 s[12:13], s[14:15], s[12:13]
	s_mov_b64 exec, s[12:13]
	s_cbranch_execz .Lxb_done_8
	v_mov_b32_e32 v0, 0x21020
	ds_read2_b32 v[2:3], v0 offset1:1
	s_lshl_b32 s16, s84, 8
	s_add_u32 s16, s76, s16
	s_addc_u32 s17, s77, 0
	v_mov_b32_e32 v1, 0x1000
	v_mov_b32_e32 v4, 1
	global_atomic_add v5, v1, v4, s[16:17] offset:1024 sc0
	buffer_inv sc1
	s_waitcnt vmcnt(0) lgkmcnt(0)
	v_readfirstlane_b32 s18, v5
	v_readfirstlane_b32 s19, v2
	v_readfirstlane_b32 s20, v3
	v_mov_b32_e32 v1, 0x3000
	s_mul_i32 s22, s19, s21
	s_mul_i32 s23, s20, s21
	s_add_u32 s18, s18, 1
	s_cmp_lg_u32 s18, s22
	s_cbranch_scc1 .Lxb_spin_8
	buffer_wbl2 sc1
	s_waitcnt vmcnt(0)
	global_atomic_add v1, v4, s[76:77] offset:1024

.LBB0_1413:
	ds_read_b128 v[128:131], v171
	ds_read_b128 v[132:135], v171 offset:1024
	ds_read_b128 v[178:181], v171 offset:2048
	ds_read_b128 v[186:189], v171 offset:3072
	ds_read_b128 v[190:193], v173
	ds_read_b128 v[194:197], v173 offset:1024
	ds_read_b128 v[198:201], v173 offset:2048
	ds_read_b128 v[202:205], v173 offset:3072
	s_add_u32 s21, s38, 0xfffc0080
	s_addc_u32 s22, s39, -1
	s_cmp_eq_u32 s20, 12
	s_cselect_b32 s43, s14, s22
	s_cselect_b32 s42, s15, s21
	s_cselect_b32 s41, s16, s19
	s_cselect_b32 s40, s17, s18
	s_add_i32 m0, s37, 0xc000
	ds_read_b128 v[206:209], v175
	ds_read_b128 v[210:213], v175 offset:1024
	ds_read_b128 v[214:217], v175 offset:2048
	ds_read_b128 v[218:221], v175 offset:3072
	ds_read_b128 v[222:225], v175 offset:4096
	ds_read_b128 v[226:229], v175 offset:5120
	ds_read_b128 v[230:233], v175 offset:6144
	ds_read_b128 v[234:237], v175 offset:7168
	global_load_lds_dwordx4 v152, s[38:39]
	s_add_i32 m0, s37, 0xe000
	s_nop 0
	global_load_lds_dwordx4 v154, s[38:39]
	s_waitcnt vmcnt(8)
	s_waitcnt lgkmcnt(0)
	s_barrier
	s_waitcnt lgkmcnt(0)
	v_mfma_f32_16x16x32_bf16 v[124:127], v[128:131], v[206:209], v[124:127]
	v_mfma_f32_16x16x32_bf16 v[120:123], v[178:181], v[206:209], v[120:123]
	v_mfma_f32_16x16x32_bf16 v[108:111], v[128:131], v[214:217], v[108:111]
	v_mfma_f32_16x16x32_bf16 v[100:103], v[178:181], v[214:217], v[100:103]
	v_mfma_f32_16x16x32_bf16 v[92:95], v[128:131], v[222:225], v[92:95]
	v_mfma_f32_16x16x32_bf16 v[84:87], v[178:181], v[222:225], v[84:87]
	v_mfma_f32_16x16x32_bf16 v[76:79], v[128:131], v[230:233], v[76:79]
	v_mfma_f32_16x16x32_bf16 v[68:71], v[178:181], v[230:233], v[68:71]
	v_mfma_f32_16x16x32_bf16 v[124:127], v[132:135], v[210:213], v[124:127]
	v_mfma_f32_16x16x32_bf16 v[120:123], v[186:189], v[210:213], v[120:123]
	v_mfma_f32_16x16x32_bf16 v[108:111], v[132:135], v[218:221], v[108:111]
	v_mfma_f32_16x16x32_bf16 v[100:103], v[186:189], v[218:221], v[100:103]
	v_mfma_f32_16x16x32_bf16 v[92:95], v[132:135], v[226:229], v[92:95]
	v_mfma_f32_16x16x32_bf16 v[84:87], v[186:189], v[226:229], v[84:87]
	v_mfma_f32_16x16x32_bf16 v[76:79], v[132:135], v[234:237], v[76:79]
	v_mfma_f32_16x16x32_bf16 v[68:71], v[186:189], v[234:237], v[68:71]
	v_mfma_f32_16x16x32_bf16 v[116:119], v[190:193], v[206:209], v[116:119]
	v_mfma_f32_16x16x32_bf16 v[112:115], v[198:201], v[206:209], v[112:115]
	v_mfma_f32_16x16x32_bf16 v[104:107], v[190:193], v[214:217], v[104:107]
	v_mfma_f32_16x16x32_bf16 v[96:99], v[198:201], v[214:217], v[96:99]
	v_mfma_f32_16x16x32_bf16 v[88:91], v[190:193], v[222:225], v[88:91]
	v_mfma_f32_16x16x32_bf16 v[80:83], v[198:201], v[222:225], v[80:83]
	v_mfma_f32_16x16x32_bf16 v[72:75], v[190:193], v[230:233], v[72:75]
	v_mfma_f32_16x16x32_bf16 v[64:67], v[198:201], v[230:233], v[64:67]
	v_mfma_f32_16x16x32_bf16 v[116:119], v[194:197], v[210:213], v[116:119]
	v_mfma_f32_16x16x32_bf16 v[112:115], v[202:205], v[210:213], v[112:115]
	v_mfma_f32_16x16x32_bf16 v[104:107], v[194:197], v[218:221], v[104:107]
	v_mfma_f32_16x16x32_bf16 v[96:99], v[202:205], v[218:221], v[96:99]
	v_mfma_f32_16x16x32_bf16 v[88:91], v[194:197], v[226:229], v[88:91]
	v_mfma_f32_16x16x32_bf16 v[80:83], v[202:205], v[226:229], v[80:83]
	v_mfma_f32_16x16x32_bf16 v[72:75], v[194:197], v[234:237], v[72:75]
	v_mfma_f32_16x16x32_bf16 v[64:67], v[202:205], v[234:237], v[64:67]
	s_barrier
	s_add_i32 s21, s44, s60
	s_mov_b32 m0, s21
	ds_read_b128 v[206:209], v175 offset:16384
	ds_read_b128 v[210:213], v175 offset:17408
	ds_read_b128 v[214:217], v175 offset:18432
	ds_read_b128 v[218:221], v175 offset:19456
	ds_read_b128 v[222:225], v175 offset:20480
	ds_read_b128 v[226:229], v175 offset:21504
	ds_read_b128 v[230:233], v175 offset:22528
	ds_read_b128 v[234:237], v175 offset:23552
	global_load_lds_dwordx4 v140, s[40:41]
	s_add_i32 m0, s21, 0x2000
	s_add_u32 s22, s40, 0x40000
	s_addc_u32 s23, s41, 0
	s_add_i32 s21, s45, s60
	global_load_lds_dwordx4 v136, s[40:41]
	s_mov_b32 m0, s21
	global_load_lds_dwordx4 v140, s[22:23]
	s_add_i32 m0, s21, 0x2000
	s_nop 0
	global_load_lds_dwordx4 v136, s[22:23]
	s_mov_b32 m0, s37
	s_nop 0
	global_load_lds_dwordx4 v142, s[42:43]
	s_mov_b32 m0, s63
	s_nop 0
	global_load_lds_dwordx4 v138, s[42:43]
	s_add_u32 s98, s40, s12
	s_addc_u32 s99, s41, s13
	s_add_u32 s100, s42, s12
	s_addc_u32 s101, s43, s13
	s_waitcnt vmcnt(8)
	s_waitcnt lgkmcnt(0)
	s_barrier
	s_waitcnt lgkmcnt(0)
	v_mfma_f32_16x16x32_bf16 v[60:63], v[128:131], v[206:209], v[60:63]
	v_mfma_f32_16x16x32_bf16 v[52:55], v[178:181], v[206:209], v[52:55]
	v_mfma_f32_16x16x32_bf16 v[44:47], v[128:131], v[214:217], v[44:47]
	v_mfma_f32_16x16x32_bf16 v[36:39], v[178:181], v[214:217], v[36:39]
	v_mfma_f32_16x16x32_bf16 v[28:31], v[128:131], v[222:225], v[28:31]
	v_mfma_f32_16x16x32_bf16 v[20:23], v[178:181], v[222:225], v[20:23]
	v_mfma_f32_16x16x32_bf16 v[12:15], v[128:131], v[230:233], v[12:15]
	v_mfma_f32_16x16x32_bf16 v[4:7], v[178:181], v[230:233], v[4:7]
	v_mfma_f32_16x16x32_bf16 v[60:63], v[132:135], v[210:213], v[60:63]
	v_mfma_f32_16x16x32_bf16 v[52:55], v[186:189], v[210:213], v[52:55]
	v_mfma_f32_16x16x32_bf16 v[44:47], v[132:135], v[218:221], v[44:47]
	v_mfma_f32_16x16x32_bf16 v[36:39], v[186:189], v[218:221], v[36:39]
	v_mfma_f32_16x16x32_bf16 v[28:31], v[132:135], v[226:229], v[28:31]
	v_mfma_f32_16x16x32_bf16 v[20:23], v[186:189], v[226:229], v[20:23]
	v_mfma_f32_16x16x32_bf16 v[12:15], v[132:135], v[234:237], v[12:15]
	v_mfma_f32_16x16x32_bf16 v[4:7], v[186:189], v[234:237], v[4:7]
	v_mfma_f32_16x16x32_bf16 v[56:59], v[190:193], v[206:209], v[56:59]
	v_mfma_f32_16x16x32_bf16 v[48:51], v[198:201], v[206:209], v[48:51]
	v_mfma_f32_16x16x32_bf16 v[40:43], v[190:193], v[214:217], v[40:43]
	v_mfma_f32_16x16x32_bf16 v[32:35], v[198:201], v[214:217], v[32:35]
	v_mfma_f32_16x16x32_bf16 v[24:27], v[190:193], v[222:225], v[24:27]
	v_mfma_f32_16x16x32_bf16 v[16:19], v[198:201], v[222:225], v[16:19]
	v_mfma_f32_16x16x32_bf16 v[8:11], v[190:193], v[230:233], v[8:11]
	v_mfma_f32_16x16x32_bf16 v[0:3], v[198:201], v[230:233], v[0:3]
	v_mfma_f32_16x16x32_bf16 v[56:59], v[194:197], v[210:213], v[56:59]
	v_mfma_f32_16x16x32_bf16 v[48:51], v[202:205], v[210:213], v[48:51]
	v_mfma_f32_16x16x32_bf16 v[40:43], v[194:197], v[218:221], v[40:43]
	v_mfma_f32_16x16x32_bf16 v[32:35], v[202:205], v[218:221], v[32:35]
	v_mfma_f32_16x16x32_bf16 v[24:27], v[194:197], v[226:229], v[24:27]
	v_mfma_f32_16x16x32_bf16 v[16:19], v[202:205], v[226:229], v[16:19]
	v_mfma_f32_16x16x32_bf16 v[8:11], v[194:197], v[234:237], v[8:11]
	v_mfma_f32_16x16x32_bf16 v[0:3], v[202:205], v[234:237], v[0:3]
	s_barrier
	s_add_i32 s21, 0, 0x18000
	v_add_u32_e32 v144, s21, v165
	s_add_i32 s27, 0, 0x1c000
	ds_read_b128 v[128:131], v144
	ds_read_b128 v[132:135], v144 offset:1024
	ds_read_b128 v[178:181], v144 offset:2048
	ds_read_b128 v[186:189], v144 offset:3072
	v_add_u32_e32 v144, s27, v165
	ds_read_b128 v[190:193], v144
	ds_read_b128 v[194:197], v144 offset:1024
	ds_read_b128 v[198:201], v144 offset:2048
	ds_read_b128 v[202:205], v144 offset:3072
	s_add_u32 s22, s42, 0x40000
	s_addc_u32 s23, s43, 0
	s_mov_b32 m0, s64
	ds_read_b128 v[206:209], v175 offset:32768
	ds_read_b128 v[210:213], v175 offset:33792
	ds_read_b128 v[214:217], v175 offset:34816
	ds_read_b128 v[218:221], v175 offset:35840
	ds_read_b128 v[222:225], v175 offset:36864
	ds_read_b128 v[226:229], v175 offset:37888
	ds_read_b128 v[230:233], v175 offset:38912
	ds_read_b128 v[234:237], v175 offset:39936
	global_load_lds_dwordx4 v142, s[22:23]
	s_mov_b32 m0, s65
	s_nop 0
	global_load_lds_dwordx4 v138, s[22:23]
	s_waitcnt vmcnt(8)
	s_waitcnt lgkmcnt(0)
	s_barrier
	s_waitcnt lgkmcnt(0)
	v_mfma_f32_16x16x32_bf16 v[124:127], v[128:131], v[206:209], v[124:127]
	v_mfma_f32_16x16x32_bf16 v[120:123], v[178:181], v[206:209], v[120:123]
	v_mfma_f32_16x16x32_bf16 v[108:111], v[128:131], v[214:217], v[108:111]
	v_mfma_f32_16x16x32_bf16 v[100:103], v[178:181], v[214:217], v[100:103]
	v_mfma_f32_16x16x32_bf16 v[92:95], v[128:131], v[222:225], v[92:95]
	v_mfma_f32_16x16x32_bf16 v[84:87], v[178:181], v[222:225], v[84:87]
	v_mfma_f32_16x16x32_bf16 v[76:79], v[128:131], v[230:233], v[76:79]
	v_mfma_f32_16x16x32_bf16 v[68:71], v[178:181], v[230:233], v[68:71]
	v_mfma_f32_16x16x32_bf16 v[124:127], v[132:135], v[210:213], v[124:127]
	v_mfma_f32_16x16x32_bf16 v[120:123], v[186:189], v[210:213], v[120:123]
	v_mfma_f32_16x16x32_bf16 v[108:111], v[132:135], v[218:221], v[108:111]
	v_mfma_f32_16x16x32_bf16 v[100:103], v[186:189], v[218:221], v[100:103]
	v_mfma_f32_16x16x32_bf16 v[92:95], v[132:135], v[226:229], v[92:95]
	v_mfma_f32_16x16x32_bf16 v[84:87], v[186:189], v[226:229], v[84:87]
	v_mfma_f32_16x16x32_bf16 v[76:79], v[132:135], v[234:237], v[76:79]
	v_mfma_f32_16x16x32_bf16 v[68:71], v[186:189], v[234:237], v[68:71]
	v_mfma_f32_16x16x32_bf16 v[116:119], v[190:193], v[206:209], v[116:119]
	v_mfma_f32_16x16x32_bf16 v[112:115], v[198:201], v[206:209], v[112:115]
	v_mfma_f32_16x16x32_bf16 v[104:107], v[190:193], v[214:217], v[104:107]
	v_mfma_f32_16x16x32_bf16 v[96:99], v[198:201], v[214:217], v[96:99]
	v_mfma_f32_16x16x32_bf16 v[88:91], v[190:193], v[222:225], v[88:91]
	v_mfma_f32_16x16x32_bf16 v[80:83], v[198:201], v[222:225], v[80:83]
	v_mfma_f32_16x16x32_bf16 v[72:75], v[190:193], v[230:233], v[72:75]
	v_mfma_f32_16x16x32_bf16 v[64:67], v[198:201], v[230:233], v[64:67]
	v_mfma_f32_16x16x32_bf16 v[116:119], v[194:197], v[210:213], v[116:119]
	v_mfma_f32_16x16x32_bf16 v[112:115], v[202:205], v[210:213], v[112:115]
	v_mfma_f32_16x16x32_bf16 v[104:107], v[194:197], v[218:221], v[104:107]
	v_mfma_f32_16x16x32_bf16 v[96:99], v[202:205], v[218:221], v[96:99]
	v_mfma_f32_16x16x32_bf16 v[88:91], v[194:197], v[226:229], v[88:91]
	v_mfma_f32_16x16x32_bf16 v[80:83], v[202:205], v[226:229], v[80:83]
	v_mfma_f32_16x16x32_bf16 v[72:75], v[194:197], v[234:237], v[72:75]
	v_mfma_f32_16x16x32_bf16 v[64:67], v[202:205], v[234:237], v[64:67]
	s_barrier
	s_add_i32 s21, s21, s60
	s_mov_b32 m0, s21
	ds_read_b128 v[206:209], v175 offset:49152
	ds_read_b128 v[210:213], v175 offset:50176
	ds_read_b128 v[214:217], v175 offset:51200
	ds_read_b128 v[218:221], v175 offset:52224
	ds_read_b128 v[222:225], v175 offset:53248
	ds_read_b128 v[226:229], v175 offset:54272
	ds_read_b128 v[230:233], v175 offset:55296
	ds_read_b128 v[234:237], v175 offset:56320
	global_load_lds_dwordx4 v140, s[98:99]
	s_add_i32 m0, s21, 0x2000
	s_add_u32 s22, s40, 0x40080
	s_addc_u32 s23, s41, 0
	s_add_i32 s21, s27, s60
	global_load_lds_dwordx4 v136, s[98:99]
	s_mov_b32 m0, s21
	s_nop 0
	global_load_lds_dwordx4 v140, s[22:23]
	s_add_i32 m0, s21, 0x2000
	s_nop 0
	global_load_lds_dwordx4 v136, s[22:23]
	s_mov_b32 m0, s67
	s_nop 0
	global_load_lds_dwordx4 v142, s[100:101]
	s_mov_b32 m0, s70
	s_nop 0
	global_load_lds_dwordx4 v138, s[100:101]
	s_waitcnt vmcnt(8)
	s_waitcnt lgkmcnt(0)
	s_barrier
	s_waitcnt lgkmcnt(0)
	v_mfma_f32_16x16x32_bf16 v[60:63], v[128:131], v[206:209], v[60:63]
	v_mfma_f32_16x16x32_bf16 v[52:55], v[178:181], v[206:209], v[52:55]
	v_mfma_f32_16x16x32_bf16 v[44:47], v[128:131], v[214:217], v[44:47]
	v_mfma_f32_16x16x32_bf16 v[36:39], v[178:181], v[214:217], v[36:39]
	v_mfma_f32_16x16x32_bf16 v[28:31], v[128:131], v[222:225], v[28:31]
	v_mfma_f32_16x16x32_bf16 v[20:23], v[178:181], v[222:225], v[20:23]
	v_mfma_f32_16x16x32_bf16 v[12:15], v[128:131], v[230:233], v[12:15]
	v_mfma_f32_16x16x32_bf16 v[4:7], v[178:181], v[230:233], v[4:7]
	v_mfma_f32_16x16x32_bf16 v[60:63], v[132:135], v[210:213], v[60:63]
	v_mfma_f32_16x16x32_bf16 v[52:55], v[186:189], v[210:213], v[52:55]
	v_mfma_f32_16x16x32_bf16 v[44:47], v[132:135], v[218:221], v[44:47]
	v_mfma_f32_16x16x32_bf16 v[36:39], v[186:189], v[218:221], v[36:39]
	v_mfma_f32_16x16x32_bf16 v[28:31], v[132:135], v[226:229], v[28:31]
	v_mfma_f32_16x16x32_bf16 v[20:23], v[186:189], v[226:229], v[20:23]
	v_mfma_f32_16x16x32_bf16 v[12:15], v[132:135], v[234:237], v[12:15]
	v_mfma_f32_16x16x32_bf16 v[4:7], v[186:189], v[234:237], v[4:7]
	v_mfma_f32_16x16x32_bf16 v[56:59], v[190:193], v[206:209], v[56:59]
	v_mfma_f32_16x16x32_bf16 v[48:51], v[198:201], v[206:209], v[48:51]
	v_mfma_f32_16x16x32_bf16 v[40:43], v[190:193], v[214:217], v[40:43]
	v_mfma_f32_16x16x32_bf16 v[32:35], v[198:201], v[214:217], v[32:35]
	v_mfma_f32_16x16x32_bf16 v[24:27], v[190:193], v[222:225], v[24:27]
	v_mfma_f32_16x16x32_bf16 v[16:19], v[198:201], v[222:225], v[16:19]
	v_mfma_f32_16x16x32_bf16 v[8:11], v[190:193], v[230:233], v[8:11]
	v_mfma_f32_16x16x32_bf16 v[0:3], v[198:201], v[230:233], v[0:3]
	v_mfma_f32_16x16x32_bf16 v[56:59], v[194:197], v[210:213], v[56:59]
	v_mfma_f32_16x16x32_bf16 v[48:51], v[202:205], v[210:213], v[48:51]
	v_mfma_f32_16x16x32_bf16 v[40:43], v[194:197], v[218:221], v[40:43]
	v_mfma_f32_16x16x32_bf16 v[32:35], v[202:205], v[218:221], v[32:35]
	v_mfma_f32_16x16x32_bf16 v[24:27], v[194:197], v[226:229], v[24:27]
	v_mfma_f32_16x16x32_bf16 v[16:19], v[202:205], v[226:229], v[16:19]
	v_mfma_f32_16x16x32_bf16 v[8:11], v[194:197], v[234:237], v[8:11]
	v_mfma_f32_16x16x32_bf16 v[0:3], v[202:205], v[234:237], v[0:3]
	s_barrier
	s_add_i32 s20, s20, 2
	s_add_u32 s38, s38, 0x100
	s_addc_u32 s39, s39, 0
	s_add_u32 s18, s18, 0x100
	s_addc_u32 s19, s19, 0
	s_cmp_gt_u32 s20, 13
	s_cbranch_scc0 .LBB0_1413
	s_and_b64 vcc, exec, s[24:25]
	s_cbranch_vccz .LBB0_1418
	s_barrier
	s_cmp_lt_i32 s80, 8
	s_mov_b64 s[38:39], -1
	s_cbranch_scc1 .LBB0_1419

.LBB0_1552:
	s_cmp_gt_i32 s79, 12
	s_cselect_b64 s[4:5], -1, 0
	s_and_b64 s[0:1], s[0:1], s[4:5]
	s_andn2_b64 vcc, exec, s[0:1]
	s_cbranch_vccnz .LBB0_1606
	s_waitcnt vmcnt(0) lgkmcnt(0)
	s_barrier
	v_readlane_b32 s21, v242, 63
	s_add_u32 s21, s21, 1
	v_readlane_b32 s12, v242, 1
	v_readlane_b32 s13, v242, 2
	s_mov_b64 s[14:15], exec
	s_and_b64 s[12:13], s[14:15], s[12:13]
	s_mov_b64 exec, s[12:13]
	s_cbranch_execz .Lxb_done_9
	v_mov_b32_e32 v0, 0x21020
	ds_read2_b32 v[2:3], v0 offset1:1
	s_lshl_b32 s16, s84, 8
	s_add_u32 s16, s76, s16
	s_addc_u32 s17, s77, 0
	v_mov_b32_e32 v1, 0x1000
	v_mov_b32_e32 v4, 1
	global_atomic_add v5, v1, v4, s[16:17] offset:1024 sc0
	buffer_inv sc1
	s_waitcnt vmcnt(0) lgkmcnt(0)
	v_readfirstlane_b32 s18, v5
	v_readfirstlane_b32 s19, v2
	v_readfirstlane_b32 s20, v3
	v_mov_b32_e32 v1, 0x3000
	s_mul_i32 s22, s19, s21
	s_mul_i32 s23, s20, s21
	s_add_u32 s18, s18, 1
	s_cmp_lg_u32 s18, s22
	s_cbranch_scc1 .Lxb_spin_9
	buffer_wbl2 sc1
	s_waitcnt vmcnt(0)
	global_atomic_add v1, v4, s[76:77] offset:1024

.LBB0_1630:
	ds_read_b128 v[128:131], v189
	ds_read_b128 v[132:135], v189 offset:1024
	ds_read_b128 v[136:139], v189 offset:2048
	ds_read_b128 v[140:143], v189 offset:3072
	ds_read_b128 v[144:147], v190
	ds_read_b128 v[148:151], v190 offset:1024
	ds_read_b128 v[172:175], v190 offset:2048
	ds_read_b128 v[176:179], v190 offset:3072
	s_add_u32 s24, s22, 0xfff50080
	s_addc_u32 s25, s23, -1
	s_cmp_eq_u32 s50, 40
	s_cselect_b32 s27, s1, s25
	s_cselect_b32 s26, s0, s24
	s_cselect_b32 s25, s19, s47
	s_cselect_b32 s24, s18, s21
	s_add_i32 m0, s30, 0xc000
	ds_read_b128 v[180:183], v191
	ds_read_b128 v[194:197], v191 offset:1024
	ds_read_b128 v[198:201], v191 offset:2048
	ds_read_b128 v[202:205], v191 offset:3072
	ds_read_b128 v[206:209], v191 offset:4096
	ds_read_b128 v[210:213], v191 offset:5120
	ds_read_b128 v[214:217], v191 offset:6144
	ds_read_b128 v[218:221], v191 offset:7168
	global_load_lds_dwordx4 v164, s[22:23]
	s_add_i32 m0, s30, 0xe000
	s_nop 0
	global_load_lds_dwordx4 v166, s[22:23]
	s_waitcnt vmcnt(8)
	s_waitcnt lgkmcnt(0)
	s_barrier
	s_waitcnt lgkmcnt(0)
	v_mfma_f32_16x16x32_bf16 v[124:127], v[128:131], v[180:183], v[124:127]
	v_mfma_f32_16x16x32_bf16 v[120:123], v[136:139], v[180:183], v[120:123]
	v_mfma_f32_16x16x32_bf16 v[108:111], v[128:131], v[198:201], v[108:111]
	v_mfma_f32_16x16x32_bf16 v[104:107], v[136:139], v[198:201], v[104:107]
	v_mfma_f32_16x16x32_bf16 v[92:95], v[128:131], v[206:209], v[92:95]
	v_mfma_f32_16x16x32_bf16 v[88:91], v[136:139], v[206:209], v[88:91]
	v_mfma_f32_16x16x32_bf16 v[76:79], v[128:131], v[214:217], v[76:79]
	v_mfma_f32_16x16x32_bf16 v[72:75], v[136:139], v[214:217], v[72:75]
	v_mfma_f32_16x16x32_bf16 v[124:127], v[132:135], v[194:197], v[124:127]
	v_mfma_f32_16x16x32_bf16 v[120:123], v[140:143], v[194:197], v[120:123]
	v_mfma_f32_16x16x32_bf16 v[108:111], v[132:135], v[202:205], v[108:111]
	v_mfma_f32_16x16x32_bf16 v[104:107], v[140:143], v[202:205], v[104:107]
	v_mfma_f32_16x16x32_bf16 v[92:95], v[132:135], v[210:213], v[92:95]
	v_mfma_f32_16x16x32_bf16 v[88:91], v[140:143], v[210:213], v[88:91]
	v_mfma_f32_16x16x32_bf16 v[76:79], v[132:135], v[218:221], v[76:79]
	v_mfma_f32_16x16x32_bf16 v[72:75], v[140:143], v[218:221], v[72:75]
	v_mfma_f32_16x16x32_bf16 v[116:119], v[144:147], v[180:183], v[116:119]
	v_mfma_f32_16x16x32_bf16 v[112:115], v[172:175], v[180:183], v[112:115]
	v_mfma_f32_16x16x32_bf16 v[100:103], v[144:147], v[198:201], v[100:103]
	v_mfma_f32_16x16x32_bf16 v[96:99], v[172:175], v[198:201], v[96:99]
	v_mfma_f32_16x16x32_bf16 v[84:87], v[144:147], v[206:209], v[84:87]
	v_mfma_f32_16x16x32_bf16 v[80:83], v[172:175], v[206:209], v[80:83]
	v_mfma_f32_16x16x32_bf16 v[68:71], v[144:147], v[214:217], v[68:71]
	v_mfma_f32_16x16x32_bf16 v[64:67], v[172:175], v[214:217], v[64:67]
	v_mfma_f32_16x16x32_bf16 v[116:119], v[148:151], v[194:197], v[116:119]
	v_mfma_f32_16x16x32_bf16 v[112:115], v[176:179], v[194:197], v[112:115]
	v_mfma_f32_16x16x32_bf16 v[100:103], v[148:151], v[202:205], v[100:103]
	v_mfma_f32_16x16x32_bf16 v[96:99], v[176:179], v[202:205], v[96:99]
	v_mfma_f32_16x16x32_bf16 v[84:87], v[148:151], v[210:213], v[84:87]
	v_mfma_f32_16x16x32_bf16 v[80:83], v[176:179], v[210:213], v[80:83]
	v_mfma_f32_16x16x32_bf16 v[68:71], v[148:151], v[218:221], v[68:71]
	v_mfma_f32_16x16x32_bf16 v[64:67], v[176:179], v[218:221], v[64:67]
	s_barrier
	s_add_i32 s51, s42, s29
	s_mov_b32 m0, s51
	ds_read_b128 v[180:183], v191 offset:16384
	ds_read_b128 v[194:197], v191 offset:17408
	ds_read_b128 v[198:201], v191 offset:18432
	ds_read_b128 v[202:205], v191 offset:19456
	ds_read_b128 v[206:209], v191 offset:20480
	ds_read_b128 v[210:213], v191 offset:21504
	ds_read_b128 v[214:217], v191 offset:22528
	ds_read_b128 v[218:221], v191 offset:23552
	global_load_lds_dwordx4 v154, s[24:25]
	s_add_i32 m0, s51, 0x2000
	s_add_u32 s52, s24, 0xb0000
	s_addc_u32 s53, s25, 0
	s_add_i32 s51, s43, s29
	global_load_lds_dwordx4 v158, s[24:25]
	s_mov_b32 m0, s51
	global_load_lds_dwordx4 v154, s[52:53]
	s_add_i32 m0, s51, 0x2000
	s_nop 0
	global_load_lds_dwordx4 v158, s[52:53]
	s_mov_b32 m0, s30
	s_nop 0
	global_load_lds_dwordx4 v152, s[26:27]
	s_mov_b32 m0, s31
	s_nop 0
	global_load_lds_dwordx4 v156, s[26:27]
	s_add_u32 s98, s24, s14
	s_addc_u32 s99, s25, s15
	s_add_u32 s100, s26, s14
	s_addc_u32 s101, s27, s15
	s_waitcnt vmcnt(8)
	s_waitcnt lgkmcnt(0)
	s_barrier
	s_waitcnt lgkmcnt(0)
	v_mfma_f32_16x16x32_bf16 v[60:63], v[128:131], v[180:183], v[60:63]
	v_mfma_f32_16x16x32_bf16 v[56:59], v[136:139], v[180:183], v[56:59]
	v_mfma_f32_16x16x32_bf16 v[44:47], v[128:131], v[198:201], v[44:47]
	v_mfma_f32_16x16x32_bf16 v[40:43], v[136:139], v[198:201], v[40:43]
	v_mfma_f32_16x16x32_bf16 v[28:31], v[128:131], v[206:209], v[28:31]
	v_mfma_f32_16x16x32_bf16 v[24:27], v[136:139], v[206:209], v[24:27]
	v_mfma_f32_16x16x32_bf16 v[12:15], v[128:131], v[214:217], v[12:15]
	v_mfma_f32_16x16x32_bf16 v[8:11], v[136:139], v[214:217], v[8:11]
	v_mfma_f32_16x16x32_bf16 v[60:63], v[132:135], v[194:197], v[60:63]
	v_mfma_f32_16x16x32_bf16 v[56:59], v[140:143], v[194:197], v[56:59]
	v_mfma_f32_16x16x32_bf16 v[44:47], v[132:135], v[202:205], v[44:47]
	v_mfma_f32_16x16x32_bf16 v[40:43], v[140:143], v[202:205], v[40:43]
	v_mfma_f32_16x16x32_bf16 v[28:31], v[132:135], v[210:213], v[28:31]
	v_mfma_f32_16x16x32_bf16 v[24:27], v[140:143], v[210:213], v[24:27]
	v_mfma_f32_16x16x32_bf16 v[12:15], v[132:135], v[218:221], v[12:15]
	v_mfma_f32_16x16x32_bf16 v[8:11], v[140:143], v[218:221], v[8:11]
	v_mfma_f32_16x16x32_bf16 v[52:55], v[144:147], v[180:183], v[52:55]
	v_mfma_f32_16x16x32_bf16 v[48:51], v[172:175], v[180:183], v[48:51]
	v_mfma_f32_16x16x32_bf16 v[36:39], v[144:147], v[198:201], v[36:39]
	v_mfma_f32_16x16x32_bf16 v[32:35], v[172:175], v[198:201], v[32:35]
	v_mfma_f32_16x16x32_bf16 v[20:23], v[144:147], v[206:209], v[20:23]
	v_mfma_f32_16x16x32_bf16 v[16:19], v[172:175], v[206:209], v[16:19]
	v_mfma_f32_16x16x32_bf16 v[4:7], v[144:147], v[214:217], v[4:7]
	v_mfma_f32_16x16x32_bf16 v[0:3], v[172:175], v[214:217], v[0:3]
	v_mfma_f32_16x16x32_bf16 v[52:55], v[148:151], v[194:197], v[52:55]
	v_mfma_f32_16x16x32_bf16 v[48:51], v[176:179], v[194:197], v[48:51]
	v_mfma_f32_16x16x32_bf16 v[36:39], v[148:151], v[202:205], v[36:39]
	v_mfma_f32_16x16x32_bf16 v[32:35], v[176:179], v[202:205], v[32:35]
	v_mfma_f32_16x16x32_bf16 v[20:23], v[148:151], v[210:213], v[20:23]
	v_mfma_f32_16x16x32_bf16 v[16:19], v[176:179], v[210:213], v[16:19]
	v_mfma_f32_16x16x32_bf16 v[4:7], v[148:151], v[218:221], v[4:7]
	v_mfma_f32_16x16x32_bf16 v[0:3], v[176:179], v[218:221], v[0:3]
	s_barrier
	s_add_i32 s51, 0, 0x18000
	s_add_i32 s52, 0, 0x1c000
	v_add_u32_e32 v140, s51, v186
	v_add_u32_e32 v176, s52, v186
	ds_read_b128 v[128:131], v140
	ds_read_b128 v[132:135], v140 offset:1024
	ds_read_b128 v[136:139], v140 offset:2048
	ds_read_b128 v[140:143], v140 offset:3072
	ds_read_b128 v[144:147], v176
	ds_read_b128 v[148:151], v176 offset:1024
	ds_read_b128 v[172:175], v176 offset:2048
	ds_read_b128 v[176:179], v176 offset:3072
	s_add_u32 s26, s26, 0xb0000
	s_addc_u32 s27, s27, 0
	s_mov_b32 m0, s34
	ds_read_b128 v[180:183], v191 offset:32768
	ds_read_b128 v[194:197], v191 offset:33792
	ds_read_b128 v[198:201], v191 offset:34816
	ds_read_b128 v[202:205], v191 offset:35840
	ds_read_b128 v[206:209], v191 offset:36864
	ds_read_b128 v[210:213], v191 offset:37888
	ds_read_b128 v[214:217], v191 offset:38912
	ds_read_b128 v[218:221], v191 offset:39936
	global_load_lds_dwordx4 v152, s[26:27]
	s_mov_b32 m0, s35
	s_nop 0
	global_load_lds_dwordx4 v156, s[26:27]
	s_waitcnt vmcnt(8)
	s_waitcnt lgkmcnt(0)
	s_barrier
	s_waitcnt lgkmcnt(0)
	v_mfma_f32_16x16x32_bf16 v[124:127], v[128:131], v[180:183], v[124:127]
	v_mfma_f32_16x16x32_bf16 v[120:123], v[136:139], v[180:183], v[120:123]
	v_mfma_f32_16x16x32_bf16 v[108:111], v[128:131], v[198:201], v[108:111]
	v_mfma_f32_16x16x32_bf16 v[104:107], v[136:139], v[198:201], v[104:107]
	v_mfma_f32_16x16x32_bf16 v[92:95], v[128:131], v[206:209], v[92:95]
	v_mfma_f32_16x16x32_bf16 v[88:91], v[136:139], v[206:209], v[88:91]
	v_mfma_f32_16x16x32_bf16 v[76:79], v[128:131], v[214:217], v[76:79]
	v_mfma_f32_16x16x32_bf16 v[72:75], v[136:139], v[214:217], v[72:75]
	v_mfma_f32_16x16x32_bf16 v[124:127], v[132:135], v[194:197], v[124:127]
	v_mfma_f32_16x16x32_bf16 v[120:123], v[140:143], v[194:197], v[120:123]
	v_mfma_f32_16x16x32_bf16 v[108:111], v[132:135], v[202:205], v[108:111]
	v_mfma_f32_16x16x32_bf16 v[104:107], v[140:143], v[202:205], v[104:107]
	v_mfma_f32_16x16x32_bf16 v[92:95], v[132:135], v[210:213], v[92:95]
	v_mfma_f32_16x16x32_bf16 v[88:91], v[140:143], v[210:213], v[88:91]
	v_mfma_f32_16x16x32_bf16 v[76:79], v[132:135], v[218:221], v[76:79]
	v_mfma_f32_16x16x32_bf16 v[72:75], v[140:143], v[218:221], v[72:75]
	v_mfma_f32_16x16x32_bf16 v[116:119], v[144:147], v[180:183], v[116:119]
	v_mfma_f32_16x16x32_bf16 v[112:115], v[172:175], v[180:183], v[112:115]
	v_mfma_f32_16x16x32_bf16 v[100:103], v[144:147], v[198:201], v[100:103]
	v_mfma_f32_16x16x32_bf16 v[96:99], v[172:175], v[198:201], v[96:99]
	v_mfma_f32_16x16x32_bf16 v[84:87], v[144:147], v[206:209], v[84:87]
	v_mfma_f32_16x16x32_bf16 v[80:83], v[172:175], v[206:209], v[80:83]
	v_mfma_f32_16x16x32_bf16 v[68:71], v[144:147], v[214:217], v[68:71]
	v_mfma_f32_16x16x32_bf16 v[64:67], v[172:175], v[214:217], v[64:67]
	v_mfma_f32_16x16x32_bf16 v[116:119], v[148:151], v[194:197], v[116:119]
	v_mfma_f32_16x16x32_bf16 v[112:115], v[176:179], v[194:197], v[112:115]
	v_mfma_f32_16x16x32_bf16 v[100:103], v[148:151], v[202:205], v[100:103]
	v_mfma_f32_16x16x32_bf16 v[96:99], v[176:179], v[202:205], v[96:99]
	v_mfma_f32_16x16x32_bf16 v[84:87], v[148:151], v[210:213], v[84:87]
	v_mfma_f32_16x16x32_bf16 v[80:83], v[176:179], v[210:213], v[80:83]
	v_mfma_f32_16x16x32_bf16 v[68:71], v[148:151], v[218:221], v[68:71]
	v_mfma_f32_16x16x32_bf16 v[64:67], v[176:179], v[218:221], v[64:67]
	s_barrier
	s_add_i32 s26, s51, s29
	s_mov_b32 m0, s26
	ds_read_b128 v[180:183], v191 offset:49152
	ds_read_b128 v[194:197], v191 offset:50176
	ds_read_b128 v[198:201], v191 offset:51200
	ds_read_b128 v[202:205], v191 offset:52224
	ds_read_b128 v[206:209], v191 offset:53248
	ds_read_b128 v[210:213], v191 offset:54272
	ds_read_b128 v[214:217], v191 offset:55296
	ds_read_b128 v[218:221], v191 offset:56320
	global_load_lds_dwordx4 v154, s[98:99]
	s_add_i32 m0, s26, 0x2000
	s_add_u32 s24, s24, 0xb0080
	s_addc_u32 s25, s25, 0
	s_add_i32 s26, s52, s29
	global_load_lds_dwordx4 v158, s[98:99]
	s_mov_b32 m0, s26
	s_nop 0
	global_load_lds_dwordx4 v154, s[24:25]
	s_add_i32 m0, s26, 0x2000
	s_nop 0
	global_load_lds_dwordx4 v158, s[24:25]
	s_mov_b32 m0, s37
	s_nop 0
	global_load_lds_dwordx4 v152, s[100:101]
	s_mov_b32 m0, s38
	s_nop 0
	global_load_lds_dwordx4 v156, s[100:101]
	s_waitcnt vmcnt(8)
	s_waitcnt lgkmcnt(0)
	s_barrier
	s_waitcnt lgkmcnt(0)
	v_mfma_f32_16x16x32_bf16 v[60:63], v[128:131], v[180:183], v[60:63]
	v_mfma_f32_16x16x32_bf16 v[56:59], v[136:139], v[180:183], v[56:59]
	v_mfma_f32_16x16x32_bf16 v[44:47], v[128:131], v[198:201], v[44:47]
	v_mfma_f32_16x16x32_bf16 v[40:43], v[136:139], v[198:201], v[40:43]
	v_mfma_f32_16x16x32_bf16 v[28:31], v[128:131], v[206:209], v[28:31]
	v_mfma_f32_16x16x32_bf16 v[24:27], v[136:139], v[206:209], v[24:27]
	v_mfma_f32_16x16x32_bf16 v[12:15], v[128:131], v[214:217], v[12:15]
	v_mfma_f32_16x16x32_bf16 v[8:11], v[136:139], v[214:217], v[8:11]
	v_mfma_f32_16x16x32_bf16 v[60:63], v[132:135], v[194:197], v[60:63]
	v_mfma_f32_16x16x32_bf16 v[56:59], v[140:143], v[194:197], v[56:59]
	v_mfma_f32_16x16x32_bf16 v[44:47], v[132:135], v[202:205], v[44:47]
	v_mfma_f32_16x16x32_bf16 v[40:43], v[140:143], v[202:205], v[40:43]
	v_mfma_f32_16x16x32_bf16 v[28:31], v[132:135], v[210:213], v[28:31]
	v_mfma_f32_16x16x32_bf16 v[24:27], v[140:143], v[210:213], v[24:27]
	v_mfma_f32_16x16x32_bf16 v[12:15], v[132:135], v[218:221], v[12:15]
	v_mfma_f32_16x16x32_bf16 v[8:11], v[140:143], v[218:221], v[8:11]
	v_mfma_f32_16x16x32_bf16 v[52:55], v[144:147], v[180:183], v[52:55]
	v_mfma_f32_16x16x32_bf16 v[48:51], v[172:175], v[180:183], v[48:51]
	v_mfma_f32_16x16x32_bf16 v[36:39], v[144:147], v[198:201], v[36:39]
	v_mfma_f32_16x16x32_bf16 v[32:35], v[172:175], v[198:201], v[32:35]
	v_mfma_f32_16x16x32_bf16 v[20:23], v[144:147], v[206:209], v[20:23]
	v_mfma_f32_16x16x32_bf16 v[16:19], v[172:175], v[206:209], v[16:19]
	v_mfma_f32_16x16x32_bf16 v[4:7], v[144:147], v[214:217], v[4:7]
	v_mfma_f32_16x16x32_bf16 v[0:3], v[172:175], v[214:217], v[0:3]
	v_mfma_f32_16x16x32_bf16 v[52:55], v[148:151], v[194:197], v[52:55]
	v_mfma_f32_16x16x32_bf16 v[48:51], v[176:179], v[194:197], v[48:51]
	v_mfma_f32_16x16x32_bf16 v[36:39], v[148:151], v[202:205], v[36:39]
	v_mfma_f32_16x16x32_bf16 v[32:35], v[176:179], v[202:205], v[32:35]
	v_mfma_f32_16x16x32_bf16 v[20:23], v[148:151], v[210:213], v[20:23]
	v_mfma_f32_16x16x32_bf16 v[16:19], v[176:179], v[210:213], v[16:19]
	v_mfma_f32_16x16x32_bf16 v[4:7], v[148:151], v[218:221], v[4:7]
	v_mfma_f32_16x16x32_bf16 v[0:3], v[176:179], v[218:221], v[0:3]
	s_barrier
	s_add_i32 s50, s50, 2
	s_add_u32 s22, s22, 0x100
	s_addc_u32 s23, s23, 0
	s_add_u32 s21, s21, 0x100
	s_addc_u32 s47, s47, 0
	s_cmp_gt_u32 s50, 41
	s_cbranch_scc0 .LBB0_1630
	s_and_b64 vcc, exec, s[16:17]
	s_cbranch_vccz .LBB0_1633
	s_barrier

.LBB0_1655:
	s_cmp_gt_i32 s79, 13
	s_cselect_b64 s[4:5], -1, 0
	s_and_b64 s[0:1], s[10:11], s[4:5]
	s_andn2_b64 vcc, exec, s[0:1]
	s_cbranch_vccnz .LBB0_1709
	s_waitcnt vmcnt(0) lgkmcnt(0)
	s_barrier
	v_readlane_b32 s21, v242, 63
	s_add_u32 s21, s21, 1
	v_readlane_b32 s12, v242, 1
	v_readlane_b32 s13, v242, 2
	s_mov_b64 s[14:15], exec
	s_and_b64 s[12:13], s[14:15], s[12:13]
	s_mov_b64 exec, s[12:13]
	s_cbranch_execz .Lxb_done_10
	v_mov_b32_e32 v0, 0x21020
	ds_read2_b32 v[2:3], v0 offset1:1
	s_lshl_b32 s16, s84, 8
	s_add_u32 s16, s76, s16
	s_addc_u32 s17, s77, 0
	v_mov_b32_e32 v1, 0x1000
	v_mov_b32_e32 v4, 1
	global_atomic_add v5, v1, v4, s[16:17] offset:1024 sc0
	buffer_inv sc1
	s_waitcnt vmcnt(0) lgkmcnt(0)
	v_readfirstlane_b32 s18, v5
	v_readfirstlane_b32 s19, v2
	v_readfirstlane_b32 s20, v3
	v_mov_b32_e32 v1, 0x3000
	s_mul_i32 s22, s19, s21
	s_mul_i32 s23, s20, s21
	s_add_u32 s18, s18, 1
	s_cmp_lg_u32 s18, s22
	s_cbranch_scc1 .Lxb_spin_10
	buffer_wbl2 sc1
	s_waitcnt vmcnt(0)
	global_atomic_add v1, v4, s[76:77] offset:1024

.LBB0_1727:
	ds_read_b128 v[128:131], v163
	ds_read_b128 v[132:135], v163 offset:1024
	ds_read_b128 v[172:175], v163 offset:2048
	ds_read_b128 v[176:179], v163 offset:3072
	ds_read_b128 v[180:183], v165
	ds_read_b128 v[186:189], v165 offset:1024
	ds_read_b128 v[190:193], v165 offset:2048
	ds_read_b128 v[194:197], v165 offset:3072
	s_add_u32 s26, s24, 0xfffc0080
	s_addc_u32 s27, s25, -1
	s_cmp_eq_u32 s51, 12
	s_cselect_b32 s29, s15, s27
	s_cselect_b32 s28, s47, s26
	s_cselect_b32 s27, s17, s50
	s_cselect_b32 s26, s48, s49
	s_add_i32 m0, s23, 0xc000
	ds_read_b128 v[198:201], v167
	ds_read_b128 v[202:205], v167 offset:1024
	ds_read_b128 v[206:209], v167 offset:2048
	ds_read_b128 v[210:213], v167 offset:3072
	ds_read_b128 v[214:217], v167 offset:4096
	ds_read_b128 v[218:221], v167 offset:5120
	ds_read_b128 v[222:225], v167 offset:6144
	ds_read_b128 v[226:229], v167 offset:7168
	global_load_lds_dwordx4 v148, s[24:25]
	s_add_i32 m0, s23, 0xe000
	s_nop 0
	global_load_lds_dwordx4 v150, s[24:25]
	s_waitcnt vmcnt(8)
	s_waitcnt lgkmcnt(0)
	s_barrier
	s_waitcnt lgkmcnt(0)
	v_mfma_f32_16x16x32_bf16 v[124:127], v[128:131], v[198:201], v[124:127]
	v_mfma_f32_16x16x32_bf16 v[120:123], v[172:175], v[198:201], v[120:123]
	v_mfma_f32_16x16x32_bf16 v[116:119], v[128:131], v[206:209], v[116:119]
	v_mfma_f32_16x16x32_bf16 v[112:115], v[172:175], v[206:209], v[112:115]
	v_mfma_f32_16x16x32_bf16 v[108:111], v[128:131], v[214:217], v[108:111]
	v_mfma_f32_16x16x32_bf16 v[104:107], v[172:175], v[214:217], v[104:107]
	v_mfma_f32_16x16x32_bf16 v[100:103], v[128:131], v[222:225], v[100:103]
	v_mfma_f32_16x16x32_bf16 v[96:99], v[172:175], v[222:225], v[96:99]
	v_mfma_f32_16x16x32_bf16 v[124:127], v[132:135], v[202:205], v[124:127]
	v_mfma_f32_16x16x32_bf16 v[120:123], v[176:179], v[202:205], v[120:123]
	v_mfma_f32_16x16x32_bf16 v[116:119], v[132:135], v[210:213], v[116:119]
	v_mfma_f32_16x16x32_bf16 v[112:115], v[176:179], v[210:213], v[112:115]
	v_mfma_f32_16x16x32_bf16 v[108:111], v[132:135], v[218:221], v[108:111]
	v_mfma_f32_16x16x32_bf16 v[104:107], v[176:179], v[218:221], v[104:107]
	v_mfma_f32_16x16x32_bf16 v[100:103], v[132:135], v[226:229], v[100:103]
	v_mfma_f32_16x16x32_bf16 v[96:99], v[176:179], v[226:229], v[96:99]
	v_mfma_f32_16x16x32_bf16 v[72:75], v[180:183], v[198:201], v[72:75]
	v_mfma_f32_16x16x32_bf16 v[64:67], v[190:193], v[198:201], v[64:67]
	v_mfma_f32_16x16x32_bf16 v[56:59], v[180:183], v[206:209], v[56:59]
	v_mfma_f32_16x16x32_bf16 v[48:51], v[190:193], v[206:209], v[48:51]
	v_mfma_f32_16x16x32_bf16 v[44:47], v[180:183], v[214:217], v[44:47]
	v_mfma_f32_16x16x32_bf16 v[40:43], v[190:193], v[214:217], v[40:43]
	v_mfma_f32_16x16x32_bf16 v[36:39], v[180:183], v[222:225], v[36:39]
	v_mfma_f32_16x16x32_bf16 v[32:35], v[190:193], v[222:225], v[32:35]
	v_mfma_f32_16x16x32_bf16 v[72:75], v[186:189], v[202:205], v[72:75]
	v_mfma_f32_16x16x32_bf16 v[64:67], v[194:197], v[202:205], v[64:67]
	v_mfma_f32_16x16x32_bf16 v[56:59], v[186:189], v[210:213], v[56:59]
	v_mfma_f32_16x16x32_bf16 v[48:51], v[194:197], v[210:213], v[48:51]
	v_mfma_f32_16x16x32_bf16 v[44:47], v[186:189], v[218:221], v[44:47]
	v_mfma_f32_16x16x32_bf16 v[40:43], v[194:197], v[218:221], v[40:43]
	v_mfma_f32_16x16x32_bf16 v[36:39], v[186:189], v[226:229], v[36:39]
	v_mfma_f32_16x16x32_bf16 v[32:35], v[194:197], v[226:229], v[32:35]
	s_barrier
	s_add_i32 s52, s44, s34
	s_mov_b32 m0, s52
	ds_read_b128 v[198:201], v167 offset:16384
	ds_read_b128 v[202:205], v167 offset:17408
	ds_read_b128 v[206:209], v167 offset:18432
	ds_read_b128 v[210:213], v167 offset:19456
	ds_read_b128 v[214:217], v167 offset:20480
	ds_read_b128 v[218:221], v167 offset:21504
	ds_read_b128 v[222:225], v167 offset:22528
	ds_read_b128 v[226:229], v167 offset:23552
	global_load_lds_dwordx4 v138, s[26:27]
	s_add_i32 m0, s52, 0x2000
	s_add_u32 s52, s26, 0x40000
	s_addc_u32 s53, s27, 0
	s_add_i32 s54, s45, s34
	global_load_lds_dwordx4 v142, s[26:27]
	s_mov_b32 m0, s54
	global_load_lds_dwordx4 v138, s[52:53]
	s_add_i32 m0, s54, 0x2000
	s_nop 0
	global_load_lds_dwordx4 v142, s[52:53]
	s_mov_b32 m0, s23
	s_nop 0
	global_load_lds_dwordx4 v136, s[28:29]
	s_mov_b32 m0, s35
	s_nop 0
	global_load_lds_dwordx4 v140, s[28:29]
	s_add_u32 s98, s26, s10
	s_addc_u32 s99, s27, s11
	s_add_u32 s100, s28, s10
	s_addc_u32 s101, s29, s11
	s_waitcnt vmcnt(8)
	s_waitcnt lgkmcnt(0)
	s_barrier
	s_waitcnt lgkmcnt(0)
	v_mfma_f32_16x16x32_bf16 v[92:95], v[128:131], v[198:201], v[92:95]
	v_mfma_f32_16x16x32_bf16 v[88:91], v[172:175], v[198:201], v[88:91]
	v_mfma_f32_16x16x32_bf16 v[84:87], v[128:131], v[206:209], v[84:87]
	v_mfma_f32_16x16x32_bf16 v[80:83], v[172:175], v[206:209], v[80:83]
	v_mfma_f32_16x16x32_bf16 v[76:79], v[128:131], v[214:217], v[76:79]
	v_mfma_f32_16x16x32_bf16 v[68:71], v[172:175], v[214:217], v[68:71]
	v_mfma_f32_16x16x32_bf16 v[60:63], v[128:131], v[222:225], v[60:63]
	v_mfma_f32_16x16x32_bf16 v[52:55], v[172:175], v[222:225], v[52:55]
	v_mfma_f32_16x16x32_bf16 v[92:95], v[132:135], v[202:205], v[92:95]
	v_mfma_f32_16x16x32_bf16 v[88:91], v[176:179], v[202:205], v[88:91]
	v_mfma_f32_16x16x32_bf16 v[84:87], v[132:135], v[210:213], v[84:87]
	v_mfma_f32_16x16x32_bf16 v[80:83], v[176:179], v[210:213], v[80:83]
	v_mfma_f32_16x16x32_bf16 v[76:79], v[132:135], v[218:221], v[76:79]
	v_mfma_f32_16x16x32_bf16 v[68:71], v[176:179], v[218:221], v[68:71]
	v_mfma_f32_16x16x32_bf16 v[60:63], v[132:135], v[226:229], v[60:63]
	v_mfma_f32_16x16x32_bf16 v[52:55], v[176:179], v[226:229], v[52:55]
	v_mfma_f32_16x16x32_bf16 v[28:31], v[180:183], v[198:201], v[28:31]
	v_mfma_f32_16x16x32_bf16 v[24:27], v[190:193], v[198:201], v[24:27]
	v_mfma_f32_16x16x32_bf16 v[20:23], v[180:183], v[206:209], v[20:23]
	v_mfma_f32_16x16x32_bf16 v[16:19], v[190:193], v[206:209], v[16:19]
	v_mfma_f32_16x16x32_bf16 v[12:15], v[180:183], v[214:217], v[12:15]
	v_mfma_f32_16x16x32_bf16 v[8:11], v[190:193], v[214:217], v[8:11]
	v_mfma_f32_16x16x32_bf16 v[4:7], v[180:183], v[222:225], v[4:7]
	v_mfma_f32_16x16x32_bf16 v[0:3], v[190:193], v[222:225], v[0:3]
	v_mfma_f32_16x16x32_bf16 v[28:31], v[186:189], v[202:205], v[28:31]
	v_mfma_f32_16x16x32_bf16 v[24:27], v[194:197], v[202:205], v[24:27]
	v_mfma_f32_16x16x32_bf16 v[20:23], v[186:189], v[210:213], v[20:23]
	v_mfma_f32_16x16x32_bf16 v[16:19], v[194:197], v[210:213], v[16:19]
	v_mfma_f32_16x16x32_bf16 v[12:15], v[186:189], v[218:221], v[12:15]
	v_mfma_f32_16x16x32_bf16 v[8:11], v[194:197], v[218:221], v[8:11]
	v_mfma_f32_16x16x32_bf16 v[4:7], v[186:189], v[226:229], v[4:7]
	v_mfma_f32_16x16x32_bf16 v[0:3], v[194:197], v[226:229], v[0:3]
	s_barrier
	s_add_i32 s52, 0, 0x18000
	v_add_u32_e32 v158, s52, v161
	s_add_i32 s53, 0, 0x1c000
	ds_read_b128 v[128:131], v158
	ds_read_b128 v[132:135], v158 offset:1024
	ds_read_b128 v[172:175], v158 offset:2048
	ds_read_b128 v[176:179], v158 offset:3072
	v_add_u32_e32 v158, s53, v161
	ds_read_b128 v[180:183], v158
	ds_read_b128 v[186:189], v158 offset:1024
	ds_read_b128 v[190:193], v158 offset:2048
	ds_read_b128 v[194:197], v158 offset:3072
	s_add_u32 s28, s28, 0x40000
	s_addc_u32 s29, s29, 0
	s_mov_b32 m0, s36
	ds_read_b128 v[198:201], v167 offset:32768
	ds_read_b128 v[202:205], v167 offset:33792
	ds_read_b128 v[206:209], v167 offset:34816
	ds_read_b128 v[210:213], v167 offset:35840
	ds_read_b128 v[214:217], v167 offset:36864
	ds_read_b128 v[218:221], v167 offset:37888
	ds_read_b128 v[222:225], v167 offset:38912
	ds_read_b128 v[226:229], v167 offset:39936
	global_load_lds_dwordx4 v136, s[28:29]
	s_mov_b32 m0, s37
	s_nop 0
	global_load_lds_dwordx4 v140, s[28:29]
	s_waitcnt vmcnt(8)
	s_waitcnt lgkmcnt(0)
	s_barrier
	s_waitcnt lgkmcnt(0)
	v_mfma_f32_16x16x32_bf16 v[124:127], v[128:131], v[198:201], v[124:127]
	v_mfma_f32_16x16x32_bf16 v[120:123], v[172:175], v[198:201], v[120:123]
	v_mfma_f32_16x16x32_bf16 v[116:119], v[128:131], v[206:209], v[116:119]
	v_mfma_f32_16x16x32_bf16 v[112:115], v[172:175], v[206:209], v[112:115]
	v_mfma_f32_16x16x32_bf16 v[108:111], v[128:131], v[214:217], v[108:111]
	v_mfma_f32_16x16x32_bf16 v[104:107], v[172:175], v[214:217], v[104:107]
	v_mfma_f32_16x16x32_bf16 v[100:103], v[128:131], v[222:225], v[100:103]
	v_mfma_f32_16x16x32_bf16 v[96:99], v[172:175], v[222:225], v[96:99]
	v_mfma_f32_16x16x32_bf16 v[124:127], v[132:135], v[202:205], v[124:127]
	v_mfma_f32_16x16x32_bf16 v[120:123], v[176:179], v[202:205], v[120:123]
	v_mfma_f32_16x16x32_bf16 v[116:119], v[132:135], v[210:213], v[116:119]
	v_mfma_f32_16x16x32_bf16 v[112:115], v[176:179], v[210:213], v[112:115]
	v_mfma_f32_16x16x32_bf16 v[108:111], v[132:135], v[218:221], v[108:111]
	v_mfma_f32_16x16x32_bf16 v[104:107], v[176:179], v[218:221], v[104:107]
	v_mfma_f32_16x16x32_bf16 v[100:103], v[132:135], v[226:229], v[100:103]
	v_mfma_f32_16x16x32_bf16 v[96:99], v[176:179], v[226:229], v[96:99]
	v_mfma_f32_16x16x32_bf16 v[72:75], v[180:183], v[198:201], v[72:75]
	v_mfma_f32_16x16x32_bf16 v[64:67], v[190:193], v[198:201], v[64:67]
	v_mfma_f32_16x16x32_bf16 v[56:59], v[180:183], v[206:209], v[56:59]
	v_mfma_f32_16x16x32_bf16 v[48:51], v[190:193], v[206:209], v[48:51]
	v_mfma_f32_16x16x32_bf16 v[44:47], v[180:183], v[214:217], v[44:47]
	v_mfma_f32_16x16x32_bf16 v[40:43], v[190:193], v[214:217], v[40:43]
	v_mfma_f32_16x16x32_bf16 v[36:39], v[180:183], v[222:225], v[36:39]
	v_mfma_f32_16x16x32_bf16 v[32:35], v[190:193], v[222:225], v[32:35]
	v_mfma_f32_16x16x32_bf16 v[72:75], v[186:189], v[202:205], v[72:75]
	v_mfma_f32_16x16x32_bf16 v[64:67], v[194:197], v[202:205], v[64:67]
	v_mfma_f32_16x16x32_bf16 v[56:59], v[186:189], v[210:213], v[56:59]
	v_mfma_f32_16x16x32_bf16 v[48:51], v[194:197], v[210:213], v[48:51]
	v_mfma_f32_16x16x32_bf16 v[44:47], v[186:189], v[218:221], v[44:47]
	v_mfma_f32_16x16x32_bf16 v[40:43], v[194:197], v[218:221], v[40:43]
	v_mfma_f32_16x16x32_bf16 v[36:39], v[186:189], v[226:229], v[36:39]
	v_mfma_f32_16x16x32_bf16 v[32:35], v[194:197], v[226:229], v[32:35]
	s_barrier
	s_add_i32 s28, s52, s34
	s_mov_b32 m0, s28
	ds_read_b128 v[198:201], v167 offset:49152
	ds_read_b128 v[202:205], v167 offset:50176
	ds_read_b128 v[206:209], v167 offset:51200
	ds_read_b128 v[210:213], v167 offset:52224
	ds_read_b128 v[214:217], v167 offset:53248
	ds_read_b128 v[218:221], v167 offset:54272
	ds_read_b128 v[222:225], v167 offset:55296
	ds_read_b128 v[226:229], v167 offset:56320
	global_load_lds_dwordx4 v138, s[98:99]
	s_add_i32 m0, s28, 0x2000
	s_add_u32 s26, s26, 0x40080
	s_addc_u32 s27, s27, 0
	s_add_i32 s28, s53, s34
	global_load_lds_dwordx4 v142, s[98:99]
	s_mov_b32 m0, s28
	s_nop 0
	global_load_lds_dwordx4 v138, s[26:27]
	s_add_i32 m0, s28, 0x2000
	s_nop 0
	global_load_lds_dwordx4 v142, s[26:27]
	s_mov_b32 m0, s39
	s_nop 0
	global_load_lds_dwordx4 v136, s[100:101]
	s_mov_b32 m0, s40
	s_nop 0
	global_load_lds_dwordx4 v140, s[100:101]
	s_waitcnt vmcnt(8)
	s_waitcnt lgkmcnt(0)
	s_barrier
	s_waitcnt lgkmcnt(0)
	v_mfma_f32_16x16x32_bf16 v[92:95], v[128:131], v[198:201], v[92:95]
	v_mfma_f32_16x16x32_bf16 v[88:91], v[172:175], v[198:201], v[88:91]
	v_mfma_f32_16x16x32_bf16 v[84:87], v[128:131], v[206:209], v[84:87]
	v_mfma_f32_16x16x32_bf16 v[80:83], v[172:175], v[206:209], v[80:83]
	v_mfma_f32_16x16x32_bf16 v[76:79], v[128:131], v[214:217], v[76:79]
	v_mfma_f32_16x16x32_bf16 v[68:71], v[172:175], v[214:217], v[68:71]
	v_mfma_f32_16x16x32_bf16 v[60:63], v[128:131], v[222:225], v[60:63]
	v_mfma_f32_16x16x32_bf16 v[52:55], v[172:175], v[222:225], v[52:55]
	v_mfma_f32_16x16x32_bf16 v[92:95], v[132:135], v[202:205], v[92:95]
	v_mfma_f32_16x16x32_bf16 v[88:91], v[176:179], v[202:205], v[88:91]
	v_mfma_f32_16x16x32_bf16 v[84:87], v[132:135], v[210:213], v[84:87]
	v_mfma_f32_16x16x32_bf16 v[80:83], v[176:179], v[210:213], v[80:83]
	v_mfma_f32_16x16x32_bf16 v[76:79], v[132:135], v[218:221], v[76:79]
	v_mfma_f32_16x16x32_bf16 v[68:71], v[176:179], v[218:221], v[68:71]
	v_mfma_f32_16x16x32_bf16 v[60:63], v[132:135], v[226:229], v[60:63]
	v_mfma_f32_16x16x32_bf16 v[52:55], v[176:179], v[226:229], v[52:55]
	v_mfma_f32_16x16x32_bf16 v[28:31], v[180:183], v[198:201], v[28:31]
	v_mfma_f32_16x16x32_bf16 v[24:27], v[190:193], v[198:201], v[24:27]
	v_mfma_f32_16x16x32_bf16 v[20:23], v[180:183], v[206:209], v[20:23]
	v_mfma_f32_16x16x32_bf16 v[16:19], v[190:193], v[206:209], v[16:19]
	v_mfma_f32_16x16x32_bf16 v[12:15], v[180:183], v[214:217], v[12:15]
	v_mfma_f32_16x16x32_bf16 v[8:11], v[190:193], v[214:217], v[8:11]
	v_mfma_f32_16x16x32_bf16 v[4:7], v[180:183], v[222:225], v[4:7]
	v_mfma_f32_16x16x32_bf16 v[0:3], v[190:193], v[222:225], v[0:3]
	v_mfma_f32_16x16x32_bf16 v[28:31], v[186:189], v[202:205], v[28:31]
	v_mfma_f32_16x16x32_bf16 v[24:27], v[194:197], v[202:205], v[24:27]
	v_mfma_f32_16x16x32_bf16 v[20:23], v[186:189], v[210:213], v[20:23]
	v_mfma_f32_16x16x32_bf16 v[16:19], v[194:197], v[210:213], v[16:19]
	v_mfma_f32_16x16x32_bf16 v[12:15], v[186:189], v[218:221], v[12:15]
	v_mfma_f32_16x16x32_bf16 v[8:11], v[194:197], v[218:221], v[8:11]
	v_mfma_f32_16x16x32_bf16 v[4:7], v[186:189], v[226:229], v[4:7]
	v_mfma_f32_16x16x32_bf16 v[0:3], v[194:197], v[226:229], v[0:3]
	s_barrier
	s_add_i32 s51, s51, 2
	s_add_u32 s24, s24, 0x100
	s_addc_u32 s25, s25, 0
	s_add_u32 s49, s49, 0x100
	s_addc_u32 s50, s50, 0
	s_cmp_gt_u32 s51, 13
	s_cbranch_scc0 .LBB0_1727
	s_and_b64 vcc, exec, s[12:13]
	s_cbranch_vccz .LBB0_1730
	s_barrier

.LBB0_1734:
	s_cmp_gt_i32 s79, 14
	s_cselect_b64 s[4:5], -1, 0
	s_and_b64 s[0:1], s[0:1], s[4:5]
	s_andn2_b64 vcc, exec, s[0:1]
	s_cbranch_vccnz .LBB0_1788
	s_waitcnt vmcnt(0) lgkmcnt(0)
	s_barrier
	v_readlane_b32 s21, v242, 63
	s_add_u32 s21, s21, 1
	v_readlane_b32 s12, v242, 1
	v_readlane_b32 s13, v242, 2
	s_mov_b64 s[14:15], exec
	s_and_b64 s[12:13], s[14:15], s[12:13]
	s_mov_b64 exec, s[12:13]
	s_cbranch_execz .Lxb_done_11
	v_mov_b32_e32 v0, 0x21020
	ds_read2_b32 v[2:3], v0 offset1:1
	s_lshl_b32 s16, s84, 8
	s_add_u32 s16, s76, s16
	s_addc_u32 s17, s77, 0
	v_mov_b32_e32 v1, 0x1000
	v_mov_b32_e32 v4, 1
	global_atomic_add v5, v1, v4, s[16:17] offset:1024 sc0
	buffer_inv sc1
	s_waitcnt vmcnt(0) lgkmcnt(0)
	v_readfirstlane_b32 s18, v5
	v_readfirstlane_b32 s19, v2
	v_readfirstlane_b32 s20, v3
	v_mov_b32_e32 v1, 0x3000
	s_mul_i32 s22, s19, s21
	s_mul_i32 s23, s20, s21
	s_add_u32 s18, s18, 1
	s_cmp_lg_u32 s18, s22
	s_cbranch_scc1 .Lxb_spin_11
	buffer_wbl2 sc1
	s_waitcnt vmcnt(0)
	global_atomic_add v1, v4, s[76:77] offset:1024

.LBB0_1812:
	s_cmp_gt_i32 s79, 15
	s_cselect_b64 s[4:5], -1, 0
	s_and_b64 s[0:1], s[0:1], s[4:5]
	s_andn2_b64 vcc, exec, s[0:1]
	s_cbranch_vccnz .LBB0_1866
	s_waitcnt vmcnt(0) lgkmcnt(0)
	s_barrier
	v_readlane_b32 s21, v242, 63
	s_add_u32 s21, s21, 1
	v_readlane_b32 s12, v242, 1
	v_readlane_b32 s13, v242, 2
	s_mov_b64 s[14:15], exec
	s_and_b64 s[12:13], s[14:15], s[12:13]
	s_mov_b64 exec, s[12:13]
	s_cbranch_execz .Lxb_done_12
	v_mov_b32_e32 v0, 0x21020
	ds_read2_b32 v[2:3], v0 offset1:1
	s_lshl_b32 s16, s84, 8
	s_add_u32 s16, s76, s16
	s_addc_u32 s17, s77, 0
	v_mov_b32_e32 v1, 0x1000
	v_mov_b32_e32 v4, 1
	global_atomic_add v5, v1, v4, s[16:17] offset:1024 sc0
	buffer_inv sc1
	s_waitcnt vmcnt(0) lgkmcnt(0)
	v_readfirstlane_b32 s18, v5
	v_readfirstlane_b32 s19, v2
	v_readfirstlane_b32 s20, v3
	v_mov_b32_e32 v1, 0x3000
	s_mul_i32 s22, s19, s21
	s_mul_i32 s23, s20, s21
	s_add_u32 s18, s18, 1
	s_cmp_lg_u32 s18, s22
	s_cbranch_scc1 .Lxb_spin_12
	buffer_wbl2 sc1
	s_waitcnt vmcnt(0)
	global_atomic_add v1, v4, s[76:77] offset:1024

.LBB0_1886:
	ds_read_b128 v[128:131], v188
	ds_read_b128 v[132:135], v188 offset:1024
	ds_read_b128 v[136:139], v188 offset:2048
	ds_read_b128 v[140:143], v188 offset:3072
	ds_read_b128 v[144:147], v189
	ds_read_b128 v[148:151], v189 offset:1024
	ds_read_b128 v[172:175], v189 offset:2048
	ds_read_b128 v[176:179], v189 offset:3072
	s_add_u32 s30, s28, 0xfffc0080
	s_addc_u32 s31, s29, -1
	s_cmp_eq_u32 s53, 12
	s_cselect_b32 s35, s17, s31
	s_cselect_b32 s34, s25, s30
	s_cselect_b32 s31, s19, s52
	s_cselect_b32 s30, s27, s51
	s_add_i32 m0, s39, 0xc000
	ds_read_b128 v[180:183], v190
	ds_read_b128 v[192:195], v190 offset:1024
	ds_read_b128 v[196:199], v190 offset:2048
	ds_read_b128 v[200:203], v190 offset:3072
	ds_read_b128 v[204:207], v190 offset:4096
	ds_read_b128 v[208:211], v190 offset:5120
	ds_read_b128 v[212:215], v190 offset:6144
	ds_read_b128 v[216:219], v190 offset:7168
	global_load_lds_dwordx4 v164, s[28:29]
	s_add_i32 m0, s39, 0xe000
	s_nop 0
	global_load_lds_dwordx4 v166, s[28:29]
	s_waitcnt vmcnt(8)
	s_waitcnt lgkmcnt(0)
	s_barrier
	s_waitcnt lgkmcnt(0)
	v_mfma_f32_16x16x32_bf16 v[124:127], v[128:131], v[180:183], v[124:127]
	v_mfma_f32_16x16x32_bf16 v[120:123], v[136:139], v[180:183], v[120:123]
	v_mfma_f32_16x16x32_bf16 v[108:111], v[128:131], v[196:199], v[108:111]
	v_mfma_f32_16x16x32_bf16 v[104:107], v[136:139], v[196:199], v[104:107]
	v_mfma_f32_16x16x32_bf16 v[92:95], v[128:131], v[204:207], v[92:95]
	v_mfma_f32_16x16x32_bf16 v[88:91], v[136:139], v[204:207], v[88:91]
	v_mfma_f32_16x16x32_bf16 v[76:79], v[128:131], v[212:215], v[76:79]
	v_mfma_f32_16x16x32_bf16 v[72:75], v[136:139], v[212:215], v[72:75]
	v_mfma_f32_16x16x32_bf16 v[124:127], v[132:135], v[192:195], v[124:127]
	v_mfma_f32_16x16x32_bf16 v[120:123], v[140:143], v[192:195], v[120:123]
	v_mfma_f32_16x16x32_bf16 v[108:111], v[132:135], v[200:203], v[108:111]
	v_mfma_f32_16x16x32_bf16 v[104:107], v[140:143], v[200:203], v[104:107]
	v_mfma_f32_16x16x32_bf16 v[92:95], v[132:135], v[208:211], v[92:95]
	v_mfma_f32_16x16x32_bf16 v[88:91], v[140:143], v[208:211], v[88:91]
	v_mfma_f32_16x16x32_bf16 v[76:79], v[132:135], v[216:219], v[76:79]
	v_mfma_f32_16x16x32_bf16 v[72:75], v[140:143], v[216:219], v[72:75]
	v_mfma_f32_16x16x32_bf16 v[116:119], v[144:147], v[180:183], v[116:119]
	v_mfma_f32_16x16x32_bf16 v[112:115], v[172:175], v[180:183], v[112:115]
	v_mfma_f32_16x16x32_bf16 v[100:103], v[144:147], v[196:199], v[100:103]
	v_mfma_f32_16x16x32_bf16 v[96:99], v[172:175], v[196:199], v[96:99]
	v_mfma_f32_16x16x32_bf16 v[84:87], v[144:147], v[204:207], v[84:87]
	v_mfma_f32_16x16x32_bf16 v[80:83], v[172:175], v[204:207], v[80:83]
	v_mfma_f32_16x16x32_bf16 v[68:71], v[144:147], v[212:215], v[68:71]
	v_mfma_f32_16x16x32_bf16 v[64:67], v[172:175], v[212:215], v[64:67]
	v_mfma_f32_16x16x32_bf16 v[116:119], v[148:151], v[192:195], v[116:119]
	v_mfma_f32_16x16x32_bf16 v[112:115], v[176:179], v[192:195], v[112:115]
	v_mfma_f32_16x16x32_bf16 v[100:103], v[148:151], v[200:203], v[100:103]
	v_mfma_f32_16x16x32_bf16 v[96:99], v[176:179], v[200:203], v[96:99]
	v_mfma_f32_16x16x32_bf16 v[84:87], v[148:151], v[208:211], v[84:87]
	v_mfma_f32_16x16x32_bf16 v[80:83], v[176:179], v[208:211], v[80:83]
	v_mfma_f32_16x16x32_bf16 v[68:71], v[148:151], v[216:219], v[68:71]
	v_mfma_f32_16x16x32_bf16 v[64:67], v[176:179], v[216:219], v[64:67]
	s_barrier
	s_add_i32 s54, s49, s38
	s_mov_b32 m0, s54
	ds_read_b128 v[180:183], v190 offset:16384
	ds_read_b128 v[192:195], v190 offset:17408
	ds_read_b128 v[196:199], v190 offset:18432
	ds_read_b128 v[200:203], v190 offset:19456
	ds_read_b128 v[204:207], v190 offset:20480
	ds_read_b128 v[208:211], v190 offset:21504
	ds_read_b128 v[212:215], v190 offset:22528
	ds_read_b128 v[216:219], v190 offset:23552
	global_load_lds_dwordx4 v154, s[30:31]
	s_add_i32 m0, s54, 0x2000
	s_add_u32 s54, s30, 0x40000
	s_addc_u32 s55, s31, 0
	s_add_i32 s56, s50, s38
	global_load_lds_dwordx4 v158, s[30:31]
	s_mov_b32 m0, s56
	global_load_lds_dwordx4 v154, s[54:55]
	s_add_i32 m0, s56, 0x2000
	s_nop 0
	global_load_lds_dwordx4 v158, s[54:55]
	s_mov_b32 m0, s39
	s_nop 0
	global_load_lds_dwordx4 v152, s[34:35]
	s_mov_b32 m0, s40
	s_nop 0
	global_load_lds_dwordx4 v156, s[34:35]
	s_add_u32 s98, s30, s12
	s_addc_u32 s99, s31, s13
	s_add_u32 s100, s34, s12
	s_addc_u32 s101, s35, s13
	s_waitcnt vmcnt(8)
	s_waitcnt lgkmcnt(0)
	s_barrier
	s_waitcnt lgkmcnt(0)
	v_mfma_f32_16x16x32_bf16 v[60:63], v[128:131], v[180:183], v[60:63]
	v_mfma_f32_16x16x32_bf16 v[56:59], v[136:139], v[180:183], v[56:59]
	v_mfma_f32_16x16x32_bf16 v[44:47], v[128:131], v[196:199], v[44:47]
	v_mfma_f32_16x16x32_bf16 v[40:43], v[136:139], v[196:199], v[40:43]
	v_mfma_f32_16x16x32_bf16 v[28:31], v[128:131], v[204:207], v[28:31]
	v_mfma_f32_16x16x32_bf16 v[24:27], v[136:139], v[204:207], v[24:27]
	v_mfma_f32_16x16x32_bf16 v[12:15], v[128:131], v[212:215], v[12:15]
	v_mfma_f32_16x16x32_bf16 v[8:11], v[136:139], v[212:215], v[8:11]
	v_mfma_f32_16x16x32_bf16 v[60:63], v[132:135], v[192:195], v[60:63]
	v_mfma_f32_16x16x32_bf16 v[56:59], v[140:143], v[192:195], v[56:59]
	v_mfma_f32_16x16x32_bf16 v[44:47], v[132:135], v[200:203], v[44:47]
	v_mfma_f32_16x16x32_bf16 v[40:43], v[140:143], v[200:203], v[40:43]
	v_mfma_f32_16x16x32_bf16 v[28:31], v[132:135], v[208:211], v[28:31]
	v_mfma_f32_16x16x32_bf16 v[24:27], v[140:143], v[208:211], v[24:27]
	v_mfma_f32_16x16x32_bf16 v[12:15], v[132:135], v[216:219], v[12:15]
	v_mfma_f32_16x16x32_bf16 v[8:11], v[140:143], v[216:219], v[8:11]
	v_mfma_f32_16x16x32_bf16 v[52:55], v[144:147], v[180:183], v[52:55]
	v_mfma_f32_16x16x32_bf16 v[48:51], v[172:175], v[180:183], v[48:51]
	v_mfma_f32_16x16x32_bf16 v[36:39], v[144:147], v[196:199], v[36:39]
	v_mfma_f32_16x16x32_bf16 v[32:35], v[172:175], v[196:199], v[32:35]
	v_mfma_f32_16x16x32_bf16 v[20:23], v[144:147], v[204:207], v[20:23]
	v_mfma_f32_16x16x32_bf16 v[16:19], v[172:175], v[204:207], v[16:19]
	v_mfma_f32_16x16x32_bf16 v[4:7], v[144:147], v[212:215], v[4:7]
	v_mfma_f32_16x16x32_bf16 v[0:3], v[172:175], v[212:215], v[0:3]
	v_mfma_f32_16x16x32_bf16 v[52:55], v[148:151], v[192:195], v[52:55]
	v_mfma_f32_16x16x32_bf16 v[48:51], v[176:179], v[192:195], v[48:51]
	v_mfma_f32_16x16x32_bf16 v[36:39], v[148:151], v[200:203], v[36:39]
	v_mfma_f32_16x16x32_bf16 v[32:35], v[176:179], v[200:203], v[32:35]
	v_mfma_f32_16x16x32_bf16 v[20:23], v[148:151], v[208:211], v[20:23]
	v_mfma_f32_16x16x32_bf16 v[16:19], v[176:179], v[208:211], v[16:19]
	v_mfma_f32_16x16x32_bf16 v[4:7], v[148:151], v[216:219], v[4:7]
	v_mfma_f32_16x16x32_bf16 v[0:3], v[176:179], v[216:219], v[0:3]
	s_barrier
	s_add_i32 s54, 0, 0x18000
	s_add_i32 s55, 0, 0x1c000
	v_add_u32_e32 v140, s54, v184
	v_add_u32_e32 v176, s55, v184
	ds_read_b128 v[128:131], v140
	ds_read_b128 v[132:135], v140 offset:1024
	ds_read_b128 v[136:139], v140 offset:2048
	ds_read_b128 v[140:143], v140 offset:3072
	ds_read_b128 v[144:147], v176
	ds_read_b128 v[148:151], v176 offset:1024
	ds_read_b128 v[172:175], v176 offset:2048
	ds_read_b128 v[176:179], v176 offset:3072
	s_add_u32 s34, s34, 0x40000
	s_addc_u32 s35, s35, 0
	s_mov_b32 m0, s41
	ds_read_b128 v[180:183], v190 offset:32768
	ds_read_b128 v[192:195], v190 offset:33792
	ds_read_b128 v[196:199], v190 offset:34816
	ds_read_b128 v[200:203], v190 offset:35840
	ds_read_b128 v[204:207], v190 offset:36864
	ds_read_b128 v[208:211], v190 offset:37888
	ds_read_b128 v[212:215], v190 offset:38912
	ds_read_b128 v[216:219], v190 offset:39936
	global_load_lds_dwordx4 v152, s[34:35]
	s_mov_b32 m0, s42
	s_nop 0
	global_load_lds_dwordx4 v156, s[34:35]
	s_waitcnt vmcnt(8)
	s_waitcnt lgkmcnt(0)
	s_barrier
	s_waitcnt lgkmcnt(0)
	v_mfma_f32_16x16x32_bf16 v[124:127], v[128:131], v[180:183], v[124:127]
	v_mfma_f32_16x16x32_bf16 v[120:123], v[136:139], v[180:183], v[120:123]
	v_mfma_f32_16x16x32_bf16 v[108:111], v[128:131], v[196:199], v[108:111]
	v_mfma_f32_16x16x32_bf16 v[104:107], v[136:139], v[196:199], v[104:107]
	v_mfma_f32_16x16x32_bf16 v[92:95], v[128:131], v[204:207], v[92:95]
	v_mfma_f32_16x16x32_bf16 v[88:91], v[136:139], v[204:207], v[88:91]
	v_mfma_f32_16x16x32_bf16 v[76:79], v[128:131], v[212:215], v[76:79]
	v_mfma_f32_16x16x32_bf16 v[72:75], v[136:139], v[212:215], v[72:75]
	v_mfma_f32_16x16x32_bf16 v[124:127], v[132:135], v[192:195], v[124:127]
	v_mfma_f32_16x16x32_bf16 v[120:123], v[140:143], v[192:195], v[120:123]
	v_mfma_f32_16x16x32_bf16 v[108:111], v[132:135], v[200:203], v[108:111]
	v_mfma_f32_16x16x32_bf16 v[104:107], v[140:143], v[200:203], v[104:107]
	v_mfma_f32_16x16x32_bf16 v[92:95], v[132:135], v[208:211], v[92:95]
	v_mfma_f32_16x16x32_bf16 v[88:91], v[140:143], v[208:211], v[88:91]
	v_mfma_f32_16x16x32_bf16 v[76:79], v[132:135], v[216:219], v[76:79]
	v_mfma_f32_16x16x32_bf16 v[72:75], v[140:143], v[216:219], v[72:75]
	v_mfma_f32_16x16x32_bf16 v[116:119], v[144:147], v[180:183], v[116:119]
	v_mfma_f32_16x16x32_bf16 v[112:115], v[172:175], v[180:183], v[112:115]
	v_mfma_f32_16x16x32_bf16 v[100:103], v[144:147], v[196:199], v[100:103]
	v_mfma_f32_16x16x32_bf16 v[96:99], v[172:175], v[196:199], v[96:99]
	v_mfma_f32_16x16x32_bf16 v[84:87], v[144:147], v[204:207], v[84:87]
	v_mfma_f32_16x16x32_bf16 v[80:83], v[172:175], v[204:207], v[80:83]
	v_mfma_f32_16x16x32_bf16 v[68:71], v[144:147], v[212:215], v[68:71]
	v_mfma_f32_16x16x32_bf16 v[64:67], v[172:175], v[212:215], v[64:67]
	v_mfma_f32_16x16x32_bf16 v[116:119], v[148:151], v[192:195], v[116:119]
	v_mfma_f32_16x16x32_bf16 v[112:115], v[176:179], v[192:195], v[112:115]
	v_mfma_f32_16x16x32_bf16 v[100:103], v[148:151], v[200:203], v[100:103]
	v_mfma_f32_16x16x32_bf16 v[96:99], v[176:179], v[200:203], v[96:99]
	v_mfma_f32_16x16x32_bf16 v[84:87], v[148:151], v[208:211], v[84:87]
	v_mfma_f32_16x16x32_bf16 v[80:83], v[176:179], v[208:211], v[80:83]
	v_mfma_f32_16x16x32_bf16 v[68:71], v[148:151], v[216:219], v[68:71]
	v_mfma_f32_16x16x32_bf16 v[64:67], v[176:179], v[216:219], v[64:67]
	s_barrier
	s_add_i32 s34, s54, s38
	s_mov_b32 m0, s34
	ds_read_b128 v[180:183], v190 offset:49152
	ds_read_b128 v[192:195], v190 offset:50176
	ds_read_b128 v[196:199], v190 offset:51200
	ds_read_b128 v[200:203], v190 offset:52224
	ds_read_b128 v[204:207], v190 offset:53248
	ds_read_b128 v[208:211], v190 offset:54272
	ds_read_b128 v[212:215], v190 offset:55296
	ds_read_b128 v[216:219], v190 offset:56320
	global_load_lds_dwordx4 v154, s[98:99]
	s_add_i32 m0, s34, 0x2000
	s_add_u32 s30, s30, 0x40080
	s_addc_u32 s31, s31, 0
	s_add_i32 s34, s55, s38
	global_load_lds_dwordx4 v158, s[98:99]
	s_mov_b32 m0, s34
	s_nop 0
	global_load_lds_dwordx4 v154, s[30:31]
	s_add_i32 m0, s34, 0x2000
	s_nop 0
	global_load_lds_dwordx4 v158, s[30:31]
	s_mov_b32 m0, s44
	s_nop 0
	global_load_lds_dwordx4 v152, s[100:101]
	s_mov_b32 m0, s45
	s_nop 0
	global_load_lds_dwordx4 v156, s[100:101]
	s_waitcnt vmcnt(8)
	s_waitcnt lgkmcnt(0)
	s_barrier
	s_waitcnt lgkmcnt(0)
	v_mfma_f32_16x16x32_bf16 v[60:63], v[128:131], v[180:183], v[60:63]
	v_mfma_f32_16x16x32_bf16 v[56:59], v[136:139], v[180:183], v[56:59]
	v_mfma_f32_16x16x32_bf16 v[44:47], v[128:131], v[196:199], v[44:47]
	v_mfma_f32_16x16x32_bf16 v[40:43], v[136:139], v[196:199], v[40:43]
	v_mfma_f32_16x16x32_bf16 v[28:31], v[128:131], v[204:207], v[28:31]
	v_mfma_f32_16x16x32_bf16 v[24:27], v[136:139], v[204:207], v[24:27]
	v_mfma_f32_16x16x32_bf16 v[12:15], v[128:131], v[212:215], v[12:15]
	v_mfma_f32_16x16x32_bf16 v[8:11], v[136:139], v[212:215], v[8:11]
	v_mfma_f32_16x16x32_bf16 v[60:63], v[132:135], v[192:195], v[60:63]
	v_mfma_f32_16x16x32_bf16 v[56:59], v[140:143], v[192:195], v[56:59]
	v_mfma_f32_16x16x32_bf16 v[44:47], v[132:135], v[200:203], v[44:47]
	v_mfma_f32_16x16x32_bf16 v[40:43], v[140:143], v[200:203], v[40:43]
	v_mfma_f32_16x16x32_bf16 v[28:31], v[132:135], v[208:211], v[28:31]
	v_mfma_f32_16x16x32_bf16 v[24:27], v[140:143], v[208:211], v[24:27]
	v_mfma_f32_16x16x32_bf16 v[12:15], v[132:135], v[216:219], v[12:15]
	v_mfma_f32_16x16x32_bf16 v[8:11], v[140:143], v[216:219], v[8:11]
	v_mfma_f32_16x16x32_bf16 v[52:55], v[144:147], v[180:183], v[52:55]
	v_mfma_f32_16x16x32_bf16 v[48:51], v[172:175], v[180:183], v[48:51]
	v_mfma_f32_16x16x32_bf16 v[36:39], v[144:147], v[196:199], v[36:39]
	v_mfma_f32_16x16x32_bf16 v[32:35], v[172:175], v[196:199], v[32:35]
	v_mfma_f32_16x16x32_bf16 v[20:23], v[144:147], v[204:207], v[20:23]
	v_mfma_f32_16x16x32_bf16 v[16:19], v[172:175], v[204:207], v[16:19]
	v_mfma_f32_16x16x32_bf16 v[4:7], v[144:147], v[212:215], v[4:7]
	v_mfma_f32_16x16x32_bf16 v[0:3], v[172:175], v[212:215], v[0:3]
	v_mfma_f32_16x16x32_bf16 v[52:55], v[148:151], v[192:195], v[52:55]
	v_mfma_f32_16x16x32_bf16 v[48:51], v[176:179], v[192:195], v[48:51]
	v_mfma_f32_16x16x32_bf16 v[36:39], v[148:151], v[200:203], v[36:39]
	v_mfma_f32_16x16x32_bf16 v[32:35], v[176:179], v[200:203], v[32:35]
	v_mfma_f32_16x16x32_bf16 v[20:23], v[148:151], v[208:211], v[20:23]
	v_mfma_f32_16x16x32_bf16 v[16:19], v[176:179], v[208:211], v[16:19]
	v_mfma_f32_16x16x32_bf16 v[4:7], v[148:151], v[216:219], v[4:7]
	v_mfma_f32_16x16x32_bf16 v[0:3], v[176:179], v[216:219], v[0:3]
	s_barrier
	s_add_i32 s53, s53, 2
	s_add_u32 s28, s28, 0x100
	s_addc_u32 s29, s29, 0
	s_add_u32 s51, s51, 0x100
	s_addc_u32 s52, s52, 0
	s_cmp_gt_u32 s53, 13
	s_cbranch_scc0 .LBB0_1886
	s_and_b64 vcc, exec, s[14:15]
	s_cbranch_vccz .LBB0_1889
	s_barrier

.LBB0_1911:
	s_cmp_gt_i32 s79, 16
	s_cselect_b64 s[4:5], -1, 0
	s_and_b64 s[0:1], s[0:1], s[4:5]
	s_andn2_b64 vcc, exec, s[0:1]
	s_cbranch_vccnz .LBB0_1965
	s_waitcnt vmcnt(0) lgkmcnt(0)
	s_barrier
	v_readlane_b32 s21, v242, 63
	s_add_u32 s21, s21, 1
	v_readlane_b32 s12, v242, 1
	v_readlane_b32 s13, v242, 2
	s_mov_b64 s[14:15], exec
	s_and_b64 s[12:13], s[14:15], s[12:13]
	s_mov_b64 exec, s[12:13]
	s_cbranch_execz .Lxb_done_13
	v_mov_b32_e32 v0, 0x21020
	ds_read2_b32 v[2:3], v0 offset1:1
	s_lshl_b32 s16, s84, 8
	s_add_u32 s16, s76, s16
	s_addc_u32 s17, s77, 0
	v_mov_b32_e32 v1, 0x1000
	v_mov_b32_e32 v4, 1
	global_atomic_add v5, v1, v4, s[16:17] offset:1024 sc0
	buffer_inv sc1
	s_waitcnt vmcnt(0) lgkmcnt(0)
	v_readfirstlane_b32 s18, v5
	v_readfirstlane_b32 s19, v2
	v_readfirstlane_b32 s20, v3
	v_mov_b32_e32 v1, 0x3000
	s_mul_i32 s22, s19, s21
	s_mul_i32 s23, s20, s21
	s_add_u32 s18, s18, 1
	s_cmp_lg_u32 s18, s22
	s_cbranch_scc1 .Lxb_spin_13
	buffer_wbl2 sc1
	s_waitcnt vmcnt(0)
	global_atomic_add v1, v4, s[76:77] offset:1024

.LBB0_1975:
	ds_read_b128 v[144:147], v155
	ds_read_b128 v[160:163], v155 offset:1024
	ds_read_b128 v[164:167], v155 offset:2048
	ds_read_b128 v[168:171], v155 offset:3072
	ds_read_b128 v[172:175], v157
	ds_read_b128 v[176:179], v157 offset:1024
	ds_read_b128 v[180:183], v157 offset:2048
	ds_read_b128 v[186:189], v157 offset:3072
	s_add_u32 s26, s24, 0xfffc0080
	s_addc_u32 s27, s25, -1
	s_cmp_eq_u32 s51, 12
	s_cselect_b32 s29, s15, s27
	s_cselect_b32 s28, s47, s26
	s_cselect_b32 s27, s17, s50
	s_cselect_b32 s26, s48, s49
	s_add_i32 m0, s23, 0xc000
	ds_read_b128 v[190:193], v158
	ds_read_b128 v[194:197], v158 offset:1024
	ds_read_b128 v[198:201], v158 offset:2048
	ds_read_b128 v[202:205], v158 offset:3072
	ds_read_b128 v[206:209], v158 offset:4096
	ds_read_b128 v[210:213], v158 offset:5120
	ds_read_b128 v[214:217], v158 offset:6144
	ds_read_b128 v[218:221], v158 offset:7168
	global_load_lds_dwordx4 v136, s[24:25]
	s_add_i32 m0, s23, 0xe000
	s_nop 0
	global_load_lds_dwordx4 v138, s[24:25]
	s_waitcnt vmcnt(8)
	s_waitcnt lgkmcnt(0)
	s_barrier
	s_waitcnt lgkmcnt(0)
	v_mfma_f32_16x16x32_bf16 v[124:127], v[144:147], v[190:193], v[124:127]
	v_mfma_f32_16x16x32_bf16 v[120:123], v[164:167], v[190:193], v[120:123]
	v_mfma_f32_16x16x32_bf16 v[116:119], v[144:147], v[198:201], v[116:119]
	v_mfma_f32_16x16x32_bf16 v[104:107], v[164:167], v[198:201], v[104:107]
	v_mfma_f32_16x16x32_bf16 v[92:95], v[144:147], v[206:209], v[92:95]
	v_mfma_f32_16x16x32_bf16 v[88:91], v[164:167], v[206:209], v[88:91]
	v_mfma_f32_16x16x32_bf16 v[76:79], v[144:147], v[214:217], v[76:79]
	v_mfma_f32_16x16x32_bf16 v[72:75], v[164:167], v[214:217], v[72:75]
	v_mfma_f32_16x16x32_bf16 v[124:127], v[160:163], v[194:197], v[124:127]
	v_mfma_f32_16x16x32_bf16 v[120:123], v[168:171], v[194:197], v[120:123]
	v_mfma_f32_16x16x32_bf16 v[116:119], v[160:163], v[202:205], v[116:119]
	v_mfma_f32_16x16x32_bf16 v[104:107], v[168:171], v[202:205], v[104:107]
	v_mfma_f32_16x16x32_bf16 v[92:95], v[160:163], v[210:213], v[92:95]
	v_mfma_f32_16x16x32_bf16 v[88:91], v[168:171], v[210:213], v[88:91]
	v_mfma_f32_16x16x32_bf16 v[76:79], v[160:163], v[218:221], v[76:79]
	v_mfma_f32_16x16x32_bf16 v[72:75], v[168:171], v[218:221], v[72:75]
	v_mfma_f32_16x16x32_bf16 v[112:115], v[172:175], v[190:193], v[112:115]
	v_mfma_f32_16x16x32_bf16 v[108:111], v[180:183], v[190:193], v[108:111]
	v_mfma_f32_16x16x32_bf16 v[100:103], v[172:175], v[198:201], v[100:103]
	v_mfma_f32_16x16x32_bf16 v[96:99], v[180:183], v[198:201], v[96:99]
	v_mfma_f32_16x16x32_bf16 v[84:87], v[172:175], v[206:209], v[84:87]
	v_mfma_f32_16x16x32_bf16 v[80:83], v[180:183], v[206:209], v[80:83]
	v_mfma_f32_16x16x32_bf16 v[68:71], v[172:175], v[214:217], v[68:71]
	v_mfma_f32_16x16x32_bf16 v[64:67], v[180:183], v[214:217], v[64:67]
	v_mfma_f32_16x16x32_bf16 v[112:115], v[176:179], v[194:197], v[112:115]
	v_mfma_f32_16x16x32_bf16 v[108:111], v[186:189], v[194:197], v[108:111]
	v_mfma_f32_16x16x32_bf16 v[100:103], v[176:179], v[202:205], v[100:103]
	v_mfma_f32_16x16x32_bf16 v[96:99], v[186:189], v[202:205], v[96:99]
	v_mfma_f32_16x16x32_bf16 v[84:87], v[176:179], v[210:213], v[84:87]
	v_mfma_f32_16x16x32_bf16 v[80:83], v[186:189], v[210:213], v[80:83]
	v_mfma_f32_16x16x32_bf16 v[68:71], v[176:179], v[218:221], v[68:71]
	v_mfma_f32_16x16x32_bf16 v[64:67], v[186:189], v[218:221], v[64:67]
	s_barrier
	s_add_i32 s52, s43, s31
	s_mov_b32 m0, s52
	ds_read_b128 v[190:193], v158 offset:16384
	ds_read_b128 v[194:197], v158 offset:17408
	ds_read_b128 v[198:201], v158 offset:18432
	ds_read_b128 v[202:205], v158 offset:19456
	ds_read_b128 v[206:209], v158 offset:20480
	ds_read_b128 v[210:213], v158 offset:21504
	ds_read_b128 v[214:217], v158 offset:22528
	ds_read_b128 v[218:221], v158 offset:23552
	global_load_lds_dwordx4 v132, s[26:27]
	s_add_i32 m0, s52, 0x2000
	s_add_u32 s52, s26, 0x40000
	s_addc_u32 s53, s27, 0
	s_add_i32 s54, s44, s31
	global_load_lds_dwordx4 v128, s[26:27]
	s_mov_b32 m0, s54
	global_load_lds_dwordx4 v132, s[52:53]
	s_add_i32 m0, s54, 0x2000
	s_nop 0
	global_load_lds_dwordx4 v128, s[52:53]
	s_mov_b32 m0, s23
	s_nop 0
	global_load_lds_dwordx4 v134, s[28:29]
	s_mov_b32 m0, s35
	s_nop 0
	global_load_lds_dwordx4 v130, s[28:29]
	s_add_u32 s98, s26, s10
	s_addc_u32 s99, s27, s11
	s_add_u32 s100, s28, s10
	s_addc_u32 s101, s29, s11
	s_waitcnt vmcnt(8)
	s_waitcnt lgkmcnt(0)
	s_barrier
	s_waitcnt lgkmcnt(0)
	v_mfma_f32_16x16x32_bf16 v[60:63], v[144:147], v[190:193], v[60:63]
	v_mfma_f32_16x16x32_bf16 v[56:59], v[164:167], v[190:193], v[56:59]
	v_mfma_f32_16x16x32_bf16 v[44:47], v[144:147], v[198:201], v[44:47]
	v_mfma_f32_16x16x32_bf16 v[40:43], v[164:167], v[198:201], v[40:43]
	v_mfma_f32_16x16x32_bf16 v[28:31], v[144:147], v[206:209], v[28:31]
	v_mfma_f32_16x16x32_bf16 v[24:27], v[164:167], v[206:209], v[24:27]
	v_mfma_f32_16x16x32_bf16 v[12:15], v[144:147], v[214:217], v[12:15]
	v_mfma_f32_16x16x32_bf16 v[8:11], v[164:167], v[214:217], v[8:11]
	v_mfma_f32_16x16x32_bf16 v[60:63], v[160:163], v[194:197], v[60:63]
	v_mfma_f32_16x16x32_bf16 v[56:59], v[168:171], v[194:197], v[56:59]
	v_mfma_f32_16x16x32_bf16 v[44:47], v[160:163], v[202:205], v[44:47]
	v_mfma_f32_16x16x32_bf16 v[40:43], v[168:171], v[202:205], v[40:43]
	v_mfma_f32_16x16x32_bf16 v[28:31], v[160:163], v[210:213], v[28:31]
	v_mfma_f32_16x16x32_bf16 v[24:27], v[168:171], v[210:213], v[24:27]
	v_mfma_f32_16x16x32_bf16 v[12:15], v[160:163], v[218:221], v[12:15]
	v_mfma_f32_16x16x32_bf16 v[8:11], v[168:171], v[218:221], v[8:11]
	v_mfma_f32_16x16x32_bf16 v[52:55], v[172:175], v[190:193], v[52:55]
	v_mfma_f32_16x16x32_bf16 v[48:51], v[180:183], v[190:193], v[48:51]
	v_mfma_f32_16x16x32_bf16 v[36:39], v[172:175], v[198:201], v[36:39]
	v_mfma_f32_16x16x32_bf16 v[32:35], v[180:183], v[198:201], v[32:35]
	v_mfma_f32_16x16x32_bf16 v[20:23], v[172:175], v[206:209], v[20:23]
	v_mfma_f32_16x16x32_bf16 v[16:19], v[180:183], v[206:209], v[16:19]
	v_mfma_f32_16x16x32_bf16 v[4:7], v[172:175], v[214:217], v[4:7]
	v_mfma_f32_16x16x32_bf16 v[0:3], v[180:183], v[214:217], v[0:3]
	v_mfma_f32_16x16x32_bf16 v[52:55], v[176:179], v[194:197], v[52:55]
	v_mfma_f32_16x16x32_bf16 v[48:51], v[186:189], v[194:197], v[48:51]
	v_mfma_f32_16x16x32_bf16 v[36:39], v[176:179], v[202:205], v[36:39]
	v_mfma_f32_16x16x32_bf16 v[32:35], v[186:189], v[202:205], v[32:35]
	v_mfma_f32_16x16x32_bf16 v[20:23], v[176:179], v[210:213], v[20:23]
	v_mfma_f32_16x16x32_bf16 v[16:19], v[186:189], v[210:213], v[16:19]
	v_mfma_f32_16x16x32_bf16 v[4:7], v[176:179], v[218:221], v[4:7]
	v_mfma_f32_16x16x32_bf16 v[0:3], v[186:189], v[218:221], v[0:3]
	s_barrier
	s_add_i32 s52, 0, 0x18000
	v_add_u32_e32 v148, s52, v151
	s_add_i32 s53, 0, 0x1c000
	ds_read_b128 v[144:147], v148
	ds_read_b128 v[160:163], v148 offset:1024
	ds_read_b128 v[164:167], v148 offset:2048
	ds_read_b128 v[168:171], v148 offset:3072
	v_add_u32_e32 v148, s53, v151
	ds_read_b128 v[172:175], v148
	ds_read_b128 v[176:179], v148 offset:1024
	ds_read_b128 v[180:183], v148 offset:2048
	ds_read_b128 v[186:189], v148 offset:3072
	s_add_u32 s28, s28, 0x40000
	s_addc_u32 s29, s29, 0
	s_mov_b32 m0, s36
	ds_read_b128 v[190:193], v158 offset:32768
	ds_read_b128 v[194:197], v158 offset:33792
	ds_read_b128 v[198:201], v158 offset:34816
	ds_read_b128 v[202:205], v158 offset:35840
	ds_read_b128 v[206:209], v158 offset:36864
	ds_read_b128 v[210:213], v158 offset:37888
	ds_read_b128 v[214:217], v158 offset:38912
	ds_read_b128 v[218:221], v158 offset:39936
	global_load_lds_dwordx4 v134, s[28:29]
	s_mov_b32 m0, s37
	s_nop 0
	global_load_lds_dwordx4 v130, s[28:29]
	s_waitcnt vmcnt(8)
	s_waitcnt lgkmcnt(0)
	s_barrier
	s_waitcnt lgkmcnt(0)
	v_mfma_f32_16x16x32_bf16 v[124:127], v[144:147], v[190:193], v[124:127]
	v_mfma_f32_16x16x32_bf16 v[120:123], v[164:167], v[190:193], v[120:123]
	v_mfma_f32_16x16x32_bf16 v[116:119], v[144:147], v[198:201], v[116:119]
	v_mfma_f32_16x16x32_bf16 v[104:107], v[164:167], v[198:201], v[104:107]
	v_mfma_f32_16x16x32_bf16 v[92:95], v[144:147], v[206:209], v[92:95]
	v_mfma_f32_16x16x32_bf16 v[88:91], v[164:167], v[206:209], v[88:91]
	v_mfma_f32_16x16x32_bf16 v[76:79], v[144:147], v[214:217], v[76:79]
	v_mfma_f32_16x16x32_bf16 v[72:75], v[164:167], v[214:217], v[72:75]
	v_mfma_f32_16x16x32_bf16 v[124:127], v[160:163], v[194:197], v[124:127]
	v_mfma_f32_16x16x32_bf16 v[120:123], v[168:171], v[194:197], v[120:123]
	v_mfma_f32_16x16x32_bf16 v[116:119], v[160:163], v[202:205], v[116:119]
	v_mfma_f32_16x16x32_bf16 v[104:107], v[168:171], v[202:205], v[104:107]
	v_mfma_f32_16x16x32_bf16 v[92:95], v[160:163], v[210:213], v[92:95]
	v_mfma_f32_16x16x32_bf16 v[88:91], v[168:171], v[210:213], v[88:91]
	v_mfma_f32_16x16x32_bf16 v[76:79], v[160:163], v[218:221], v[76:79]
	v_mfma_f32_16x16x32_bf16 v[72:75], v[168:171], v[218:221], v[72:75]
	v_mfma_f32_16x16x32_bf16 v[112:115], v[172:175], v[190:193], v[112:115]
	v_mfma_f32_16x16x32_bf16 v[108:111], v[180:183], v[190:193], v[108:111]
	v_mfma_f32_16x16x32_bf16 v[100:103], v[172:175], v[198:201], v[100:103]
	v_mfma_f32_16x16x32_bf16 v[96:99], v[180:183], v[198:201], v[96:99]
	v_mfma_f32_16x16x32_bf16 v[84:87], v[172:175], v[206:209], v[84:87]
	v_mfma_f32_16x16x32_bf16 v[80:83], v[180:183], v[206:209], v[80:83]
	v_mfma_f32_16x16x32_bf16 v[68:71], v[172:175], v[214:217], v[68:71]
	v_mfma_f32_16x16x32_bf16 v[64:67], v[180:183], v[214:217], v[64:67]
	v_mfma_f32_16x16x32_bf16 v[112:115], v[176:179], v[194:197], v[112:115]
	v_mfma_f32_16x16x32_bf16 v[108:111], v[186:189], v[194:197], v[108:111]
	v_mfma_f32_16x16x32_bf16 v[100:103], v[176:179], v[202:205], v[100:103]
	v_mfma_f32_16x16x32_bf16 v[96:99], v[186:189], v[202:205], v[96:99]
	v_mfma_f32_16x16x32_bf16 v[84:87], v[176:179], v[210:213], v[84:87]
	v_mfma_f32_16x16x32_bf16 v[80:83], v[186:189], v[210:213], v[80:83]
	v_mfma_f32_16x16x32_bf16 v[68:71], v[176:179], v[218:221], v[68:71]
	v_mfma_f32_16x16x32_bf16 v[64:67], v[186:189], v[218:221], v[64:67]
	s_barrier
	s_add_i32 s28, s52, s31
	s_mov_b32 m0, s28
	ds_read_b128 v[190:193], v158 offset:49152
	ds_read_b128 v[194:197], v158 offset:50176
	ds_read_b128 v[198:201], v158 offset:51200
	ds_read_b128 v[202:205], v158 offset:52224
	ds_read_b128 v[206:209], v158 offset:53248
	ds_read_b128 v[210:213], v158 offset:54272
	ds_read_b128 v[214:217], v158 offset:55296
	ds_read_b128 v[218:221], v158 offset:56320
	global_load_lds_dwordx4 v132, s[98:99]
	s_add_i32 m0, s28, 0x2000
	s_add_u32 s26, s26, 0x40080
	s_addc_u32 s27, s27, 0
	s_add_i32 s28, s53, s31
	global_load_lds_dwordx4 v128, s[98:99]
	s_mov_b32 m0, s28
	s_nop 0
	global_load_lds_dwordx4 v132, s[26:27]
	s_add_i32 m0, s28, 0x2000
	s_nop 0
	global_load_lds_dwordx4 v128, s[26:27]
	s_mov_b32 m0, s39
	s_nop 0
	global_load_lds_dwordx4 v134, s[100:101]
	s_mov_b32 m0, s40
	s_nop 0
	global_load_lds_dwordx4 v130, s[100:101]
	s_waitcnt vmcnt(8)
	s_waitcnt lgkmcnt(0)
	s_barrier
	s_waitcnt lgkmcnt(0)
	v_mfma_f32_16x16x32_bf16 v[60:63], v[144:147], v[190:193], v[60:63]
	v_mfma_f32_16x16x32_bf16 v[56:59], v[164:167], v[190:193], v[56:59]
	v_mfma_f32_16x16x32_bf16 v[44:47], v[144:147], v[198:201], v[44:47]
	v_mfma_f32_16x16x32_bf16 v[40:43], v[164:167], v[198:201], v[40:43]
	v_mfma_f32_16x16x32_bf16 v[28:31], v[144:147], v[206:209], v[28:31]
	v_mfma_f32_16x16x32_bf16 v[24:27], v[164:167], v[206:209], v[24:27]
	v_mfma_f32_16x16x32_bf16 v[12:15], v[144:147], v[214:217], v[12:15]
	v_mfma_f32_16x16x32_bf16 v[8:11], v[164:167], v[214:217], v[8:11]
	v_mfma_f32_16x16x32_bf16 v[60:63], v[160:163], v[194:197], v[60:63]
	v_mfma_f32_16x16x32_bf16 v[56:59], v[168:171], v[194:197], v[56:59]
	v_mfma_f32_16x16x32_bf16 v[44:47], v[160:163], v[202:205], v[44:47]
	v_mfma_f32_16x16x32_bf16 v[40:43], v[168:171], v[202:205], v[40:43]
	v_mfma_f32_16x16x32_bf16 v[28:31], v[160:163], v[210:213], v[28:31]
	v_mfma_f32_16x16x32_bf16 v[24:27], v[168:171], v[210:213], v[24:27]
	v_mfma_f32_16x16x32_bf16 v[12:15], v[160:163], v[218:221], v[12:15]
	v_mfma_f32_16x16x32_bf16 v[8:11], v[168:171], v[218:221], v[8:11]
	v_mfma_f32_16x16x32_bf16 v[52:55], v[172:175], v[190:193], v[52:55]
	v_mfma_f32_16x16x32_bf16 v[48:51], v[180:183], v[190:193], v[48:51]
	v_mfma_f32_16x16x32_bf16 v[36:39], v[172:175], v[198:201], v[36:39]
	v_mfma_f32_16x16x32_bf16 v[32:35], v[180:183], v[198:201], v[32:35]
	v_mfma_f32_16x16x32_bf16 v[20:23], v[172:175], v[206:209], v[20:23]
	v_mfma_f32_16x16x32_bf16 v[16:19], v[180:183], v[206:209], v[16:19]
	v_mfma_f32_16x16x32_bf16 v[4:7], v[172:175], v[214:217], v[4:7]
	v_mfma_f32_16x16x32_bf16 v[0:3], v[180:183], v[214:217], v[0:3]
	v_mfma_f32_16x16x32_bf16 v[52:55], v[176:179], v[194:197], v[52:55]
	v_mfma_f32_16x16x32_bf16 v[48:51], v[186:189], v[194:197], v[48:51]
	v_mfma_f32_16x16x32_bf16 v[36:39], v[176:179], v[202:205], v[36:39]
	v_mfma_f32_16x16x32_bf16 v[32:35], v[186:189], v[202:205], v[32:35]
	v_mfma_f32_16x16x32_bf16 v[20:23], v[176:179], v[210:213], v[20:23]
	v_mfma_f32_16x16x32_bf16 v[16:19], v[186:189], v[210:213], v[16:19]
	v_mfma_f32_16x16x32_bf16 v[4:7], v[176:179], v[218:221], v[4:7]
	v_mfma_f32_16x16x32_bf16 v[0:3], v[186:189], v[218:221], v[0:3]
	s_barrier
	s_add_i32 s51, s51, 2
	s_add_u32 s24, s24, 0x100
	s_addc_u32 s25, s25, 0
	s_add_u32 s49, s49, 0x100
	s_addc_u32 s50, s50, 0
	s_cmp_gt_u32 s51, 13
	s_cbranch_scc0 .LBB0_1975
	s_and_b64 vcc, exec, s[12:13]
	s_cbranch_vccz .LBB0_1978
	s_barrier

.LBB0_1982:
	s_cmp_gt_i32 s79, 17
	s_cselect_b64 s[4:5], -1, 0
	s_and_b64 s[0:1], s[0:1], s[4:5]
	s_andn2_b64 vcc, exec, s[0:1]
	s_cbranch_vccnz .LBB0_2036
	s_waitcnt vmcnt(0) lgkmcnt(0)
	s_barrier
	v_readlane_b32 s21, v242, 63
	s_add_u32 s21, s21, 1
	v_readlane_b32 s12, v242, 1
	v_readlane_b32 s13, v242, 2
	s_mov_b64 s[14:15], exec
	s_and_b64 s[12:13], s[14:15], s[12:13]
	s_mov_b64 exec, s[12:13]
	s_cbranch_execz .Lxb_done_14
	v_mov_b32_e32 v0, 0x21020
	ds_read2_b32 v[2:3], v0 offset1:1
	s_lshl_b32 s16, s84, 8
	s_add_u32 s16, s76, s16
	s_addc_u32 s17, s77, 0
	v_mov_b32_e32 v1, 0x1000
	v_mov_b32_e32 v4, 1
	global_atomic_add v5, v1, v4, s[16:17] offset:1024 sc0
	buffer_inv sc1
	s_waitcnt vmcnt(0) lgkmcnt(0)
	v_readfirstlane_b32 s18, v5
	v_readfirstlane_b32 s19, v2
	v_readfirstlane_b32 s20, v3
	v_mov_b32_e32 v1, 0x3000
	s_mul_i32 s22, s19, s21
	s_mul_i32 s23, s20, s21
	s_add_u32 s18, s18, 1
	s_cmp_lg_u32 s18, s22
	s_cbranch_scc1 .Lxb_spin_14
	buffer_wbl2 sc1
	s_waitcnt vmcnt(0)
	global_atomic_add v1, v4, s[76:77] offset:1024

.LBB0_2058:
	ds_read_b128 v[146:149], v155
	ds_read_b128 v[150:153], v155 offset:1024
	ds_read_b128 v[158:161], v155 offset:2048
	ds_read_b128 v[162:165], v155 offset:3072
	ds_read_b128 v[166:169], v156
	ds_read_b128 v[170:173], v156 offset:1024
	ds_read_b128 v[174:177], v156 offset:2048
	ds_read_b128 v[178:181], v156 offset:3072
	s_add_u32 s20, s18, 0xfff50080
	s_addc_u32 s21, s19, -1
	s_cmp_eq_u32 s43, 40
	s_cselect_b32 s23, s5, s21
	s_cselect_b32 s22, s4, s20
	s_cselect_b32 s21, s15, s42
	s_cselect_b32 s20, s14, s17
	s_add_i32 m0, s27, 0xc000
	ds_read_b128 v[182:185], v157
	ds_read_b128 v[186:189], v157 offset:1024
	ds_read_b128 v[190:193], v157 offset:2048
	ds_read_b128 v[194:197], v157 offset:3072
	ds_read_b128 v[198:201], v157 offset:4096
	ds_read_b128 v[202:205], v157 offset:5120
	ds_read_b128 v[206:209], v157 offset:6144
	ds_read_b128 v[210:213], v157 offset:7168
	global_load_lds_dwordx4 v138, s[18:19]
	s_add_i32 m0, s27, 0xe000
	s_nop 0
	global_load_lds_dwordx4 v140, s[18:19]
	s_waitcnt vmcnt(8)
	s_waitcnt lgkmcnt(0)
	s_barrier
	s_waitcnt lgkmcnt(0)
	v_mfma_f32_16x16x32_bf16 v[124:127], v[146:149], v[182:185], v[124:127]
	v_mfma_f32_16x16x32_bf16 v[120:123], v[158:161], v[182:185], v[120:123]
	v_mfma_f32_16x16x32_bf16 v[116:119], v[146:149], v[190:193], v[116:119]
	v_mfma_f32_16x16x32_bf16 v[112:115], v[158:161], v[190:193], v[112:115]
	v_mfma_f32_16x16x32_bf16 v[96:99], v[146:149], v[198:201], v[96:99]
	v_mfma_f32_16x16x32_bf16 v[88:91], v[158:161], v[198:201], v[88:91]
	v_mfma_f32_16x16x32_bf16 v[80:83], v[146:149], v[206:209], v[80:83]
	v_mfma_f32_16x16x32_bf16 v[72:75], v[158:161], v[206:209], v[72:75]
	v_mfma_f32_16x16x32_bf16 v[124:127], v[150:153], v[186:189], v[124:127]
	v_mfma_f32_16x16x32_bf16 v[120:123], v[162:165], v[186:189], v[120:123]
	v_mfma_f32_16x16x32_bf16 v[116:119], v[150:153], v[194:197], v[116:119]
	v_mfma_f32_16x16x32_bf16 v[112:115], v[162:165], v[194:197], v[112:115]
	v_mfma_f32_16x16x32_bf16 v[96:99], v[150:153], v[202:205], v[96:99]
	v_mfma_f32_16x16x32_bf16 v[88:91], v[162:165], v[202:205], v[88:91]
	v_mfma_f32_16x16x32_bf16 v[80:83], v[150:153], v[210:213], v[80:83]
	v_mfma_f32_16x16x32_bf16 v[72:75], v[162:165], v[210:213], v[72:75]
	v_mfma_f32_16x16x32_bf16 v[108:111], v[166:169], v[182:185], v[108:111]
	v_mfma_f32_16x16x32_bf16 v[104:107], v[174:177], v[182:185], v[104:107]
	v_mfma_f32_16x16x32_bf16 v[100:103], v[166:169], v[190:193], v[100:103]
	v_mfma_f32_16x16x32_bf16 v[92:95], v[174:177], v[190:193], v[92:95]
	v_mfma_f32_16x16x32_bf16 v[84:87], v[166:169], v[198:201], v[84:87]
	v_mfma_f32_16x16x32_bf16 v[76:79], v[174:177], v[198:201], v[76:79]
	v_mfma_f32_16x16x32_bf16 v[68:71], v[166:169], v[206:209], v[68:71]
	v_mfma_f32_16x16x32_bf16 v[64:67], v[174:177], v[206:209], v[64:67]
	v_mfma_f32_16x16x32_bf16 v[108:111], v[170:173], v[186:189], v[108:111]
	v_mfma_f32_16x16x32_bf16 v[104:107], v[178:181], v[186:189], v[104:107]
	v_mfma_f32_16x16x32_bf16 v[100:103], v[170:173], v[194:197], v[100:103]
	v_mfma_f32_16x16x32_bf16 v[92:95], v[178:181], v[194:197], v[92:95]
	v_mfma_f32_16x16x32_bf16 v[84:87], v[170:173], v[202:205], v[84:87]
	v_mfma_f32_16x16x32_bf16 v[76:79], v[178:181], v[202:205], v[76:79]
	v_mfma_f32_16x16x32_bf16 v[68:71], v[170:173], v[210:213], v[68:71]
	v_mfma_f32_16x16x32_bf16 v[64:67], v[178:181], v[210:213], v[64:67]
	s_barrier
	s_add_i32 s44, s37, s26
	s_mov_b32 m0, s44
	ds_read_b128 v[182:185], v157 offset:16384
	ds_read_b128 v[186:189], v157 offset:17408
	ds_read_b128 v[190:193], v157 offset:18432
	ds_read_b128 v[194:197], v157 offset:19456
	ds_read_b128 v[198:201], v157 offset:20480
	ds_read_b128 v[202:205], v157 offset:21504
	ds_read_b128 v[206:209], v157 offset:22528
	ds_read_b128 v[210:213], v157 offset:23552
	global_load_lds_dwordx4 v130, s[20:21]
	s_add_i32 m0, s44, 0x2000
	s_add_u32 s44, s20, 0xb0000
	s_addc_u32 s45, s21, 0
	s_add_i32 s46, s38, s26
	global_load_lds_dwordx4 v134, s[20:21]
	s_mov_b32 m0, s46
	global_load_lds_dwordx4 v130, s[44:45]
	s_add_i32 m0, s46, 0x2000
	s_nop 0
	global_load_lds_dwordx4 v134, s[44:45]
	s_mov_b32 m0, s27
	s_nop 0
	global_load_lds_dwordx4 v128, s[22:23]
	s_mov_b32 m0, s28
	s_nop 0
	global_load_lds_dwordx4 v132, s[22:23]
	s_add_u32 s98, s20, s10
	s_addc_u32 s99, s21, s11
	s_add_u32 s100, s22, s10
	s_addc_u32 s101, s23, s11
	s_waitcnt vmcnt(8)
	s_waitcnt lgkmcnt(0)
	s_barrier
	s_waitcnt lgkmcnt(0)
	v_mfma_f32_16x16x32_bf16 v[60:63], v[146:149], v[182:185], v[60:63]
	v_mfma_f32_16x16x32_bf16 v[56:59], v[158:161], v[182:185], v[56:59]
	v_mfma_f32_16x16x32_bf16 v[48:51], v[146:149], v[190:193], v[48:51]
	v_mfma_f32_16x16x32_bf16 v[40:43], v[158:161], v[190:193], v[40:43]
	v_mfma_f32_16x16x32_bf16 v[32:35], v[146:149], v[198:201], v[32:35]
	v_mfma_f32_16x16x32_bf16 v[24:27], v[158:161], v[198:201], v[24:27]
	v_mfma_f32_16x16x32_bf16 v[16:19], v[146:149], v[206:209], v[16:19]
	v_mfma_f32_16x16x32_bf16 v[8:11], v[158:161], v[206:209], v[8:11]
	v_mfma_f32_16x16x32_bf16 v[60:63], v[150:153], v[186:189], v[60:63]
	v_mfma_f32_16x16x32_bf16 v[56:59], v[162:165], v[186:189], v[56:59]
	v_mfma_f32_16x16x32_bf16 v[48:51], v[150:153], v[194:197], v[48:51]
	v_mfma_f32_16x16x32_bf16 v[40:43], v[162:165], v[194:197], v[40:43]
	v_mfma_f32_16x16x32_bf16 v[32:35], v[150:153], v[202:205], v[32:35]
	v_mfma_f32_16x16x32_bf16 v[24:27], v[162:165], v[202:205], v[24:27]
	v_mfma_f32_16x16x32_bf16 v[16:19], v[150:153], v[210:213], v[16:19]
	v_mfma_f32_16x16x32_bf16 v[8:11], v[162:165], v[210:213], v[8:11]
	v_mfma_f32_16x16x32_bf16 v[52:55], v[166:169], v[182:185], v[52:55]
	v_mfma_f32_16x16x32_bf16 v[44:47], v[174:177], v[182:185], v[44:47]
	v_mfma_f32_16x16x32_bf16 v[36:39], v[166:169], v[190:193], v[36:39]
	v_mfma_f32_16x16x32_bf16 v[28:31], v[174:177], v[190:193], v[28:31]
	v_mfma_f32_16x16x32_bf16 v[20:23], v[166:169], v[198:201], v[20:23]
	v_mfma_f32_16x16x32_bf16 v[12:15], v[174:177], v[198:201], v[12:15]
	v_mfma_f32_16x16x32_bf16 v[4:7], v[166:169], v[206:209], v[4:7]
	v_mfma_f32_16x16x32_bf16 v[0:3], v[174:177], v[206:209], v[0:3]
	v_mfma_f32_16x16x32_bf16 v[52:55], v[170:173], v[186:189], v[52:55]
	v_mfma_f32_16x16x32_bf16 v[44:47], v[178:181], v[186:189], v[44:47]
	v_mfma_f32_16x16x32_bf16 v[36:39], v[170:173], v[194:197], v[36:39]
	v_mfma_f32_16x16x32_bf16 v[28:31], v[178:181], v[194:197], v[28:31]
	v_mfma_f32_16x16x32_bf16 v[20:23], v[170:173], v[202:205], v[20:23]
	v_mfma_f32_16x16x32_bf16 v[12:15], v[178:181], v[202:205], v[12:15]
	v_mfma_f32_16x16x32_bf16 v[4:7], v[170:173], v[210:213], v[4:7]
	v_mfma_f32_16x16x32_bf16 v[0:3], v[178:181], v[210:213], v[0:3]
	s_barrier
	s_add_i32 s44, 0, 0x18000
	s_add_i32 s45, 0, 0x1c000
	v_add_u32_e32 v162, s44, v154
	v_add_u32_e32 v178, s45, v154
	ds_read_b128 v[146:149], v162
	ds_read_b128 v[150:153], v162 offset:1024
	ds_read_b128 v[158:161], v162 offset:2048
	ds_read_b128 v[162:165], v162 offset:3072
	ds_read_b128 v[166:169], v178
	ds_read_b128 v[170:173], v178 offset:1024
	ds_read_b128 v[174:177], v178 offset:2048
	ds_read_b128 v[178:181], v178 offset:3072
	s_add_u32 s22, s22, 0xb0000
	s_addc_u32 s23, s23, 0
	s_mov_b32 m0, s29
	ds_read_b128 v[182:185], v157 offset:32768
	ds_read_b128 v[186:189], v157 offset:33792
	ds_read_b128 v[190:193], v157 offset:34816
	ds_read_b128 v[194:197], v157 offset:35840
	ds_read_b128 v[198:201], v157 offset:36864
	ds_read_b128 v[202:205], v157 offset:37888
	ds_read_b128 v[206:209], v157 offset:38912
	ds_read_b128 v[210:213], v157 offset:39936
	global_load_lds_dwordx4 v128, s[22:23]
	s_mov_b32 m0, s30
	s_nop 0
	global_load_lds_dwordx4 v132, s[22:23]
	s_waitcnt vmcnt(8)
	s_waitcnt lgkmcnt(0)
	s_barrier
	s_waitcnt lgkmcnt(0)
	v_mfma_f32_16x16x32_bf16 v[124:127], v[146:149], v[182:185], v[124:127]
	v_mfma_f32_16x16x32_bf16 v[120:123], v[158:161], v[182:185], v[120:123]
	v_mfma_f32_16x16x32_bf16 v[116:119], v[146:149], v[190:193], v[116:119]
	v_mfma_f32_16x16x32_bf16 v[112:115], v[158:161], v[190:193], v[112:115]
	v_mfma_f32_16x16x32_bf16 v[96:99], v[146:149], v[198:201], v[96:99]
	v_mfma_f32_16x16x32_bf16 v[88:91], v[158:161], v[198:201], v[88:91]
	v_mfma_f32_16x16x32_bf16 v[80:83], v[146:149], v[206:209], v[80:83]
	v_mfma_f32_16x16x32_bf16 v[72:75], v[158:161], v[206:209], v[72:75]
	v_mfma_f32_16x16x32_bf16 v[124:127], v[150:153], v[186:189], v[124:127]
	v_mfma_f32_16x16x32_bf16 v[120:123], v[162:165], v[186:189], v[120:123]
	v_mfma_f32_16x16x32_bf16 v[116:119], v[150:153], v[194:197], v[116:119]
	v_mfma_f32_16x16x32_bf16 v[112:115], v[162:165], v[194:197], v[112:115]
	v_mfma_f32_16x16x32_bf16 v[96:99], v[150:153], v[202:205], v[96:99]
	v_mfma_f32_16x16x32_bf16 v[88:91], v[162:165], v[202:205], v[88:91]
	v_mfma_f32_16x16x32_bf16 v[80:83], v[150:153], v[210:213], v[80:83]
	v_mfma_f32_16x16x32_bf16 v[72:75], v[162:165], v[210:213], v[72:75]
	v_mfma_f32_16x16x32_bf16 v[108:111], v[166:169], v[182:185], v[108:111]
	v_mfma_f32_16x16x32_bf16 v[104:107], v[174:177], v[182:185], v[104:107]
	v_mfma_f32_16x16x32_bf16 v[100:103], v[166:169], v[190:193], v[100:103]
	v_mfma_f32_16x16x32_bf16 v[92:95], v[174:177], v[190:193], v[92:95]
	v_mfma_f32_16x16x32_bf16 v[84:87], v[166:169], v[198:201], v[84:87]
	v_mfma_f32_16x16x32_bf16 v[76:79], v[174:177], v[198:201], v[76:79]
	v_mfma_f32_16x16x32_bf16 v[68:71], v[166:169], v[206:209], v[68:71]
	v_mfma_f32_16x16x32_bf16 v[64:67], v[174:177], v[206:209], v[64:67]
	v_mfma_f32_16x16x32_bf16 v[108:111], v[170:173], v[186:189], v[108:111]
	v_mfma_f32_16x16x32_bf16 v[104:107], v[178:181], v[186:189], v[104:107]
	v_mfma_f32_16x16x32_bf16 v[100:103], v[170:173], v[194:197], v[100:103]
	v_mfma_f32_16x16x32_bf16 v[92:95], v[178:181], v[194:197], v[92:95]
	v_mfma_f32_16x16x32_bf16 v[84:87], v[170:173], v[202:205], v[84:87]
	v_mfma_f32_16x16x32_bf16 v[76:79], v[178:181], v[202:205], v[76:79]
	v_mfma_f32_16x16x32_bf16 v[68:71], v[170:173], v[210:213], v[68:71]
	v_mfma_f32_16x16x32_bf16 v[64:67], v[178:181], v[210:213], v[64:67]
	s_barrier
	s_add_i32 s22, s44, s26
	s_mov_b32 m0, s22
	ds_read_b128 v[182:185], v157 offset:49152
	ds_read_b128 v[186:189], v157 offset:50176
	ds_read_b128 v[190:193], v157 offset:51200
	ds_read_b128 v[194:197], v157 offset:52224
	ds_read_b128 v[198:201], v157 offset:53248
	ds_read_b128 v[202:205], v157 offset:54272
	ds_read_b128 v[206:209], v157 offset:55296
	ds_read_b128 v[210:213], v157 offset:56320
	global_load_lds_dwordx4 v130, s[98:99]
	s_add_i32 m0, s22, 0x2000
	s_add_u32 s20, s20, 0xb0080
	s_addc_u32 s21, s21, 0
	s_add_i32 s22, s45, s26
	global_load_lds_dwordx4 v134, s[98:99]
	s_mov_b32 m0, s22
	s_nop 0
	global_load_lds_dwordx4 v130, s[20:21]
	s_add_i32 m0, s22, 0x2000
	s_nop 0
	global_load_lds_dwordx4 v134, s[20:21]
	s_mov_b32 m0, s33
	s_nop 0
	global_load_lds_dwordx4 v128, s[100:101]
	s_mov_b32 m0, s34
	s_nop 0
	global_load_lds_dwordx4 v132, s[100:101]
	s_waitcnt vmcnt(8)
	s_waitcnt lgkmcnt(0)
	s_barrier
	s_waitcnt lgkmcnt(0)
	v_mfma_f32_16x16x32_bf16 v[60:63], v[146:149], v[182:185], v[60:63]
	v_mfma_f32_16x16x32_bf16 v[56:59], v[158:161], v[182:185], v[56:59]
	v_mfma_f32_16x16x32_bf16 v[48:51], v[146:149], v[190:193], v[48:51]
	v_mfma_f32_16x16x32_bf16 v[40:43], v[158:161], v[190:193], v[40:43]
	v_mfma_f32_16x16x32_bf16 v[32:35], v[146:149], v[198:201], v[32:35]
	v_mfma_f32_16x16x32_bf16 v[24:27], v[158:161], v[198:201], v[24:27]
	v_mfma_f32_16x16x32_bf16 v[16:19], v[146:149], v[206:209], v[16:19]
	v_mfma_f32_16x16x32_bf16 v[8:11], v[158:161], v[206:209], v[8:11]
	v_mfma_f32_16x16x32_bf16 v[60:63], v[150:153], v[186:189], v[60:63]
	v_mfma_f32_16x16x32_bf16 v[56:59], v[162:165], v[186:189], v[56:59]
	v_mfma_f32_16x16x32_bf16 v[48:51], v[150:153], v[194:197], v[48:51]
	v_mfma_f32_16x16x32_bf16 v[40:43], v[162:165], v[194:197], v[40:43]
	v_mfma_f32_16x16x32_bf16 v[32:35], v[150:153], v[202:205], v[32:35]
	v_mfma_f32_16x16x32_bf16 v[24:27], v[162:165], v[202:205], v[24:27]
	v_mfma_f32_16x16x32_bf16 v[16:19], v[150:153], v[210:213], v[16:19]
	v_mfma_f32_16x16x32_bf16 v[8:11], v[162:165], v[210:213], v[8:11]
	v_mfma_f32_16x16x32_bf16 v[52:55], v[166:169], v[182:185], v[52:55]
	v_mfma_f32_16x16x32_bf16 v[44:47], v[174:177], v[182:185], v[44:47]
	v_mfma_f32_16x16x32_bf16 v[36:39], v[166:169], v[190:193], v[36:39]
	v_mfma_f32_16x16x32_bf16 v[28:31], v[174:177], v[190:193], v[28:31]
	v_mfma_f32_16x16x32_bf16 v[20:23], v[166:169], v[198:201], v[20:23]
	v_mfma_f32_16x16x32_bf16 v[12:15], v[174:177], v[198:201], v[12:15]
	v_mfma_f32_16x16x32_bf16 v[4:7], v[166:169], v[206:209], v[4:7]
	v_mfma_f32_16x16x32_bf16 v[0:3], v[174:177], v[206:209], v[0:3]
	v_mfma_f32_16x16x32_bf16 v[52:55], v[170:173], v[186:189], v[52:55]
	v_mfma_f32_16x16x32_bf16 v[44:47], v[178:181], v[186:189], v[44:47]
	v_mfma_f32_16x16x32_bf16 v[36:39], v[170:173], v[194:197], v[36:39]
	v_mfma_f32_16x16x32_bf16 v[28:31], v[178:181], v[194:197], v[28:31]
	v_mfma_f32_16x16x32_bf16 v[20:23], v[170:173], v[202:205], v[20:23]
	v_mfma_f32_16x16x32_bf16 v[12:15], v[178:181], v[202:205], v[12:15]
	v_mfma_f32_16x16x32_bf16 v[4:7], v[170:173], v[210:213], v[4:7]
	v_mfma_f32_16x16x32_bf16 v[0:3], v[178:181], v[210:213], v[0:3]
	s_barrier
	s_add_i32 s43, s43, 2
	s_add_u32 s18, s18, 0x100
	s_addc_u32 s19, s19, 0
	s_add_u32 s17, s17, 0x100
	s_addc_u32 s42, s42, 0
	s_cmp_gt_u32 s43, 41
	s_cbranch_scc0 .LBB0_2058
	s_and_b64 vcc, exec, s[12:13]
	s_cbranch_vccz .LBB0_2061
	s_barrier
